# P5 w_in epilogue: 80 arm ends branch straight past the arm-skip cascade (5 taken branches + ~12 SALU per half-row removed from the serialized unit boundary)
# speedup vs baseline: 1.0091x; 1.0063x over previous
.LBB0_1378:
	s_lshl_b32 s41, s4, 8
	s_add_i32 s41, s41, s94
	v_or_b32_e32 v204, s41, v171
	v_or_b32_e32 v214, 16, v204
	v_or_b32_e32 v210, 32, v204
	v_or_b32_e32 v206, 48, v204
	v_add_u32_e32 v198, 0x90, v204
	v_ashrrev_i32_e32 v205, 31, v204
	v_ashrrev_i32_e32 v215, 31, v214
	v_ashrrev_i32_e32 v211, 31, v210
	v_ashrrev_i32_e32 v207, 31, v206
	v_ashrrev_i32_e32 v199, 31, v198
	v_add_u32_e32 v194, 0xa0, v204
	v_add_u32_e32 v188, 0xb0, v204
	v_lshl_add_u64 v[192:193], v[204:205], 2, s[0:1]
	v_lshl_add_u64 v[190:191], v[214:215], 2, s[0:1]
	v_lshl_add_u64 v[196:197], v[210:211], 2, s[0:1]
	v_lshl_add_u64 v[200:201], v[206:207], 2, s[0:1]
	v_lshl_add_u64 v[202:203], v[198:199], 2, s[0:1]
	v_ashrrev_i32_e32 v195, 31, v194
	v_ashrrev_i32_e32 v189, 31, v188
	v_lshl_add_u64 v[220:221], v[194:195], 2, s[0:1]
	v_lshl_add_u64 v[222:223], v[188:189], 2, s[0:1]
	global_load_dword v218, v[192:193], off
	global_load_dword v216, v[190:191], off
	global_load_dword v212, v[196:197], off
	global_load_dword v208, v[200:201], off
	s_nop 0
	global_load_dword v200, v[202:203], off
	global_load_dword v196, v[220:221], off
	global_load_dword v190, v[222:223], off
	s_nop 0
	global_load_dword v202, v[192:193], off offset:512
	s_ashr_i32 s39, s2, 1
	s_cmpk_gt_u32 s3, 0x1ff
	v_add_u32_e32 v176, 0xfffff600, v186
	s_cselect_b64 s[2:3], -1, 0
	s_cmp_gt_i32 s39, 2
	v_ashrrev_i32_e32 v192, 3, v176
	s_cselect_b64 s[34:35], -1, 0
	s_cmp_gt_u32 s39, 7
	v_ashrrev_i32_e32 v193, 31, v192
	s_cselect_b64 s[56:57], -1, 0
	s_cmp_eq_u32 s39, 1
	v_and_b32_e32 v191, 0x178, v186
	s_waitcnt vmcnt(0)
	v_sub_f32_e32 v242, 1.0, v38
	v_sub_f32_e32 v241, 1.0, v39
	v_sub_f32_e32 v240, 1.0, v40
	v_sub_f32_e32 v239, 1.0, v41
	v_sub_f32_e32 v238, 1.0, v34
	v_sub_f32_e32 v234, 1.0, v35
	v_sub_f32_e32 v233, 1.0, v36
	v_sub_f32_e32 v229, 1.0, v37
	s_mov_b64 s[4:5], -1
	v_lshlrev_b64 v[192:193], 15, v[192:193]
	s_cselect_b64 s[54:55], -1, 0
	s_and_b64 vcc, exec, s[2:3]
	v_pk_fma_f32 v[220:221], v[158:159], v[218:219], v[54:55] op_sel_hi:[1,0,1]
	v_pk_fma_f32 v[160:161], v[160:161], v[218:219], v[56:57] op_sel_hi:[1,0,1]
	v_pk_fma_f32 v[154:155], v[154:155], v[218:219], v[50:51] op_sel_hi:[1,0,1]
	v_pk_fma_f32 v[222:223], v[156:157], v[218:219], v[52:53] op_sel_hi:[1,0,1]
	s_cbranch_vccz .LBB0_1396
	s_and_b64 vcc, exec, s[34:35]
	s_cbranch_vccz .LBB0_1393
	s_cmp_lt_i32 s39, 4
	s_cbranch_scc1 .LBB0_1390
	s_cmp_lg_u32 s39, 4
	s_cbranch_scc0 .LBB0_1387
	s_andn2_b64 vcc, exec, s[56:57]
	s_cbranch_vccnz .LBB0_1384
	v_mul_f32_e32 v156, 0xbfb8aa3b, v220
	v_mul_f32_e32 v157, 0xbfb8aa3b, v221
	v_exp_f32_e32 v156, v156
	v_exp_f32_e32 v157, v157
	v_mul_f32_e32 v159, 0xbfb8aa3b, v161
	v_exp_f32_e32 v159, v159
	v_add_f32_e32 v156, 1.0, v156
	v_add_f32_e32 v157, 1.0, v157
	v_rcp_f32_e32 v156, v156
	v_rcp_f32_e32 v157, v157
	v_mul_f32_e32 v158, 0xbfb8aa3b, v160
	v_mul_f32_e32 v203, 0xbfb8aa3b, v223
	v_max_f32_e32 v176, 0x219392ef, v156
	v_max_f32_e32 v197, 0x219392ef, v157
	v_add_f32_e32 v156, 1.0, v159
	v_mul_f32_e32 v157, 0xbfb8aa3b, v154
	v_mul_f32_e32 v159, 0xbfb8aa3b, v155
	v_rcp_f32_e32 v156, v156
	v_exp_f32_e32 v157, v157
	v_exp_f32_e32 v159, v159
	v_exp_f32_e32 v158, v158
	v_max_f32_e32 v201, 0x219392ef, v156
	v_add_f32_e32 v156, 1.0, v157
	v_add_f32_e32 v157, 1.0, v159
	v_mul_f32_e32 v159, 0xbfb8aa3b, v222
	v_exp_f32_e32 v159, v159
	v_exp_f32_e32 v203, v203
	v_rcp_f32_e32 v156, v156
	v_rcp_f32_e32 v157, v157
	v_add_f32_e32 v158, 1.0, v158
	v_add_f32_e32 v159, 1.0, v159
	v_add_f32_e32 v203, 1.0, v203
	v_rcp_f32_e32 v158, v158
	v_rcp_f32_e32 v159, v159
	v_rcp_f32_e32 v203, v203
	v_max_f32_e32 v209, 0x219392ef, v156
	v_max_f32_e32 v213, 0x219392ef, v157
	v_lshlrev_b64 v[156:157], 12, v[204:205]
	v_lshl_add_u64 v[156:157], s[16:17], 0, v[156:157]
	v_lshl_add_u64 v[236:237], v[186:187], 1, v[156:157]
	v_max_f32_e32 v158, 0x219392ef, v158
	v_max_f32_e32 v159, 0x219392ef, v159
	v_max_f32_e32 v203, 0x219392ef, v203
	v_add_co_u32_e32 v236, vcc, 0xffffe000, v236
	v_cvt_pk_bf16_f32 v156, v176, v197
	v_cvt_pk_bf16_f32 v157, v158, v201
	v_cvt_pk_bf16_f32 v158, v209, v213
	v_cvt_pk_bf16_f32 v159, v159, v203
	v_addc_co_u32_e32 v237, vcc, -1, v237, vcc
	s_mov_b64 s[4:5], 0
	global_store_dwordx4 v[236:237], v[156:159], off nt
	s_nop 1
	v_lshlrev_b64 v[158:159], 10, v[204:205]
	v_lshl_add_u64 v[156:157], s[8:9], 0, v[158:159]
	s_branch .LBB0_1398
.LBB0_1384:
	s_andn2_b64 vcc, exec, s[4:5]
	s_cbranch_vccnz .LBB0_1386
	s_ashr_i32 s4, s41, 11
	s_ashr_i32 s5, s4, 31
	s_lshl_b64 s[4:5], s[4:5], 11
	v_lshl_add_u64 v[156:157], s[4:5], 0, v[192:193]
	s_movk_i32 s4, 0x7cf
	v_and_or_b32 v156, v204, s4, v156
	v_lshl_add_u64 v[236:237], v[156:157], 4, s[14:15]
	v_cvt_pk_bf16_f32 v156, v220, v221
	v_cvt_pk_bf16_f32 v157, v160, v161
	v_cvt_pk_bf16_f32 v158, v154, v155
	v_cvt_pk_bf16_f32 v159, v222, v223
	global_store_dwordx4 v[236:237], v[156:159], off nt
	s_nop 1
	v_lshlrev_b64 v[158:159], 10, v[204:205]
	v_lshl_add_u64 v[156:157], s[8:9], 0, v[158:159]
	s_branch .LBB0_1398

.LBB0_1387:
	s_andn2_b64 vcc, exec, s[4:5]
	s_cbranch_vccnz .LBB0_1389
	v_mul_f32_e32 v176, 0xbfb8aa3b, v154
	v_exp_f32_e32 v176, v176
	v_mul_f32_e32 v197, 0xbfb8aa3b, v155
	v_exp_f32_e32 v197, v197
	v_mul_f32_e32 v156, 0xbfb8aa3b, v220
	v_add_f32_e32 v176, 1.0, v176
	v_rcp_f32_e32 v236, v176
	v_add_f32_e32 v176, 1.0, v197
	v_mul_f32_e32 v197, 0xbfb8aa3b, v222
	v_mul_f32_e32 v157, 0xbfb8aa3b, v221
	v_mul_f32_e32 v158, 0xbfb8aa3b, v160
	v_mul_f32_e32 v159, 0xbfb8aa3b, v161
	v_exp_f32_e32 v197, v197
	v_mul_f32_e32 v201, 0xbfb8aa3b, v223
	v_exp_f32_e32 v156, v156
	v_exp_f32_e32 v157, v157
	v_exp_f32_e32 v158, v158
	v_exp_f32_e32 v159, v159
	v_exp_f32_e32 v201, v201
	v_rcp_f32_e32 v237, v176
	v_add_f32_e32 v176, 1.0, v197
	v_add_f32_e32 v156, 1.0, v156
	v_add_f32_e32 v157, 1.0, v157
	v_add_f32_e32 v158, 1.0, v158
	v_add_f32_e32 v159, 1.0, v159
	v_rcp_f32_e32 v244, v176
	v_add_f32_e32 v176, 1.0, v201
	v_rcp_f32_e32 v156, v156
	v_rcp_f32_e32 v157, v157
	v_rcp_f32_e32 v158, v158
	v_rcp_f32_e32 v159, v159
	v_rcp_f32_e32 v245, v176
	v_lshlrev_b64 v[246:247], 10, v[204:205]
	v_pk_mul_f32 v[156:157], v[220:221], v[156:157]
	v_pk_mul_f32 v[158:159], v[160:161], v[158:159]
	v_pk_mul_f32 v[236:237], v[154:155], v[236:237]
	v_pk_mul_f32 v[244:245], v[222:223], v[244:245]
	v_lshl_add_u64 v[246:247], s[12:13], 0, v[246:247]
	v_lshl_add_u64 v[246:247], v[186:187], 1, v[246:247]
	v_cvt_pk_bf16_f32 v156, v156, v157
	v_cvt_pk_bf16_f32 v157, v158, v159
	v_cvt_pk_bf16_f32 v158, v236, v237
	v_cvt_pk_bf16_f32 v159, v244, v245
	global_store_dwordx4 v[246:247], v[156:159], off offset:-4096 nt
	s_nop 1
	v_lshlrev_b64 v[158:159], 10, v[204:205]
	v_lshl_add_u64 v[156:157], s[8:9], 0, v[158:159]
	s_branch .LBB0_1398

.LBB0_1390:
	s_andn2_b64 vcc, exec, s[4:5]
	s_cbranch_vccnz .LBB0_1392
	v_mul_f32_e32 v176, 0xbfb8aa3b, v154
	v_exp_f32_e32 v176, v176
	v_mul_f32_e32 v197, 0xbfb8aa3b, v155
	v_exp_f32_e32 v197, v197
	v_mul_f32_e32 v156, 0xbfb8aa3b, v220
	v_add_f32_e32 v176, 1.0, v176
	v_rcp_f32_e32 v236, v176
	v_add_f32_e32 v176, 1.0, v197
	v_mul_f32_e32 v197, 0xbfb8aa3b, v222
	v_mul_f32_e32 v157, 0xbfb8aa3b, v221
	v_mul_f32_e32 v158, 0xbfb8aa3b, v160
	v_mul_f32_e32 v159, 0xbfb8aa3b, v161
	v_exp_f32_e32 v197, v197
	v_mul_f32_e32 v201, 0xbfb8aa3b, v223
	v_exp_f32_e32 v156, v156
	v_exp_f32_e32 v157, v157
	v_exp_f32_e32 v158, v158
	v_exp_f32_e32 v159, v159
	v_exp_f32_e32 v201, v201
	v_rcp_f32_e32 v237, v176
	v_add_f32_e32 v176, 1.0, v197
	v_add_f32_e32 v156, 1.0, v156
	v_add_f32_e32 v157, 1.0, v157
	v_add_f32_e32 v158, 1.0, v158
	v_add_f32_e32 v159, 1.0, v159
	v_rcp_f32_e32 v244, v176
	v_add_f32_e32 v176, 1.0, v201
	v_rcp_f32_e32 v156, v156
	v_rcp_f32_e32 v157, v157
	v_rcp_f32_e32 v158, v158
	v_rcp_f32_e32 v159, v159
	v_rcp_f32_e32 v245, v176
	v_lshlrev_b64 v[246:247], 10, v[204:205]
	v_pk_mul_f32 v[156:157], v[220:221], v[156:157]
	v_pk_mul_f32 v[158:159], v[160:161], v[158:159]
	v_pk_mul_f32 v[236:237], v[154:155], v[236:237]
	v_pk_mul_f32 v[244:245], v[222:223], v[244:245]
	v_lshl_add_u64 v[246:247], s[10:11], 0, v[246:247]
	v_lshl_add_u64 v[246:247], v[186:187], 1, v[246:247]
	v_cvt_pk_bf16_f32 v156, v156, v157
	v_cvt_pk_bf16_f32 v157, v158, v159
	v_cvt_pk_bf16_f32 v158, v236, v237
	v_cvt_pk_bf16_f32 v159, v244, v245
	global_store_dwordx4 v[246:247], v[156:159], off offset:-3072 nt
	s_nop 1
	v_lshlrev_b64 v[158:159], 10, v[204:205]
	v_lshl_add_u64 v[156:157], s[8:9], 0, v[158:159]
	s_branch .LBB0_1398

.LBB0_1393:
	s_and_b64 vcc, exec, s[4:5]
	s_cbranch_vccz .LBB0_1395
	v_mul_f32_e32 v158, 0xbfb8aa3b, v160
	v_exp_f32_e32 v158, v158
	v_mul_f32_e32 v159, 0xbfb8aa3b, v161
	v_mul_f32_e32 v176, 0xbfb8aa3b, v154
	v_exp_f32_e32 v159, v159
	v_add_f32_e32 v158, 1.0, v158
	v_rcp_f32_e32 v158, v158
	v_exp_f32_e32 v176, v176
	v_mul_f32_e32 v203, 0xbfb8aa3b, v223
	v_mul_f32_e32 v156, 0xbfb8aa3b, v220
	v_fma_f32 v158, v240, v158, v40
	v_log_f32_e32 v197, v158
	v_add_f32_e32 v158, 1.0, v159
	v_add_f32_e32 v159, 1.0, v176
	v_rcp_f32_e32 v159, v159
	v_mul_f32_e32 v176, 0xbfb8aa3b, v155
	v_exp_f32_e32 v176, v176
	v_mul_f32_e32 v157, 0xbfb8aa3b, v221
	v_fma_f32 v159, v238, v159, v34
	v_log_f32_e32 v201, v159
	v_add_f32_e32 v159, 1.0, v176
	v_mul_f32_e32 v176, 0xbfb8aa3b, v222
	v_exp_f32_e32 v176, v176
	v_exp_f32_e32 v203, v203
	v_exp_f32_e32 v156, v156
	v_exp_f32_e32 v157, v157
	v_add_f32_e32 v176, 1.0, v176
	v_add_f32_e32 v203, 1.0, v203
	v_add_f32_e32 v156, 1.0, v156
	v_add_f32_e32 v157, 1.0, v157
	v_rcp_f32_e32 v176, v176
	v_rcp_f32_e32 v203, v203
	v_rcp_f32_e32 v156, v156
	v_rcp_f32_e32 v157, v157
	v_rcp_f32_e32 v158, v158
	v_rcp_f32_e32 v159, v159
	v_fma_f32 v176, v233, v176, v36
	v_fma_f32 v203, v229, v203, v37
	v_fma_f32 v156, v242, v156, v38
	v_fma_f32 v157, v241, v157, v39
	v_fma_f32 v158, v239, v158, v41
	v_fma_f32 v159, v234, v159, v35
	v_log_f32_e32 v176, v176
	v_log_f32_e32 v203, v203
	v_log_f32_e32 v156, v156
	v_log_f32_e32 v209, v159
	v_log_f32_e32 v213, v158
	v_log_f32_e32 v217, v157
	s_and_b64 s[4:5], s[54:55], exec
	s_cselect_b32 s5, s87, s92
	s_cselect_b32 s4, s79, s89
	v_lshlrev_b64 v[236:237], 10, v[204:205]
	v_cvt_pk_f16_f32 v159, v176, v203
	v_lshl_add_u64 v[236:237], s[4:5], 0, v[236:237]
	v_lshlrev_b32_e32 v176, 1, v191
	v_cvt_pk_f16_f32 v158, v201, v209
	v_cvt_pk_f16_f32 v157, v197, v213
	v_cvt_pk_f16_f32 v156, v156, v217
	v_lshl_add_u64 v[236:237], v[236:237], 0, v[176:177]
	global_store_dwordx4 v[236:237], v[156:159], off
	s_nop 1
	v_lshlrev_b64 v[158:159], 10, v[204:205]
	v_lshl_add_u64 v[156:157], s[8:9], 0, v[158:159]
	s_branch .LBB0_1398

.LBB0_1398:
	v_add_u32_e32 v154, 0xfffff680, v186
	v_ashrrev_i32_e32 v154, 3, v154
	v_mov_b32_e32 v219, v218
	v_ashrrev_i32_e32 v155, 31, v154
	s_movk_i32 s4, 0x1f8
	v_lshlrev_b64 v[154:155], 15, v[154:155]
	v_bitop3_b32 v160, v186, s4, v228 bitop3:0xc8
	v_sub_f32_e32 v237, 1.0, v10
	v_sub_f32_e32 v236, 1.0, v11
	v_sub_f32_e32 v235, 1.0, v12
	v_sub_f32_e32 v222, 1.0, v13
	v_sub_f32_e32 v223, 1.0, v14
	v_sub_f32_e32 v220, 1.0, v15
	v_sub_f32_e32 v221, 1.0, v16
	v_sub_f32_e32 v161, 1.0, v17
	v_pk_fma_f32 v[150:151], v[150:151], v[218:219], v[30:31]
	v_pk_fma_f32 v[152:153], v[152:153], v[218:219], v[32:33]
	v_pk_fma_f32 v[146:147], v[146:147], v[218:219], v[26:27]
	v_pk_fma_f32 v[148:149], v[148:149], v[218:219], v[28:29]
	s_mov_b64 s[4:5], -1
	s_and_b64 vcc, exec, s[2:3]
	s_cbranch_vccz .LBB0_1416
	s_and_b64 vcc, exec, s[34:35]
	s_cbranch_vccz .LBB0_1413
	s_cmp_lt_i32 s39, 4
	s_cbranch_scc1 .LBB0_1410
	s_cmp_lg_u32 s39, 4
	s_cbranch_scc0 .LBB0_1407
	s_andn2_b64 vcc, exec, s[56:57]
	s_cbranch_vccnz .LBB0_1404
	v_mul_f32_e32 v218, 0xbfb8aa3b, v149
	v_exp_f32_e32 v218, v218
	v_mul_f32_e32 v176, 0xbfb8aa3b, v150
	v_mul_f32_e32 v197, 0xbfb8aa3b, v151
	v_mul_f32_e32 v201, 0xbfb8aa3b, v152
	v_mul_f32_e32 v203, 0xbfb8aa3b, v153
	v_mul_f32_e32 v209, 0xbfb8aa3b, v146
	v_mul_f32_e32 v213, 0xbfb8aa3b, v147
	v_mul_f32_e32 v217, 0xbfb8aa3b, v148
	v_exp_f32_e32 v176, v176
	v_exp_f32_e32 v197, v197
	v_exp_f32_e32 v201, v201
	v_exp_f32_e32 v203, v203
	v_exp_f32_e32 v209, v209
	v_exp_f32_e32 v213, v213
	v_exp_f32_e32 v217, v217
	v_add_f32_e32 v218, 1.0, v218
	v_rcp_f32_e32 v218, v218
	v_add_f32_e32 v176, 1.0, v176
	v_add_f32_e32 v197, 1.0, v197
	v_add_f32_e32 v201, 1.0, v201
	v_add_f32_e32 v203, 1.0, v203
	v_add_f32_e32 v209, 1.0, v209
	v_add_f32_e32 v213, 1.0, v213
	v_add_f32_e32 v217, 1.0, v217
	v_rcp_f32_e32 v176, v176
	v_rcp_f32_e32 v197, v197
	v_rcp_f32_e32 v201, v201
	v_rcp_f32_e32 v203, v203
	v_rcp_f32_e32 v209, v209
	v_rcp_f32_e32 v213, v213
	v_rcp_f32_e32 v217, v217
	v_max_f32_e32 v243, 0x219392ef, v218
	v_lshlrev_b64 v[218:219], 12, v[204:205]
	v_lshl_add_u64 v[218:219], s[16:17], 0, v[218:219]
	v_lshl_add_u64 v[218:219], v[186:187], 1, v[218:219]
	v_max_f32_e32 v176, 0x219392ef, v176
	v_max_f32_e32 v197, 0x219392ef, v197
	v_max_f32_e32 v201, 0x219392ef, v201
	v_max_f32_e32 v203, 0x219392ef, v203
	v_max_f32_e32 v209, 0x219392ef, v209
	v_max_f32_e32 v213, 0x219392ef, v213
	v_max_f32_e32 v217, 0x219392ef, v217
	v_add_co_u32_e32 v218, vcc, 0xfffff000, v218
	v_cvt_pk_bf16_f32 v244, v176, v197
	v_cvt_pk_bf16_f32 v245, v201, v203
	v_cvt_pk_bf16_f32 v246, v209, v213
	v_cvt_pk_bf16_f32 v247, v217, v243
	v_addc_co_u32_e32 v219, vcc, -1, v219, vcc
	s_mov_b64 s[4:5], 0
	global_store_dwordx4 v[218:219], v[244:247], off offset:-3840 nt
	s_nop 1
	s_branch .LBB0_1418
.LBB0_1404:
	s_andn2_b64 vcc, exec, s[4:5]
	s_cbranch_vccnz .LBB0_1406
	s_ashr_i32 s4, s41, 11
	s_ashr_i32 s5, s4, 31
	s_lshl_b64 s[4:5], s[4:5], 11
	v_lshl_add_u64 v[218:219], s[4:5], 0, v[154:155]
	s_movk_i32 s4, 0x7cf
	v_and_or_b32 v218, v204, s4, v218
	v_lshl_add_u64 v[218:219], v[218:219], 4, s[14:15]
	v_cvt_pk_bf16_f32 v244, v150, v151
	v_cvt_pk_bf16_f32 v245, v152, v153
	v_cvt_pk_bf16_f32 v246, v146, v147
	v_cvt_pk_bf16_f32 v247, v148, v149
	global_store_dwordx4 v[218:219], v[244:247], off nt
	s_nop 1
	s_branch .LBB0_1418

.LBB0_1407:
	s_andn2_b64 vcc, exec, s[4:5]
	s_cbranch_vccnz .LBB0_1409
	v_mul_f32_e32 v176, 0xbfb8aa3b, v150
	v_exp_f32_e32 v176, v176
	v_mul_f32_e32 v197, 0xbfb8aa3b, v151
	v_exp_f32_e32 v197, v197
	v_mul_f32_e32 v201, 0xbfb8aa3b, v153
	v_add_f32_e32 v176, 1.0, v176
	v_rcp_f32_e32 v218, v176
	v_mul_f32_e32 v176, 0xbfb8aa3b, v152
	v_exp_f32_e32 v176, v176
	v_exp_f32_e32 v201, v201
	v_add_f32_e32 v197, 1.0, v197
	v_rcp_f32_e32 v219, v197
	v_add_f32_e32 v176, 1.0, v176
	v_mul_f32_e32 v197, 0xbfb8aa3b, v146
	v_rcp_f32_e32 v244, v176
	v_add_f32_e32 v176, 1.0, v201
	v_exp_f32_e32 v197, v197
	v_mul_f32_e32 v201, 0xbfb8aa3b, v147
	v_exp_f32_e32 v201, v201
	v_rcp_f32_e32 v245, v176
	v_add_f32_e32 v176, 1.0, v197
	v_mul_f32_e32 v197, 0xbfb8aa3b, v148
	v_rcp_f32_e32 v246, v176
	v_add_f32_e32 v176, 1.0, v201
	v_exp_f32_e32 v197, v197
	v_mul_f32_e32 v201, 0xbfb8aa3b, v149
	v_exp_f32_e32 v201, v201
	v_rcp_f32_e32 v247, v176
	v_add_f32_e32 v176, 1.0, v197
	v_rcp_f32_e32 v248, v176
	v_add_f32_e32 v176, 1.0, v201
	v_rcp_f32_e32 v249, v176
	v_pk_mul_f32 v[218:219], v[150:151], v[218:219]
	v_pk_mul_f32 v[250:251], v[152:153], v[244:245]
	v_pk_mul_f32 v[246:247], v[146:147], v[246:247]
	v_pk_mul_f32 v[248:249], v[148:149], v[248:249]
	v_lshl_add_u64 v[244:245], s[12:13], 0, v[158:159]
	v_lshl_add_u64 v[252:253], v[186:187], 1, v[244:245]
	v_cvt_pk_bf16_f32 v244, v218, v219
	v_cvt_pk_bf16_f32 v245, v250, v251
	v_cvt_pk_bf16_f32 v246, v246, v247
	v_cvt_pk_bf16_f32 v247, v248, v249
	global_store_dwordx4 v[252:253], v[244:247], off offset:-3840 nt
	s_nop 1
	s_branch .LBB0_1418

.LBB0_1410:
	s_andn2_b64 vcc, exec, s[4:5]
	s_cbranch_vccnz .LBB0_1412
	v_mul_f32_e32 v176, 0xbfb8aa3b, v150
	v_exp_f32_e32 v176, v176
	v_mul_f32_e32 v197, 0xbfb8aa3b, v151
	v_exp_f32_e32 v197, v197
	v_mul_f32_e32 v201, 0xbfb8aa3b, v153
	v_add_f32_e32 v176, 1.0, v176
	v_rcp_f32_e32 v218, v176
	v_mul_f32_e32 v176, 0xbfb8aa3b, v152
	v_exp_f32_e32 v176, v176
	v_exp_f32_e32 v201, v201
	v_add_f32_e32 v197, 1.0, v197
	v_rcp_f32_e32 v219, v197
	v_add_f32_e32 v176, 1.0, v176
	v_mul_f32_e32 v197, 0xbfb8aa3b, v146
	v_rcp_f32_e32 v244, v176
	v_add_f32_e32 v176, 1.0, v201
	v_exp_f32_e32 v197, v197
	v_mul_f32_e32 v201, 0xbfb8aa3b, v147
	v_exp_f32_e32 v201, v201
	v_rcp_f32_e32 v245, v176
	v_add_f32_e32 v176, 1.0, v197
	v_mul_f32_e32 v197, 0xbfb8aa3b, v148
	v_rcp_f32_e32 v246, v176
	v_add_f32_e32 v176, 1.0, v201
	v_exp_f32_e32 v197, v197
	v_mul_f32_e32 v201, 0xbfb8aa3b, v149
	v_exp_f32_e32 v201, v201
	v_rcp_f32_e32 v247, v176
	v_add_f32_e32 v176, 1.0, v197
	v_rcp_f32_e32 v248, v176
	v_add_f32_e32 v176, 1.0, v201
	v_rcp_f32_e32 v249, v176
	v_pk_mul_f32 v[218:219], v[150:151], v[218:219]
	v_pk_mul_f32 v[250:251], v[152:153], v[244:245]
	v_pk_mul_f32 v[246:247], v[146:147], v[246:247]
	v_pk_mul_f32 v[248:249], v[148:149], v[248:249]
	v_lshl_add_u64 v[244:245], s[10:11], 0, v[158:159]
	v_lshl_add_u64 v[252:253], v[186:187], 1, v[244:245]
	v_cvt_pk_bf16_f32 v244, v218, v219
	v_cvt_pk_bf16_f32 v245, v250, v251
	v_cvt_pk_bf16_f32 v246, v246, v247
	v_cvt_pk_bf16_f32 v247, v248, v249
	global_store_dwordx4 v[252:253], v[244:247], off offset:-2816 nt
	s_nop 1
	s_branch .LBB0_1418

.LBB0_1413:
	s_and_b64 vcc, exec, s[4:5]
	s_cbranch_vccz .LBB0_1415
	v_mul_f32_e32 v176, 0xbfb8aa3b, v150
	v_mul_f32_e32 v197, 0xbfb8aa3b, v151
	v_exp_f32_e32 v176, v176
	v_exp_f32_e32 v197, v197
	v_mul_f32_e32 v201, 0xbfb8aa3b, v152
	v_mul_f32_e32 v203, 0xbfb8aa3b, v153
	v_mul_f32_e32 v205, 0xbfb8aa3b, v146
	v_mul_f32_e32 v209, 0xbfb8aa3b, v147
	v_mul_f32_e32 v213, 0xbfb8aa3b, v148
	v_mul_f32_e32 v217, 0xbfb8aa3b, v149
	v_exp_f32_e32 v201, v201
	v_exp_f32_e32 v203, v203
	v_exp_f32_e32 v205, v205
	v_exp_f32_e32 v209, v209
	v_exp_f32_e32 v213, v213
	v_exp_f32_e32 v217, v217
	v_add_f32_e32 v176, 1.0, v176
	v_add_f32_e32 v197, 1.0, v197
	v_rcp_f32_e32 v176, v176
	v_rcp_f32_e32 v197, v197
	v_add_f32_e32 v201, 1.0, v201
	v_add_f32_e32 v203, 1.0, v203
	v_add_f32_e32 v205, 1.0, v205
	v_add_f32_e32 v209, 1.0, v209
	v_add_f32_e32 v213, 1.0, v213
	v_add_f32_e32 v217, 1.0, v217
	v_rcp_f32_e32 v201, v201
	v_rcp_f32_e32 v203, v203
	v_rcp_f32_e32 v205, v205
	v_rcp_f32_e32 v209, v209
	v_rcp_f32_e32 v213, v213
	v_rcp_f32_e32 v217, v217
	v_fma_f32 v176, v237, v176, v10
	v_fma_f32 v197, v236, v197, v11
	v_log_f32_e32 v176, v176
	v_fma_f32 v201, v235, v201, v12
	v_fma_f32 v203, v222, v203, v13
	v_fma_f32 v205, v223, v205, v14
	v_fma_f32 v209, v220, v209, v15
	v_fma_f32 v213, v221, v213, v16
	v_fma_f32 v217, v161, v217, v17
	v_log_f32_e32 v197, v197
	v_log_f32_e32 v201, v201
	v_log_f32_e32 v205, v205
	v_log_f32_e32 v213, v213
	v_log_f32_e32 v217, v217
	v_log_f32_e32 v209, v209
	v_log_f32_e32 v203, v203
	s_and_b64 s[4:5], s[54:55], exec
	s_cselect_b32 s5, s87, s92
	s_cselect_b32 s4, s79, s89
	v_cvt_pk_f16_f32 v244, v176, v197
	v_lshl_add_u64 v[158:159], s[4:5], 0, v[158:159]
	v_lshlrev_b32_e32 v176, 1, v160
	v_cvt_pk_f16_f32 v247, v213, v217
	v_cvt_pk_f16_f32 v246, v205, v209
	v_cvt_pk_f16_f32 v245, v201, v203
	v_lshl_add_u64 v[158:159], v[158:159], 0, v[176:177]
	global_store_dwordx4 v[158:159], v[244:247], off
	s_nop 1
	s_branch .LBB0_1418

.LBB0_1418:
	v_pk_fma_f32 v[146:147], v[138:139], v[216:217], v[50:51] op_sel_hi:[1,0,1]
	v_cndmask_b32_e64 v138, 0, 1, s[2:3]
	v_cmp_ne_u32_e64 s[4:5], 1, v138
	v_cndmask_b32_e64 v138, 0, 1, s[34:35]
	v_pk_fma_f32 v[142:143], v[142:143], v[216:217], v[54:55] op_sel_hi:[1,0,1]
	v_pk_fma_f32 v[144:145], v[144:145], v[216:217], v[56:57] op_sel_hi:[1,0,1]
	v_pk_fma_f32 v[140:141], v[140:141], v[216:217], v[52:53] op_sel_hi:[1,0,1]
	s_mov_b64 s[18:19], -1
	s_andn2_b64 vcc, exec, s[2:3]
	v_cmp_ne_u32_e64 s[2:3], 1, v138
	s_cbranch_vccnz .LBB0_1436
	s_and_b64 vcc, exec, s[2:3]
	s_cbranch_vccnz .LBB0_1433
	s_cmp_lt_i32 s39, 4
	s_cbranch_scc1 .LBB0_1430
	s_cmp_lg_u32 s39, 4
	s_cbranch_scc0 .LBB0_1427
	s_andn2_b64 vcc, exec, s[56:57]
	s_cbranch_vccnz .LBB0_1424
	v_mul_f32_e32 v138, 0xbfb8aa3b, v142
	v_mul_f32_e32 v139, 0xbfb8aa3b, v143
	v_mul_f32_e32 v148, 0xbfb8aa3b, v144
	v_exp_f32_e32 v138, v138
	v_exp_f32_e32 v139, v139
	v_exp_f32_e32 v148, v148
	v_mul_f32_e32 v149, 0xbfb8aa3b, v145
	v_add_f32_e32 v138, 1.0, v138
	v_add_f32_e32 v139, 1.0, v139
	v_add_f32_e32 v148, 1.0, v148
	v_rcp_f32_e32 v138, v138
	v_rcp_f32_e32 v139, v139
	v_rcp_f32_e32 v148, v148
	v_exp_f32_e32 v149, v149
	v_max_f32_e32 v150, 0x219392ef, v138
	v_max_f32_e32 v151, 0x219392ef, v139
	v_max_f32_e32 v152, 0x219392ef, v148
	v_add_f32_e32 v138, 1.0, v149
	v_mul_f32_e32 v139, 0xbfb8aa3b, v146
	v_mul_f32_e32 v148, 0xbfb8aa3b, v147
	v_rcp_f32_e32 v138, v138
	v_exp_f32_e32 v139, v139
	v_exp_f32_e32 v148, v148
	v_mul_f32_e32 v153, 0xbfb8aa3b, v141
	v_max_f32_e32 v149, 0x219392ef, v138
	v_add_f32_e32 v138, 1.0, v139
	v_add_f32_e32 v139, 1.0, v148
	v_mul_f32_e32 v148, 0xbfb8aa3b, v140
	v_exp_f32_e32 v148, v148
	v_exp_f32_e32 v153, v153
	v_rcp_f32_e32 v138, v138
	v_rcp_f32_e32 v139, v139
	v_add_f32_e32 v148, 1.0, v148
	v_add_f32_e32 v153, 1.0, v153
	v_rcp_f32_e32 v148, v148
	v_rcp_f32_e32 v153, v153
	v_max_f32_e32 v156, 0x219392ef, v138
	v_max_f32_e32 v157, 0x219392ef, v139
	v_lshlrev_b64 v[138:139], 12, v[214:215]
	v_lshl_add_u64 v[138:139], s[16:17], 0, v[138:139]
	v_lshl_add_u64 v[138:139], v[186:187], 1, v[138:139]
	v_max_f32_e32 v158, 0x219392ef, v148
	v_max_f32_e32 v153, 0x219392ef, v153
	v_add_co_u32_e32 v138, vcc, 0xffffe000, v138
	v_cvt_pk_bf16_f32 v148, v150, v151
	v_cvt_pk_bf16_f32 v149, v152, v149
	v_cvt_pk_bf16_f32 v150, v156, v157
	v_cvt_pk_bf16_f32 v151, v158, v153
	v_addc_co_u32_e32 v139, vcc, -1, v139, vcc
	s_mov_b64 s[18:19], 0
	global_store_dwordx4 v[138:139], v[148:151], off nt
	s_nop 1
	v_lshlrev_b64 v[148:149], 10, v[214:215]
	v_lshl_add_u64 v[138:139], s[8:9], 0, v[148:149]
	s_branch .LBB0_1438
.LBB0_1424:
	s_andn2_b64 vcc, exec, s[18:19]
	s_cbranch_vccnz .LBB0_1426
	s_ashr_i32 s18, s41, 11
	s_ashr_i32 s19, s18, 31
	s_lshl_b64 s[18:19], s[18:19], 11
	v_lshl_add_u64 v[138:139], s[18:19], 0, v[192:193]
	s_movk_i32 s18, 0x7df
	v_and_or_b32 v138, v214, s18, v138
	v_lshl_add_u64 v[138:139], v[138:139], 4, s[14:15]
	v_cvt_pk_bf16_f32 v148, v142, v143
	v_cvt_pk_bf16_f32 v149, v144, v145
	v_cvt_pk_bf16_f32 v150, v146, v147
	v_cvt_pk_bf16_f32 v151, v140, v141
	global_store_dwordx4 v[138:139], v[148:151], off nt
	s_nop 1
	v_lshlrev_b64 v[148:149], 10, v[214:215]
	v_lshl_add_u64 v[138:139], s[8:9], 0, v[148:149]
	s_branch .LBB0_1438

.LBB0_1427:
	s_andn2_b64 vcc, exec, s[18:19]
	s_cbranch_vccnz .LBB0_1429
	v_mul_f32_e32 v148, 0xbfb8aa3b, v144
	v_mul_f32_e32 v149, 0xbfb8aa3b, v145
	v_mul_f32_e32 v138, 0xbfb8aa3b, v142
	v_mul_f32_e32 v139, 0xbfb8aa3b, v143
	v_exp_f32_e32 v148, v148
	v_exp_f32_e32 v149, v149
	v_mul_f32_e32 v150, 0xbfb8aa3b, v146
	v_mul_f32_e32 v151, 0xbfb8aa3b, v147
	v_mul_f32_e32 v152, 0xbfb8aa3b, v140
	v_mul_f32_e32 v153, 0xbfb8aa3b, v141
	v_exp_f32_e32 v138, v138
	v_exp_f32_e32 v139, v139
	v_exp_f32_e32 v150, v150
	v_exp_f32_e32 v151, v151
	v_exp_f32_e32 v152, v152
	v_exp_f32_e32 v153, v153
	v_add_f32_e32 v148, 1.0, v148
	v_add_f32_e32 v149, 1.0, v149
	v_add_f32_e32 v138, 1.0, v138
	v_add_f32_e32 v139, 1.0, v139
	v_rcp_f32_e32 v148, v148
	v_rcp_f32_e32 v149, v149
	v_add_f32_e32 v150, 1.0, v150
	v_add_f32_e32 v151, 1.0, v151
	v_add_f32_e32 v152, 1.0, v152
	v_add_f32_e32 v153, 1.0, v153
	v_rcp_f32_e32 v138, v138
	v_rcp_f32_e32 v139, v139
	v_rcp_f32_e32 v150, v150
	v_rcp_f32_e32 v151, v151
	v_rcp_f32_e32 v152, v152
	v_rcp_f32_e32 v153, v153
	v_pk_mul_f32 v[156:157], v[144:145], v[148:149]
	v_lshlrev_b64 v[148:149], 10, v[214:215]
	v_pk_mul_f32 v[138:139], v[142:143], v[138:139]
	v_pk_mul_f32 v[150:151], v[146:147], v[150:151]
	v_pk_mul_f32 v[152:153], v[140:141], v[152:153]
	v_lshl_add_u64 v[148:149], s[12:13], 0, v[148:149]
	v_lshl_add_u64 v[158:159], v[186:187], 1, v[148:149]
	v_cvt_pk_bf16_f32 v148, v138, v139
	v_cvt_pk_bf16_f32 v149, v156, v157
	v_cvt_pk_bf16_f32 v150, v150, v151
	v_cvt_pk_bf16_f32 v151, v152, v153
	global_store_dwordx4 v[158:159], v[148:151], off offset:-4096 nt
	s_nop 1
	v_lshlrev_b64 v[148:149], 10, v[214:215]
	v_lshl_add_u64 v[138:139], s[8:9], 0, v[148:149]
	s_branch .LBB0_1438

.LBB0_1430:
	s_andn2_b64 vcc, exec, s[18:19]
	s_cbranch_vccnz .LBB0_1432
	v_mul_f32_e32 v148, 0xbfb8aa3b, v144
	v_mul_f32_e32 v149, 0xbfb8aa3b, v145
	v_mul_f32_e32 v138, 0xbfb8aa3b, v142
	v_mul_f32_e32 v139, 0xbfb8aa3b, v143
	v_exp_f32_e32 v148, v148
	v_exp_f32_e32 v149, v149
	v_mul_f32_e32 v150, 0xbfb8aa3b, v146
	v_mul_f32_e32 v151, 0xbfb8aa3b, v147
	v_mul_f32_e32 v152, 0xbfb8aa3b, v140
	v_mul_f32_e32 v153, 0xbfb8aa3b, v141
	v_exp_f32_e32 v138, v138
	v_exp_f32_e32 v139, v139
	v_exp_f32_e32 v150, v150
	v_exp_f32_e32 v151, v151
	v_exp_f32_e32 v152, v152
	v_exp_f32_e32 v153, v153
	v_add_f32_e32 v148, 1.0, v148
	v_add_f32_e32 v149, 1.0, v149
	v_add_f32_e32 v138, 1.0, v138
	v_add_f32_e32 v139, 1.0, v139
	v_rcp_f32_e32 v148, v148
	v_rcp_f32_e32 v149, v149
	v_add_f32_e32 v150, 1.0, v150
	v_add_f32_e32 v151, 1.0, v151
	v_add_f32_e32 v152, 1.0, v152
	v_add_f32_e32 v153, 1.0, v153
	v_rcp_f32_e32 v138, v138
	v_rcp_f32_e32 v139, v139
	v_rcp_f32_e32 v150, v150
	v_rcp_f32_e32 v151, v151
	v_rcp_f32_e32 v152, v152
	v_rcp_f32_e32 v153, v153
	v_pk_mul_f32 v[156:157], v[144:145], v[148:149]
	v_lshlrev_b64 v[148:149], 10, v[214:215]
	v_pk_mul_f32 v[138:139], v[142:143], v[138:139]
	v_pk_mul_f32 v[150:151], v[146:147], v[150:151]
	v_pk_mul_f32 v[152:153], v[140:141], v[152:153]
	v_lshl_add_u64 v[148:149], s[10:11], 0, v[148:149]
	v_lshl_add_u64 v[158:159], v[186:187], 1, v[148:149]
	v_cvt_pk_bf16_f32 v148, v138, v139
	v_cvt_pk_bf16_f32 v149, v156, v157
	v_cvt_pk_bf16_f32 v150, v150, v151
	v_cvt_pk_bf16_f32 v151, v152, v153
	global_store_dwordx4 v[158:159], v[148:151], off offset:-3072 nt
	s_nop 1
	v_lshlrev_b64 v[148:149], 10, v[214:215]
	v_lshl_add_u64 v[138:139], s[8:9], 0, v[148:149]
	s_branch .LBB0_1438

.LBB0_1433:
	s_and_b64 vcc, exec, s[18:19]
	s_cbranch_vccz .LBB0_1435
	v_mul_f32_e32 v150, 0xbfb8aa3b, v144
	v_exp_f32_e32 v150, v150
	v_mul_f32_e32 v151, 0xbfb8aa3b, v145
	v_mul_f32_e32 v152, 0xbfb8aa3b, v146
	v_exp_f32_e32 v151, v151
	v_add_f32_e32 v150, 1.0, v150
	v_rcp_f32_e32 v150, v150
	v_exp_f32_e32 v152, v152
	v_mul_f32_e32 v138, 0xbfb8aa3b, v142
	v_mul_f32_e32 v149, 0xbfb8aa3b, v143
	v_fma_f32 v150, v240, v150, v40
	v_log_f32_e32 v153, v150
	v_add_f32_e32 v150, 1.0, v151
	v_add_f32_e32 v151, 1.0, v152
	v_rcp_f32_e32 v151, v151
	v_mul_f32_e32 v152, 0xbfb8aa3b, v147
	v_exp_f32_e32 v152, v152
	v_exp_f32_e32 v148, v138
	v_fma_f32 v151, v238, v151, v34
	v_exp_f32_e32 v149, v149
	v_log_f32_e32 v156, v151
	v_add_f32_e32 v151, 1.0, v152
	v_mul_f32_e32 v152, 0xbfb8aa3b, v140
	v_mul_f32_e32 v157, 0xbfb8aa3b, v141
	v_exp_f32_e32 v152, v152
	v_exp_f32_e32 v157, v157
	v_add_f32_e32 v148, 1.0, v148
	v_add_f32_e32 v149, 1.0, v149
	v_rcp_f32_e32 v148, v148
	v_rcp_f32_e32 v149, v149
	v_add_f32_e32 v152, 1.0, v152
	v_add_f32_e32 v157, 1.0, v157
	v_rcp_f32_e32 v150, v150
	v_rcp_f32_e32 v151, v151
	v_rcp_f32_e32 v152, v152
	v_rcp_f32_e32 v157, v157
	v_fma_f32 v148, v242, v148, v38
	v_fma_f32 v149, v241, v149, v39
	v_log_f32_e32 v148, v148
	v_fma_f32 v150, v239, v150, v41
	v_fma_f32 v151, v234, v151, v35
	v_fma_f32 v152, v233, v152, v36
	v_fma_f32 v157, v229, v157, v37
	v_log_f32_e32 v176, v149
	v_log_f32_e32 v152, v152
	v_log_f32_e32 v157, v157
	v_log_f32_e32 v158, v151
	v_log_f32_e32 v159, v150
	s_and_b64 s[18:19], s[54:55], exec
	s_cselect_b32 s19, s87, s92
	s_cselect_b32 s18, s79, s89
	v_lshlrev_b64 v[138:139], 10, v[214:215]
	v_cvt_pk_f16_f32 v148, v148, v176
	v_lshl_add_u64 v[138:139], s[18:19], 0, v[138:139]
	v_lshlrev_b32_e32 v176, 1, v191
	v_cvt_pk_f16_f32 v151, v152, v157
	v_cvt_pk_f16_f32 v150, v156, v158
	v_cvt_pk_f16_f32 v149, v153, v159
	v_lshl_add_u64 v[138:139], v[138:139], 0, v[176:177]
	global_store_dwordx4 v[138:139], v[148:151], off
	s_nop 1
	v_lshlrev_b64 v[148:149], 10, v[214:215]
	v_lshl_add_u64 v[138:139], s[8:9], 0, v[148:149]
	s_branch .LBB0_1438

.LBB0_1438:
	v_mov_b32_e32 v217, v216
	v_pk_fma_f32 v[134:135], v[134:135], v[216:217], v[30:31]
	v_pk_fma_f32 v[136:137], v[136:137], v[216:217], v[32:33]
	v_pk_fma_f32 v[130:131], v[130:131], v[216:217], v[26:27]
	v_pk_fma_f32 v[132:133], v[132:133], v[216:217], v[28:29]
	s_and_b64 vcc, exec, s[4:5]
	s_mov_b64 s[18:19], -1
	s_cbranch_vccnz .LBB0_1456
	s_and_b64 vcc, exec, s[2:3]
	s_cbranch_vccnz .LBB0_1453
	s_cmp_lt_i32 s39, 4
	s_cbranch_scc1 .LBB0_1450
	s_cmp_lg_u32 s39, 4
	s_cbranch_scc0 .LBB0_1447
	s_andn2_b64 vcc, exec, s[56:57]
	s_cbranch_vccnz .LBB0_1444
	v_mul_f32_e32 v140, 0xbfb8aa3b, v134
	v_mul_f32_e32 v141, 0xbfb8aa3b, v135
	v_exp_f32_e32 v140, v140
	v_exp_f32_e32 v141, v141
	v_mul_f32_e32 v143, 0xbfb8aa3b, v137
	v_exp_f32_e32 v143, v143
	v_add_f32_e32 v140, 1.0, v140
	v_add_f32_e32 v141, 1.0, v141
	v_rcp_f32_e32 v140, v140
	v_rcp_f32_e32 v141, v141
	v_mul_f32_e32 v144, 0xbfb8aa3b, v133
	v_mul_f32_e32 v142, 0xbfb8aa3b, v136
	v_max_f32_e32 v146, 0x219392ef, v140
	v_max_f32_e32 v147, 0x219392ef, v141
	v_add_f32_e32 v140, 1.0, v143
	v_mul_f32_e32 v141, 0xbfb8aa3b, v130
	v_mul_f32_e32 v143, 0xbfb8aa3b, v131
	v_rcp_f32_e32 v140, v140
	v_exp_f32_e32 v141, v141
	v_exp_f32_e32 v143, v143
	v_exp_f32_e32 v144, v144
	v_max_f32_e32 v150, 0x219392ef, v140
	v_add_f32_e32 v140, 1.0, v141
	v_add_f32_e32 v141, 1.0, v143
	v_mul_f32_e32 v143, 0xbfb8aa3b, v132
	v_exp_f32_e32 v142, v142
	v_exp_f32_e32 v143, v143
	v_rcp_f32_e32 v140, v140
	v_rcp_f32_e32 v141, v141
	v_add_f32_e32 v144, 1.0, v144
	v_add_f32_e32 v142, 1.0, v142
	v_add_f32_e32 v143, 1.0, v143
	v_rcp_f32_e32 v144, v144
	v_rcp_f32_e32 v142, v142
	v_rcp_f32_e32 v143, v143
	v_max_f32_e32 v151, 0x219392ef, v140
	v_max_f32_e32 v152, 0x219392ef, v141
	v_lshlrev_b64 v[140:141], 12, v[214:215]
	v_lshl_add_u64 v[140:141], s[16:17], 0, v[140:141]
	v_max_f32_e32 v153, 0x219392ef, v144
	v_lshl_add_u64 v[144:145], v[186:187], 1, v[140:141]
	v_max_f32_e32 v142, 0x219392ef, v142
	v_max_f32_e32 v143, 0x219392ef, v143
	v_add_co_u32_e32 v144, vcc, 0xfffff000, v144
	v_cvt_pk_bf16_f32 v140, v146, v147
	v_cvt_pk_bf16_f32 v141, v142, v150
	v_cvt_pk_bf16_f32 v142, v151, v152
	v_cvt_pk_bf16_f32 v143, v143, v153
	v_addc_co_u32_e32 v145, vcc, -1, v145, vcc
	s_mov_b64 s[18:19], 0
	global_store_dwordx4 v[144:145], v[140:143], off offset:-3840 nt
	s_nop 1
	s_branch .LBB0_1458
.LBB0_1444:
	s_andn2_b64 vcc, exec, s[18:19]
	s_cbranch_vccnz .LBB0_1446
	s_ashr_i32 s18, s41, 11
	s_ashr_i32 s19, s18, 31
	s_lshl_b64 s[18:19], s[18:19], 11
	v_lshl_add_u64 v[140:141], s[18:19], 0, v[154:155]
	s_movk_i32 s18, 0x7df
	v_and_or_b32 v140, v214, s18, v140
	v_lshl_add_u64 v[144:145], v[140:141], 4, s[14:15]
	v_cvt_pk_bf16_f32 v140, v134, v135
	v_cvt_pk_bf16_f32 v141, v136, v137
	v_cvt_pk_bf16_f32 v142, v130, v131
	v_cvt_pk_bf16_f32 v143, v132, v133
	global_store_dwordx4 v[144:145], v[140:143], off nt
	s_nop 1
	s_branch .LBB0_1458

.LBB0_1447:
	s_andn2_b64 vcc, exec, s[18:19]
	s_cbranch_vccnz .LBB0_1449
	v_mul_f32_e32 v140, 0xbfb8aa3b, v134
	v_mul_f32_e32 v141, 0xbfb8aa3b, v135
	v_mul_f32_e32 v142, 0xbfb8aa3b, v136
	v_mul_f32_e32 v143, 0xbfb8aa3b, v137
	v_mul_f32_e32 v144, 0xbfb8aa3b, v130
	v_mul_f32_e32 v145, 0xbfb8aa3b, v131
	v_mul_f32_e32 v146, 0xbfb8aa3b, v132
	v_mul_f32_e32 v147, 0xbfb8aa3b, v133
	v_exp_f32_e32 v140, v140
	v_exp_f32_e32 v141, v141
	v_exp_f32_e32 v142, v142
	v_exp_f32_e32 v143, v143
	v_exp_f32_e32 v144, v144
	v_exp_f32_e32 v145, v145
	v_exp_f32_e32 v146, v146
	v_exp_f32_e32 v147, v147
	v_add_f32_e32 v140, 1.0, v140
	v_add_f32_e32 v141, 1.0, v141
	v_add_f32_e32 v142, 1.0, v142
	v_add_f32_e32 v143, 1.0, v143
	v_add_f32_e32 v144, 1.0, v144
	v_add_f32_e32 v145, 1.0, v145
	v_add_f32_e32 v146, 1.0, v146
	v_add_f32_e32 v147, 1.0, v147
	v_rcp_f32_e32 v140, v140
	v_rcp_f32_e32 v141, v141
	v_rcp_f32_e32 v142, v142
	v_rcp_f32_e32 v143, v143
	v_rcp_f32_e32 v144, v144
	v_rcp_f32_e32 v145, v145
	v_rcp_f32_e32 v146, v146
	v_rcp_f32_e32 v147, v147
	v_pk_mul_f32 v[140:141], v[134:135], v[140:141]
	v_pk_mul_f32 v[142:143], v[136:137], v[142:143]
	v_pk_mul_f32 v[144:145], v[130:131], v[144:145]
	v_pk_mul_f32 v[146:147], v[132:133], v[146:147]
	v_lshl_add_u64 v[150:151], s[12:13], 0, v[148:149]
	v_lshl_add_u64 v[150:151], v[186:187], 1, v[150:151]
	v_cvt_pk_bf16_f32 v140, v140, v141
	v_cvt_pk_bf16_f32 v141, v142, v143
	v_cvt_pk_bf16_f32 v142, v144, v145
	v_cvt_pk_bf16_f32 v143, v146, v147
	global_store_dwordx4 v[150:151], v[140:143], off offset:-3840 nt
	s_nop 1
	s_branch .LBB0_1458

.LBB0_1450:
	s_andn2_b64 vcc, exec, s[18:19]
	s_cbranch_vccnz .LBB0_1452
	v_mul_f32_e32 v140, 0xbfb8aa3b, v134
	v_mul_f32_e32 v141, 0xbfb8aa3b, v135
	v_mul_f32_e32 v142, 0xbfb8aa3b, v136
	v_mul_f32_e32 v143, 0xbfb8aa3b, v137
	v_mul_f32_e32 v144, 0xbfb8aa3b, v130
	v_mul_f32_e32 v145, 0xbfb8aa3b, v131
	v_mul_f32_e32 v146, 0xbfb8aa3b, v132
	v_mul_f32_e32 v147, 0xbfb8aa3b, v133
	v_exp_f32_e32 v140, v140
	v_exp_f32_e32 v141, v141
	v_exp_f32_e32 v142, v142
	v_exp_f32_e32 v143, v143
	v_exp_f32_e32 v144, v144
	v_exp_f32_e32 v145, v145
	v_exp_f32_e32 v146, v146
	v_exp_f32_e32 v147, v147
	v_add_f32_e32 v140, 1.0, v140
	v_add_f32_e32 v141, 1.0, v141
	v_add_f32_e32 v142, 1.0, v142
	v_add_f32_e32 v143, 1.0, v143
	v_add_f32_e32 v144, 1.0, v144
	v_add_f32_e32 v145, 1.0, v145
	v_add_f32_e32 v146, 1.0, v146
	v_add_f32_e32 v147, 1.0, v147
	v_rcp_f32_e32 v140, v140
	v_rcp_f32_e32 v141, v141
	v_rcp_f32_e32 v142, v142
	v_rcp_f32_e32 v143, v143
	v_rcp_f32_e32 v144, v144
	v_rcp_f32_e32 v145, v145
	v_rcp_f32_e32 v146, v146
	v_rcp_f32_e32 v147, v147
	v_pk_mul_f32 v[140:141], v[134:135], v[140:141]
	v_pk_mul_f32 v[142:143], v[136:137], v[142:143]
	v_pk_mul_f32 v[144:145], v[130:131], v[144:145]
	v_pk_mul_f32 v[146:147], v[132:133], v[146:147]
	v_lshl_add_u64 v[150:151], s[10:11], 0, v[148:149]
	v_lshl_add_u64 v[150:151], v[186:187], 1, v[150:151]
	v_cvt_pk_bf16_f32 v140, v140, v141
	v_cvt_pk_bf16_f32 v141, v142, v143
	v_cvt_pk_bf16_f32 v142, v144, v145
	v_cvt_pk_bf16_f32 v143, v146, v147
	global_store_dwordx4 v[150:151], v[140:143], off offset:-2816 nt
	s_nop 1
	s_branch .LBB0_1458

.LBB0_1453:
	s_and_b64 vcc, exec, s[18:19]
	s_cbranch_vccz .LBB0_1455
	v_mul_f32_e32 v142, 0xbfb8aa3b, v136
	v_exp_f32_e32 v142, v142
	v_mul_f32_e32 v143, 0xbfb8aa3b, v137
	v_mul_f32_e32 v144, 0xbfb8aa3b, v130
	v_exp_f32_e32 v143, v143
	v_add_f32_e32 v142, 1.0, v142
	v_rcp_f32_e32 v142, v142
	v_exp_f32_e32 v144, v144
	v_mul_f32_e32 v147, 0xbfb8aa3b, v133
	v_mul_f32_e32 v140, 0xbfb8aa3b, v134
	v_fma_f32 v142, v235, v142, v12
	v_log_f32_e32 v145, v142
	v_add_f32_e32 v142, 1.0, v143
	v_add_f32_e32 v143, 1.0, v144
	v_rcp_f32_e32 v143, v143
	v_mul_f32_e32 v144, 0xbfb8aa3b, v131
	v_exp_f32_e32 v144, v144
	v_mul_f32_e32 v141, 0xbfb8aa3b, v135
	v_fma_f32 v143, v223, v143, v14
	v_log_f32_e32 v146, v143
	v_add_f32_e32 v143, 1.0, v144
	v_mul_f32_e32 v144, 0xbfb8aa3b, v132
	v_exp_f32_e32 v144, v144
	v_exp_f32_e32 v147, v147
	v_exp_f32_e32 v140, v140
	v_exp_f32_e32 v141, v141
	v_add_f32_e32 v144, 1.0, v144
	v_add_f32_e32 v147, 1.0, v147
	v_add_f32_e32 v140, 1.0, v140
	v_add_f32_e32 v141, 1.0, v141
	v_rcp_f32_e32 v142, v142
	v_rcp_f32_e32 v144, v144
	v_rcp_f32_e32 v147, v147
	v_rcp_f32_e32 v140, v140
	v_rcp_f32_e32 v141, v141
	v_rcp_f32_e32 v143, v143
	v_fma_f32 v142, v222, v142, v13
	v_fma_f32 v144, v221, v144, v16
	v_fma_f32 v147, v161, v147, v17
	v_fma_f32 v140, v237, v140, v10
	v_fma_f32 v141, v236, v141, v11
	v_fma_f32 v143, v220, v143, v15
	v_log_f32_e32 v144, v144
	v_log_f32_e32 v147, v147
	v_log_f32_e32 v151, v142
	v_log_f32_e32 v140, v140
	v_log_f32_e32 v150, v143
	v_log_f32_e32 v152, v141
	s_and_b64 s[18:19], s[54:55], exec
	s_cselect_b32 s19, s87, s92
	s_cselect_b32 s18, s79, s89
	v_cvt_pk_f16_f32 v143, v144, v147
	v_cvt_pk_f16_f32 v141, v145, v151
	v_lshl_add_u64 v[144:145], s[18:19], 0, v[148:149]
	v_lshlrev_b32_e32 v176, 1, v160
	v_cvt_pk_f16_f32 v142, v146, v150
	v_cvt_pk_f16_f32 v140, v140, v152
	v_lshl_add_u64 v[144:145], v[144:145], 0, v[176:177]
	global_store_dwordx4 v[144:145], v[140:143], off
	s_nop 1
	s_branch .LBB0_1458

.LBB0_1458:
	v_pk_fma_f32 v[126:127], v[126:127], v[212:213], v[54:55] op_sel_hi:[1,0,1]
	v_pk_fma_f32 v[128:129], v[128:129], v[212:213], v[56:57] op_sel_hi:[1,0,1]
	v_pk_fma_f32 v[130:131], v[122:123], v[212:213], v[50:51] op_sel_hi:[1,0,1]
	v_pk_fma_f32 v[124:125], v[124:125], v[212:213], v[52:53] op_sel_hi:[1,0,1]
	s_and_b64 vcc, exec, s[4:5]
	s_mov_b64 s[18:19], -1
	s_cbranch_vccnz .LBB0_1476
	s_and_b64 vcc, exec, s[2:3]
	s_cbranch_vccnz .LBB0_1473
	s_cmp_lt_i32 s39, 4
	s_cbranch_scc1 .LBB0_1470
	s_cmp_lg_u32 s39, 4
	s_cbranch_scc0 .LBB0_1467
	s_andn2_b64 vcc, exec, s[56:57]
	s_cbranch_vccnz .LBB0_1464
	v_mul_f32_e32 v122, 0xbfb8aa3b, v126
	v_mul_f32_e32 v123, 0xbfb8aa3b, v127
	v_mul_f32_e32 v132, 0xbfb8aa3b, v128
	v_exp_f32_e32 v122, v122
	v_exp_f32_e32 v123, v123
	v_exp_f32_e32 v132, v132
	v_mul_f32_e32 v133, 0xbfb8aa3b, v129
	v_add_f32_e32 v122, 1.0, v122
	v_add_f32_e32 v123, 1.0, v123
	v_add_f32_e32 v132, 1.0, v132
	v_rcp_f32_e32 v122, v122
	v_rcp_f32_e32 v123, v123
	v_rcp_f32_e32 v132, v132
	v_exp_f32_e32 v133, v133
	v_max_f32_e32 v134, 0x219392ef, v122
	v_max_f32_e32 v135, 0x219392ef, v123
	v_max_f32_e32 v136, 0x219392ef, v132
	v_add_f32_e32 v122, 1.0, v133
	v_mul_f32_e32 v123, 0xbfb8aa3b, v130
	v_mul_f32_e32 v132, 0xbfb8aa3b, v131
	v_rcp_f32_e32 v122, v122
	v_exp_f32_e32 v123, v123
	v_exp_f32_e32 v132, v132
	v_mul_f32_e32 v137, 0xbfb8aa3b, v125
	v_max_f32_e32 v133, 0x219392ef, v122
	v_add_f32_e32 v122, 1.0, v123
	v_add_f32_e32 v123, 1.0, v132
	v_mul_f32_e32 v132, 0xbfb8aa3b, v124
	v_exp_f32_e32 v132, v132
	v_exp_f32_e32 v137, v137
	v_rcp_f32_e32 v122, v122
	v_rcp_f32_e32 v123, v123
	v_add_f32_e32 v132, 1.0, v132
	v_add_f32_e32 v137, 1.0, v137
	v_rcp_f32_e32 v132, v132
	v_rcp_f32_e32 v137, v137
	v_max_f32_e32 v138, 0x219392ef, v122
	v_max_f32_e32 v139, 0x219392ef, v123
	v_lshlrev_b64 v[122:123], 12, v[210:211]
	v_lshl_add_u64 v[122:123], s[16:17], 0, v[122:123]
	v_lshl_add_u64 v[122:123], v[186:187], 1, v[122:123]
	v_max_f32_e32 v140, 0x219392ef, v132
	v_max_f32_e32 v137, 0x219392ef, v137
	v_add_co_u32_e32 v122, vcc, 0xffffe000, v122
	v_cvt_pk_bf16_f32 v132, v134, v135
	v_cvt_pk_bf16_f32 v133, v136, v133
	v_cvt_pk_bf16_f32 v134, v138, v139
	v_cvt_pk_bf16_f32 v135, v140, v137
	v_addc_co_u32_e32 v123, vcc, -1, v123, vcc
	s_mov_b64 s[18:19], 0
	global_store_dwordx4 v[122:123], v[132:135], off nt
	s_nop 1
	v_lshlrev_b64 v[132:133], 10, v[210:211]
	v_lshl_add_u64 v[122:123], s[8:9], 0, v[132:133]
	s_branch .LBB0_1478
.LBB0_1464:
	s_andn2_b64 vcc, exec, s[18:19]
	s_cbranch_vccnz .LBB0_1466
	s_ashr_i32 s18, s41, 11
	s_ashr_i32 s19, s18, 31
	s_lshl_b64 s[18:19], s[18:19], 11
	v_lshl_add_u64 v[122:123], s[18:19], 0, v[192:193]
	s_movk_i32 s18, 0x7ef
	v_and_or_b32 v122, v210, s18, v122
	v_lshl_add_u64 v[122:123], v[122:123], 4, s[14:15]
	v_cvt_pk_bf16_f32 v132, v126, v127
	v_cvt_pk_bf16_f32 v133, v128, v129
	v_cvt_pk_bf16_f32 v134, v130, v131
	v_cvt_pk_bf16_f32 v135, v124, v125
	global_store_dwordx4 v[122:123], v[132:135], off nt
	s_nop 1
	v_lshlrev_b64 v[132:133], 10, v[210:211]
	v_lshl_add_u64 v[122:123], s[8:9], 0, v[132:133]
	s_branch .LBB0_1478

.LBB0_1467:
	s_andn2_b64 vcc, exec, s[18:19]
	s_cbranch_vccnz .LBB0_1469
	v_mul_f32_e32 v132, 0xbfb8aa3b, v128
	v_mul_f32_e32 v133, 0xbfb8aa3b, v129
	v_mul_f32_e32 v122, 0xbfb8aa3b, v126
	v_mul_f32_e32 v123, 0xbfb8aa3b, v127
	v_exp_f32_e32 v132, v132
	v_exp_f32_e32 v133, v133
	v_mul_f32_e32 v134, 0xbfb8aa3b, v130
	v_mul_f32_e32 v135, 0xbfb8aa3b, v131
	v_mul_f32_e32 v136, 0xbfb8aa3b, v124
	v_mul_f32_e32 v137, 0xbfb8aa3b, v125
	v_exp_f32_e32 v122, v122
	v_exp_f32_e32 v123, v123
	v_exp_f32_e32 v134, v134
	v_exp_f32_e32 v135, v135
	v_exp_f32_e32 v136, v136
	v_exp_f32_e32 v137, v137
	v_add_f32_e32 v132, 1.0, v132
	v_add_f32_e32 v133, 1.0, v133
	v_add_f32_e32 v122, 1.0, v122
	v_add_f32_e32 v123, 1.0, v123
	v_rcp_f32_e32 v132, v132
	v_rcp_f32_e32 v133, v133
	v_add_f32_e32 v134, 1.0, v134
	v_add_f32_e32 v135, 1.0, v135
	v_add_f32_e32 v136, 1.0, v136
	v_add_f32_e32 v137, 1.0, v137
	v_rcp_f32_e32 v122, v122
	v_rcp_f32_e32 v123, v123
	v_rcp_f32_e32 v134, v134
	v_rcp_f32_e32 v135, v135
	v_rcp_f32_e32 v136, v136
	v_rcp_f32_e32 v137, v137
	v_pk_mul_f32 v[138:139], v[128:129], v[132:133]
	v_lshlrev_b64 v[132:133], 10, v[210:211]
	v_pk_mul_f32 v[122:123], v[126:127], v[122:123]
	v_pk_mul_f32 v[134:135], v[130:131], v[134:135]
	v_pk_mul_f32 v[136:137], v[124:125], v[136:137]
	v_lshl_add_u64 v[132:133], s[12:13], 0, v[132:133]
	v_lshl_add_u64 v[140:141], v[186:187], 1, v[132:133]
	v_cvt_pk_bf16_f32 v132, v122, v123
	v_cvt_pk_bf16_f32 v133, v138, v139
	v_cvt_pk_bf16_f32 v134, v134, v135
	v_cvt_pk_bf16_f32 v135, v136, v137
	global_store_dwordx4 v[140:141], v[132:135], off offset:-4096 nt
	s_nop 1
	v_lshlrev_b64 v[132:133], 10, v[210:211]
	v_lshl_add_u64 v[122:123], s[8:9], 0, v[132:133]
	s_branch .LBB0_1478

.LBB0_1470:
	s_andn2_b64 vcc, exec, s[18:19]
	s_cbranch_vccnz .LBB0_1472
	v_mul_f32_e32 v132, 0xbfb8aa3b, v128
	v_mul_f32_e32 v133, 0xbfb8aa3b, v129
	v_mul_f32_e32 v122, 0xbfb8aa3b, v126
	v_mul_f32_e32 v123, 0xbfb8aa3b, v127
	v_exp_f32_e32 v132, v132
	v_exp_f32_e32 v133, v133
	v_mul_f32_e32 v134, 0xbfb8aa3b, v130
	v_mul_f32_e32 v135, 0xbfb8aa3b, v131
	v_mul_f32_e32 v136, 0xbfb8aa3b, v124
	v_mul_f32_e32 v137, 0xbfb8aa3b, v125
	v_exp_f32_e32 v122, v122
	v_exp_f32_e32 v123, v123
	v_exp_f32_e32 v134, v134
	v_exp_f32_e32 v135, v135
	v_exp_f32_e32 v136, v136
	v_exp_f32_e32 v137, v137
	v_add_f32_e32 v132, 1.0, v132
	v_add_f32_e32 v133, 1.0, v133
	v_add_f32_e32 v122, 1.0, v122
	v_add_f32_e32 v123, 1.0, v123
	v_rcp_f32_e32 v132, v132
	v_rcp_f32_e32 v133, v133
	v_add_f32_e32 v134, 1.0, v134
	v_add_f32_e32 v135, 1.0, v135
	v_add_f32_e32 v136, 1.0, v136
	v_add_f32_e32 v137, 1.0, v137
	v_rcp_f32_e32 v122, v122
	v_rcp_f32_e32 v123, v123
	v_rcp_f32_e32 v134, v134
	v_rcp_f32_e32 v135, v135
	v_rcp_f32_e32 v136, v136
	v_rcp_f32_e32 v137, v137
	v_pk_mul_f32 v[138:139], v[128:129], v[132:133]
	v_lshlrev_b64 v[132:133], 10, v[210:211]
	v_pk_mul_f32 v[122:123], v[126:127], v[122:123]
	v_pk_mul_f32 v[134:135], v[130:131], v[134:135]
	v_pk_mul_f32 v[136:137], v[124:125], v[136:137]
	v_lshl_add_u64 v[132:133], s[10:11], 0, v[132:133]
	v_lshl_add_u64 v[140:141], v[186:187], 1, v[132:133]
	v_cvt_pk_bf16_f32 v132, v122, v123
	v_cvt_pk_bf16_f32 v133, v138, v139
	v_cvt_pk_bf16_f32 v134, v134, v135
	v_cvt_pk_bf16_f32 v135, v136, v137
	global_store_dwordx4 v[140:141], v[132:135], off offset:-3072 nt
	s_nop 1
	v_lshlrev_b64 v[132:133], 10, v[210:211]
	v_lshl_add_u64 v[122:123], s[8:9], 0, v[132:133]
	s_branch .LBB0_1478

.LBB0_1473:
	s_and_b64 vcc, exec, s[18:19]
	s_cbranch_vccz .LBB0_1475
	v_mul_f32_e32 v134, 0xbfb8aa3b, v128
	v_exp_f32_e32 v134, v134
	v_mul_f32_e32 v135, 0xbfb8aa3b, v129
	v_mul_f32_e32 v136, 0xbfb8aa3b, v130
	v_exp_f32_e32 v135, v135
	v_add_f32_e32 v134, 1.0, v134
	v_rcp_f32_e32 v134, v134
	v_exp_f32_e32 v136, v136
	v_mul_f32_e32 v122, 0xbfb8aa3b, v126
	v_mul_f32_e32 v133, 0xbfb8aa3b, v127
	v_fma_f32 v134, v240, v134, v40
	v_log_f32_e32 v137, v134
	v_add_f32_e32 v134, 1.0, v135
	v_add_f32_e32 v135, 1.0, v136
	v_rcp_f32_e32 v135, v135
	v_mul_f32_e32 v136, 0xbfb8aa3b, v131
	v_exp_f32_e32 v136, v136
	v_mul_f32_e32 v139, 0xbfb8aa3b, v125
	v_fma_f32 v135, v238, v135, v34
	v_log_f32_e32 v138, v135
	v_add_f32_e32 v135, 1.0, v136
	v_mul_f32_e32 v136, 0xbfb8aa3b, v124
	v_exp_f32_e32 v132, v122
	v_exp_f32_e32 v133, v133
	v_exp_f32_e32 v136, v136
	v_exp_f32_e32 v139, v139
	v_add_f32_e32 v132, 1.0, v132
	v_add_f32_e32 v133, 1.0, v133
	v_add_f32_e32 v136, 1.0, v136
	v_add_f32_e32 v139, 1.0, v139
	v_rcp_f32_e32 v132, v132
	v_rcp_f32_e32 v133, v133
	v_rcp_f32_e32 v134, v134
	v_rcp_f32_e32 v135, v135
	v_rcp_f32_e32 v136, v136
	v_rcp_f32_e32 v139, v139
	v_fma_f32 v132, v242, v132, v38
	v_fma_f32 v133, v241, v133, v39
	v_fma_f32 v134, v239, v134, v41
	v_fma_f32 v135, v234, v135, v35
	v_fma_f32 v136, v233, v136, v36
	v_fma_f32 v139, v229, v139, v37
	v_log_f32_e32 v132, v132
	v_log_f32_e32 v136, v136
	v_log_f32_e32 v139, v139
	v_log_f32_e32 v140, v135
	v_log_f32_e32 v141, v134
	v_log_f32_e32 v142, v133
	s_and_b64 s[18:19], s[54:55], exec
	s_cselect_b32 s19, s87, s92
	s_cselect_b32 s18, s79, s89
	v_lshlrev_b64 v[122:123], 10, v[210:211]
	v_lshl_add_u64 v[122:123], s[18:19], 0, v[122:123]
	v_lshlrev_b32_e32 v176, 1, v191
	v_cvt_pk_f16_f32 v135, v136, v139
	v_cvt_pk_f16_f32 v134, v138, v140
	v_cvt_pk_f16_f32 v133, v137, v141
	v_cvt_pk_f16_f32 v132, v132, v142
	v_lshl_add_u64 v[122:123], v[122:123], 0, v[176:177]
	global_store_dwordx4 v[122:123], v[132:135], off
	s_nop 1
	v_lshlrev_b64 v[132:133], 10, v[210:211]
	v_lshl_add_u64 v[122:123], s[8:9], 0, v[132:133]
	s_branch .LBB0_1478

.LBB0_1478:
	v_mov_b32_e32 v213, v212
	v_pk_fma_f32 v[118:119], v[118:119], v[212:213], v[30:31]
	v_pk_fma_f32 v[120:121], v[120:121], v[212:213], v[32:33]
	v_pk_fma_f32 v[114:115], v[114:115], v[212:213], v[26:27]
	v_pk_fma_f32 v[116:117], v[116:117], v[212:213], v[28:29]
	s_and_b64 vcc, exec, s[4:5]
	s_mov_b64 s[18:19], -1
	s_cbranch_vccnz .LBB0_1496
	s_and_b64 vcc, exec, s[2:3]
	s_cbranch_vccnz .LBB0_1493
	s_cmp_lt_i32 s39, 4
	s_cbranch_scc1 .LBB0_1490
	s_cmp_lg_u32 s39, 4
	s_cbranch_scc0 .LBB0_1487
	s_andn2_b64 vcc, exec, s[56:57]
	s_cbranch_vccnz .LBB0_1484
	v_mul_f32_e32 v124, 0xbfb8aa3b, v118
	v_mul_f32_e32 v125, 0xbfb8aa3b, v119
	v_exp_f32_e32 v124, v124
	v_exp_f32_e32 v125, v125
	v_mul_f32_e32 v127, 0xbfb8aa3b, v121
	v_exp_f32_e32 v127, v127
	v_add_f32_e32 v124, 1.0, v124
	v_add_f32_e32 v125, 1.0, v125
	v_rcp_f32_e32 v124, v124
	v_rcp_f32_e32 v125, v125
	v_mul_f32_e32 v128, 0xbfb8aa3b, v117
	v_mul_f32_e32 v126, 0xbfb8aa3b, v120
	v_max_f32_e32 v130, 0x219392ef, v124
	v_max_f32_e32 v131, 0x219392ef, v125
	v_add_f32_e32 v124, 1.0, v127
	v_mul_f32_e32 v125, 0xbfb8aa3b, v114
	v_mul_f32_e32 v127, 0xbfb8aa3b, v115
	v_rcp_f32_e32 v124, v124
	v_exp_f32_e32 v125, v125
	v_exp_f32_e32 v127, v127
	v_exp_f32_e32 v128, v128
	v_max_f32_e32 v134, 0x219392ef, v124
	v_add_f32_e32 v124, 1.0, v125
	v_add_f32_e32 v125, 1.0, v127
	v_mul_f32_e32 v127, 0xbfb8aa3b, v116
	v_exp_f32_e32 v126, v126
	v_exp_f32_e32 v127, v127
	v_rcp_f32_e32 v124, v124
	v_rcp_f32_e32 v125, v125
	v_add_f32_e32 v128, 1.0, v128
	v_add_f32_e32 v126, 1.0, v126
	v_add_f32_e32 v127, 1.0, v127
	v_rcp_f32_e32 v128, v128
	v_rcp_f32_e32 v126, v126
	v_rcp_f32_e32 v127, v127
	v_max_f32_e32 v135, 0x219392ef, v124
	v_max_f32_e32 v136, 0x219392ef, v125
	v_lshlrev_b64 v[124:125], 12, v[210:211]
	v_lshl_add_u64 v[124:125], s[16:17], 0, v[124:125]
	v_max_f32_e32 v137, 0x219392ef, v128
	v_lshl_add_u64 v[128:129], v[186:187], 1, v[124:125]
	v_max_f32_e32 v126, 0x219392ef, v126
	v_max_f32_e32 v127, 0x219392ef, v127
	v_add_co_u32_e32 v128, vcc, 0xfffff000, v128
	v_cvt_pk_bf16_f32 v124, v130, v131
	v_cvt_pk_bf16_f32 v125, v126, v134
	v_cvt_pk_bf16_f32 v126, v135, v136
	v_cvt_pk_bf16_f32 v127, v127, v137
	v_addc_co_u32_e32 v129, vcc, -1, v129, vcc
	s_mov_b64 s[18:19], 0
	global_store_dwordx4 v[128:129], v[124:127], off offset:-3840 nt
	s_nop 1
	s_branch .LBB0_1498
.LBB0_1484:
	s_andn2_b64 vcc, exec, s[18:19]
	s_cbranch_vccnz .LBB0_1486
	s_ashr_i32 s18, s41, 11
	s_ashr_i32 s19, s18, 31
	s_lshl_b64 s[18:19], s[18:19], 11
	v_lshl_add_u64 v[124:125], s[18:19], 0, v[154:155]
	s_movk_i32 s18, 0x7ef
	v_and_or_b32 v124, v210, s18, v124
	v_lshl_add_u64 v[128:129], v[124:125], 4, s[14:15]
	v_cvt_pk_bf16_f32 v124, v118, v119
	v_cvt_pk_bf16_f32 v125, v120, v121
	v_cvt_pk_bf16_f32 v126, v114, v115
	v_cvt_pk_bf16_f32 v127, v116, v117
	global_store_dwordx4 v[128:129], v[124:127], off nt
	s_nop 1
	s_branch .LBB0_1498

.LBB0_1487:
	s_andn2_b64 vcc, exec, s[18:19]
	s_cbranch_vccnz .LBB0_1489
	v_mul_f32_e32 v124, 0xbfb8aa3b, v118
	v_mul_f32_e32 v125, 0xbfb8aa3b, v119
	v_mul_f32_e32 v126, 0xbfb8aa3b, v120
	v_mul_f32_e32 v127, 0xbfb8aa3b, v121
	v_mul_f32_e32 v128, 0xbfb8aa3b, v114
	v_mul_f32_e32 v129, 0xbfb8aa3b, v115
	v_mul_f32_e32 v130, 0xbfb8aa3b, v116
	v_mul_f32_e32 v131, 0xbfb8aa3b, v117
	v_exp_f32_e32 v124, v124
	v_exp_f32_e32 v125, v125
	v_exp_f32_e32 v126, v126
	v_exp_f32_e32 v127, v127
	v_exp_f32_e32 v128, v128
	v_exp_f32_e32 v129, v129
	v_exp_f32_e32 v130, v130
	v_exp_f32_e32 v131, v131
	v_add_f32_e32 v124, 1.0, v124
	v_add_f32_e32 v125, 1.0, v125
	v_add_f32_e32 v126, 1.0, v126
	v_add_f32_e32 v127, 1.0, v127
	v_add_f32_e32 v128, 1.0, v128
	v_add_f32_e32 v129, 1.0, v129
	v_add_f32_e32 v130, 1.0, v130
	v_add_f32_e32 v131, 1.0, v131
	v_rcp_f32_e32 v124, v124
	v_rcp_f32_e32 v125, v125
	v_rcp_f32_e32 v126, v126
	v_rcp_f32_e32 v127, v127
	v_rcp_f32_e32 v128, v128
	v_rcp_f32_e32 v129, v129
	v_rcp_f32_e32 v130, v130
	v_rcp_f32_e32 v131, v131
	v_pk_mul_f32 v[124:125], v[118:119], v[124:125]
	v_pk_mul_f32 v[126:127], v[120:121], v[126:127]
	v_pk_mul_f32 v[128:129], v[114:115], v[128:129]
	v_pk_mul_f32 v[130:131], v[116:117], v[130:131]
	v_lshl_add_u64 v[134:135], s[12:13], 0, v[132:133]
	v_lshl_add_u64 v[134:135], v[186:187], 1, v[134:135]
	v_cvt_pk_bf16_f32 v124, v124, v125
	v_cvt_pk_bf16_f32 v125, v126, v127
	v_cvt_pk_bf16_f32 v126, v128, v129
	v_cvt_pk_bf16_f32 v127, v130, v131
	global_store_dwordx4 v[134:135], v[124:127], off offset:-3840 nt
	s_nop 1
	s_branch .LBB0_1498

.LBB0_1490:
	s_andn2_b64 vcc, exec, s[18:19]
	s_cbranch_vccnz .LBB0_1492
	v_mul_f32_e32 v124, 0xbfb8aa3b, v118
	v_mul_f32_e32 v125, 0xbfb8aa3b, v119
	v_mul_f32_e32 v126, 0xbfb8aa3b, v120
	v_mul_f32_e32 v127, 0xbfb8aa3b, v121
	v_mul_f32_e32 v128, 0xbfb8aa3b, v114
	v_mul_f32_e32 v129, 0xbfb8aa3b, v115
	v_mul_f32_e32 v130, 0xbfb8aa3b, v116
	v_mul_f32_e32 v131, 0xbfb8aa3b, v117
	v_exp_f32_e32 v124, v124
	v_exp_f32_e32 v125, v125
	v_exp_f32_e32 v126, v126
	v_exp_f32_e32 v127, v127
	v_exp_f32_e32 v128, v128
	v_exp_f32_e32 v129, v129
	v_exp_f32_e32 v130, v130
	v_exp_f32_e32 v131, v131
	v_add_f32_e32 v124, 1.0, v124
	v_add_f32_e32 v125, 1.0, v125
	v_add_f32_e32 v126, 1.0, v126
	v_add_f32_e32 v127, 1.0, v127
	v_add_f32_e32 v128, 1.0, v128
	v_add_f32_e32 v129, 1.0, v129
	v_add_f32_e32 v130, 1.0, v130
	v_add_f32_e32 v131, 1.0, v131
	v_rcp_f32_e32 v124, v124
	v_rcp_f32_e32 v125, v125
	v_rcp_f32_e32 v126, v126
	v_rcp_f32_e32 v127, v127
	v_rcp_f32_e32 v128, v128
	v_rcp_f32_e32 v129, v129
	v_rcp_f32_e32 v130, v130
	v_rcp_f32_e32 v131, v131
	v_pk_mul_f32 v[124:125], v[118:119], v[124:125]
	v_pk_mul_f32 v[126:127], v[120:121], v[126:127]
	v_pk_mul_f32 v[128:129], v[114:115], v[128:129]
	v_pk_mul_f32 v[130:131], v[116:117], v[130:131]
	v_lshl_add_u64 v[134:135], s[10:11], 0, v[132:133]
	v_lshl_add_u64 v[134:135], v[186:187], 1, v[134:135]
	v_cvt_pk_bf16_f32 v124, v124, v125
	v_cvt_pk_bf16_f32 v125, v126, v127
	v_cvt_pk_bf16_f32 v126, v128, v129
	v_cvt_pk_bf16_f32 v127, v130, v131
	global_store_dwordx4 v[134:135], v[124:127], off offset:-2816 nt
	s_nop 1
	s_branch .LBB0_1498

.LBB0_1493:
	s_and_b64 vcc, exec, s[18:19]
	s_cbranch_vccz .LBB0_1495
	v_mul_f32_e32 v126, 0xbfb8aa3b, v120
	v_exp_f32_e32 v126, v126
	v_mul_f32_e32 v127, 0xbfb8aa3b, v121
	v_mul_f32_e32 v128, 0xbfb8aa3b, v114
	v_exp_f32_e32 v127, v127
	v_add_f32_e32 v126, 1.0, v126
	v_rcp_f32_e32 v126, v126
	v_exp_f32_e32 v128, v128
	v_mul_f32_e32 v131, 0xbfb8aa3b, v117
	v_mul_f32_e32 v124, 0xbfb8aa3b, v118
	v_fma_f32 v126, v235, v126, v12
	v_log_f32_e32 v129, v126
	v_add_f32_e32 v126, 1.0, v127
	v_add_f32_e32 v127, 1.0, v128
	v_rcp_f32_e32 v127, v127
	v_mul_f32_e32 v128, 0xbfb8aa3b, v115
	v_exp_f32_e32 v128, v128
	v_mul_f32_e32 v125, 0xbfb8aa3b, v119
	v_fma_f32 v127, v223, v127, v14
	v_log_f32_e32 v130, v127
	v_add_f32_e32 v127, 1.0, v128
	v_mul_f32_e32 v128, 0xbfb8aa3b, v116
	v_exp_f32_e32 v128, v128
	v_exp_f32_e32 v131, v131
	v_exp_f32_e32 v124, v124
	v_exp_f32_e32 v125, v125
	v_add_f32_e32 v128, 1.0, v128
	v_add_f32_e32 v131, 1.0, v131
	v_add_f32_e32 v124, 1.0, v124
	v_add_f32_e32 v125, 1.0, v125
	v_rcp_f32_e32 v126, v126
	v_rcp_f32_e32 v128, v128
	v_rcp_f32_e32 v131, v131
	v_rcp_f32_e32 v124, v124
	v_rcp_f32_e32 v125, v125
	v_rcp_f32_e32 v127, v127
	v_fma_f32 v126, v222, v126, v13
	v_fma_f32 v128, v221, v128, v16
	v_fma_f32 v131, v161, v131, v17
	v_fma_f32 v124, v237, v124, v10
	v_fma_f32 v125, v236, v125, v11
	v_fma_f32 v127, v220, v127, v15
	v_log_f32_e32 v128, v128
	v_log_f32_e32 v131, v131
	v_log_f32_e32 v135, v126
	v_log_f32_e32 v124, v124
	v_log_f32_e32 v134, v127
	v_log_f32_e32 v136, v125
	s_and_b64 s[18:19], s[54:55], exec
	s_cselect_b32 s19, s87, s92
	s_cselect_b32 s18, s79, s89
	v_cvt_pk_f16_f32 v127, v128, v131
	v_cvt_pk_f16_f32 v125, v129, v135
	v_lshl_add_u64 v[128:129], s[18:19], 0, v[132:133]
	v_lshlrev_b32_e32 v176, 1, v160
	v_cvt_pk_f16_f32 v126, v130, v134
	v_cvt_pk_f16_f32 v124, v124, v136
	v_lshl_add_u64 v[128:129], v[128:129], 0, v[176:177]
	global_store_dwordx4 v[128:129], v[124:127], off
	s_nop 1
	s_branch .LBB0_1498

.LBB0_1498:
	v_pk_fma_f32 v[110:111], v[110:111], v[208:209], v[54:55] op_sel_hi:[1,0,1]
	v_pk_fma_f32 v[112:113], v[112:113], v[208:209], v[56:57] op_sel_hi:[1,0,1]
	v_pk_fma_f32 v[114:115], v[106:107], v[208:209], v[50:51] op_sel_hi:[1,0,1]
	v_pk_fma_f32 v[108:109], v[108:109], v[208:209], v[52:53] op_sel_hi:[1,0,1]
	s_and_b64 vcc, exec, s[4:5]
	s_mov_b64 s[18:19], -1
	s_cbranch_vccnz .LBB0_1516
	s_and_b64 vcc, exec, s[2:3]
	s_cbranch_vccnz .LBB0_1513
	s_cmp_lt_i32 s39, 4
	s_cbranch_scc1 .LBB0_1510
	s_cmp_lg_u32 s39, 4
	s_cbranch_scc0 .LBB0_1507
	s_andn2_b64 vcc, exec, s[56:57]
	s_cbranch_vccnz .LBB0_1504
	v_mul_f32_e32 v106, 0xbfb8aa3b, v110
	v_mul_f32_e32 v107, 0xbfb8aa3b, v111
	v_mul_f32_e32 v116, 0xbfb8aa3b, v112
	v_exp_f32_e32 v106, v106
	v_exp_f32_e32 v107, v107
	v_exp_f32_e32 v116, v116
	v_mul_f32_e32 v117, 0xbfb8aa3b, v113
	v_add_f32_e32 v106, 1.0, v106
	v_add_f32_e32 v107, 1.0, v107
	v_add_f32_e32 v116, 1.0, v116
	v_rcp_f32_e32 v106, v106
	v_rcp_f32_e32 v107, v107
	v_rcp_f32_e32 v116, v116
	v_exp_f32_e32 v117, v117
	v_max_f32_e32 v118, 0x219392ef, v106
	v_max_f32_e32 v119, 0x219392ef, v107
	v_max_f32_e32 v120, 0x219392ef, v116
	v_add_f32_e32 v106, 1.0, v117
	v_mul_f32_e32 v107, 0xbfb8aa3b, v114
	v_mul_f32_e32 v116, 0xbfb8aa3b, v115
	v_rcp_f32_e32 v106, v106
	v_exp_f32_e32 v107, v107
	v_exp_f32_e32 v116, v116
	v_mul_f32_e32 v121, 0xbfb8aa3b, v109
	v_max_f32_e32 v117, 0x219392ef, v106
	v_add_f32_e32 v106, 1.0, v107
	v_add_f32_e32 v107, 1.0, v116
	v_mul_f32_e32 v116, 0xbfb8aa3b, v108
	v_exp_f32_e32 v116, v116
	v_exp_f32_e32 v121, v121
	v_rcp_f32_e32 v106, v106
	v_rcp_f32_e32 v107, v107
	v_add_f32_e32 v116, 1.0, v116
	v_add_f32_e32 v121, 1.0, v121
	v_rcp_f32_e32 v116, v116
	v_rcp_f32_e32 v121, v121
	v_max_f32_e32 v122, 0x219392ef, v106
	v_max_f32_e32 v123, 0x219392ef, v107
	v_lshlrev_b64 v[106:107], 12, v[206:207]
	v_lshl_add_u64 v[106:107], s[16:17], 0, v[106:107]
	v_lshl_add_u64 v[106:107], v[186:187], 1, v[106:107]
	v_max_f32_e32 v124, 0x219392ef, v116
	v_max_f32_e32 v121, 0x219392ef, v121
	v_add_co_u32_e32 v106, vcc, 0xffffe000, v106
	v_cvt_pk_bf16_f32 v116, v118, v119
	v_cvt_pk_bf16_f32 v117, v120, v117
	v_cvt_pk_bf16_f32 v118, v122, v123
	v_cvt_pk_bf16_f32 v119, v124, v121
	v_addc_co_u32_e32 v107, vcc, -1, v107, vcc
	s_mov_b64 s[18:19], 0
	global_store_dwordx4 v[106:107], v[116:119], off nt
	s_nop 1
	v_lshlrev_b64 v[116:117], 10, v[206:207]
	v_lshl_add_u64 v[106:107], s[8:9], 0, v[116:117]
	s_branch .LBB0_1518
.LBB0_1504:
	s_andn2_b64 vcc, exec, s[18:19]
	s_cbranch_vccnz .LBB0_1506
	s_ashr_i32 s18, s41, 11
	s_ashr_i32 s19, s18, 31
	s_lshl_b64 s[18:19], s[18:19], 11
	v_lshl_add_u64 v[106:107], s[18:19], 0, v[192:193]
	s_movk_i32 s18, 0x7ff
	v_and_or_b32 v106, v206, s18, v106
	v_lshl_add_u64 v[106:107], v[106:107], 4, s[14:15]
	v_cvt_pk_bf16_f32 v116, v110, v111
	v_cvt_pk_bf16_f32 v117, v112, v113
	v_cvt_pk_bf16_f32 v118, v114, v115
	v_cvt_pk_bf16_f32 v119, v108, v109
	global_store_dwordx4 v[106:107], v[116:119], off nt
	s_nop 1
	v_lshlrev_b64 v[116:117], 10, v[206:207]
	v_lshl_add_u64 v[106:107], s[8:9], 0, v[116:117]
	s_branch .LBB0_1518

.LBB0_1507:
	s_andn2_b64 vcc, exec, s[18:19]
	s_cbranch_vccnz .LBB0_1509
	v_mul_f32_e32 v116, 0xbfb8aa3b, v112
	v_mul_f32_e32 v117, 0xbfb8aa3b, v113
	v_mul_f32_e32 v106, 0xbfb8aa3b, v110
	v_mul_f32_e32 v107, 0xbfb8aa3b, v111
	v_exp_f32_e32 v116, v116
	v_exp_f32_e32 v117, v117
	v_mul_f32_e32 v118, 0xbfb8aa3b, v114
	v_mul_f32_e32 v119, 0xbfb8aa3b, v115
	v_mul_f32_e32 v120, 0xbfb8aa3b, v108
	v_mul_f32_e32 v121, 0xbfb8aa3b, v109
	v_exp_f32_e32 v106, v106
	v_exp_f32_e32 v107, v107
	v_exp_f32_e32 v118, v118
	v_exp_f32_e32 v119, v119
	v_exp_f32_e32 v120, v120
	v_exp_f32_e32 v121, v121
	v_add_f32_e32 v116, 1.0, v116
	v_add_f32_e32 v117, 1.0, v117
	v_add_f32_e32 v106, 1.0, v106
	v_add_f32_e32 v107, 1.0, v107
	v_rcp_f32_e32 v116, v116
	v_rcp_f32_e32 v117, v117
	v_add_f32_e32 v118, 1.0, v118
	v_add_f32_e32 v119, 1.0, v119
	v_add_f32_e32 v120, 1.0, v120
	v_add_f32_e32 v121, 1.0, v121
	v_rcp_f32_e32 v106, v106
	v_rcp_f32_e32 v107, v107
	v_rcp_f32_e32 v118, v118
	v_rcp_f32_e32 v119, v119
	v_rcp_f32_e32 v120, v120
	v_rcp_f32_e32 v121, v121
	v_pk_mul_f32 v[122:123], v[112:113], v[116:117]
	v_lshlrev_b64 v[116:117], 10, v[206:207]
	v_pk_mul_f32 v[106:107], v[110:111], v[106:107]
	v_pk_mul_f32 v[118:119], v[114:115], v[118:119]
	v_pk_mul_f32 v[120:121], v[108:109], v[120:121]
	v_lshl_add_u64 v[116:117], s[12:13], 0, v[116:117]
	v_lshl_add_u64 v[124:125], v[186:187], 1, v[116:117]
	v_cvt_pk_bf16_f32 v116, v106, v107
	v_cvt_pk_bf16_f32 v117, v122, v123
	v_cvt_pk_bf16_f32 v118, v118, v119
	v_cvt_pk_bf16_f32 v119, v120, v121
	global_store_dwordx4 v[124:125], v[116:119], off offset:-4096 nt
	s_nop 1
	v_lshlrev_b64 v[116:117], 10, v[206:207]
	v_lshl_add_u64 v[106:107], s[8:9], 0, v[116:117]
	s_branch .LBB0_1518

.LBB0_1510:
	s_andn2_b64 vcc, exec, s[18:19]
	s_cbranch_vccnz .LBB0_1512
	v_mul_f32_e32 v116, 0xbfb8aa3b, v112
	v_mul_f32_e32 v117, 0xbfb8aa3b, v113
	v_mul_f32_e32 v106, 0xbfb8aa3b, v110
	v_mul_f32_e32 v107, 0xbfb8aa3b, v111
	v_exp_f32_e32 v116, v116
	v_exp_f32_e32 v117, v117
	v_mul_f32_e32 v118, 0xbfb8aa3b, v114
	v_mul_f32_e32 v119, 0xbfb8aa3b, v115
	v_mul_f32_e32 v120, 0xbfb8aa3b, v108
	v_mul_f32_e32 v121, 0xbfb8aa3b, v109
	v_exp_f32_e32 v106, v106
	v_exp_f32_e32 v107, v107
	v_exp_f32_e32 v118, v118
	v_exp_f32_e32 v119, v119
	v_exp_f32_e32 v120, v120
	v_exp_f32_e32 v121, v121
	v_add_f32_e32 v116, 1.0, v116
	v_add_f32_e32 v117, 1.0, v117
	v_add_f32_e32 v106, 1.0, v106
	v_add_f32_e32 v107, 1.0, v107
	v_rcp_f32_e32 v116, v116
	v_rcp_f32_e32 v117, v117
	v_add_f32_e32 v118, 1.0, v118
	v_add_f32_e32 v119, 1.0, v119
	v_add_f32_e32 v120, 1.0, v120
	v_add_f32_e32 v121, 1.0, v121
	v_rcp_f32_e32 v106, v106
	v_rcp_f32_e32 v107, v107
	v_rcp_f32_e32 v118, v118
	v_rcp_f32_e32 v119, v119
	v_rcp_f32_e32 v120, v120
	v_rcp_f32_e32 v121, v121
	v_pk_mul_f32 v[122:123], v[112:113], v[116:117]
	v_lshlrev_b64 v[116:117], 10, v[206:207]
	v_pk_mul_f32 v[106:107], v[110:111], v[106:107]
	v_pk_mul_f32 v[118:119], v[114:115], v[118:119]
	v_pk_mul_f32 v[120:121], v[108:109], v[120:121]
	v_lshl_add_u64 v[116:117], s[10:11], 0, v[116:117]
	v_lshl_add_u64 v[124:125], v[186:187], 1, v[116:117]
	v_cvt_pk_bf16_f32 v116, v106, v107
	v_cvt_pk_bf16_f32 v117, v122, v123
	v_cvt_pk_bf16_f32 v118, v118, v119
	v_cvt_pk_bf16_f32 v119, v120, v121
	global_store_dwordx4 v[124:125], v[116:119], off offset:-3072 nt
	s_nop 1
	v_lshlrev_b64 v[116:117], 10, v[206:207]
	v_lshl_add_u64 v[106:107], s[8:9], 0, v[116:117]
	s_branch .LBB0_1518

.LBB0_1513:
	s_and_b64 vcc, exec, s[18:19]
	s_cbranch_vccz .LBB0_1515
	v_mul_f32_e32 v118, 0xbfb8aa3b, v112
	v_exp_f32_e32 v118, v118
	v_mul_f32_e32 v119, 0xbfb8aa3b, v113
	v_mul_f32_e32 v120, 0xbfb8aa3b, v114
	v_exp_f32_e32 v119, v119
	v_add_f32_e32 v118, 1.0, v118
	v_rcp_f32_e32 v118, v118
	v_exp_f32_e32 v120, v120
	v_mul_f32_e32 v106, 0xbfb8aa3b, v110
	v_mul_f32_e32 v117, 0xbfb8aa3b, v111
	v_fma_f32 v118, v240, v118, v40
	v_log_f32_e32 v121, v118
	v_add_f32_e32 v118, 1.0, v119
	v_add_f32_e32 v119, 1.0, v120
	v_rcp_f32_e32 v119, v119
	v_mul_f32_e32 v120, 0xbfb8aa3b, v115
	v_exp_f32_e32 v120, v120
	v_mul_f32_e32 v123, 0xbfb8aa3b, v109
	v_fma_f32 v119, v238, v119, v34
	v_log_f32_e32 v122, v119
	v_add_f32_e32 v119, 1.0, v120
	v_mul_f32_e32 v120, 0xbfb8aa3b, v108
	v_exp_f32_e32 v116, v106
	v_exp_f32_e32 v117, v117
	v_exp_f32_e32 v120, v120
	v_exp_f32_e32 v123, v123
	v_add_f32_e32 v116, 1.0, v116
	v_add_f32_e32 v117, 1.0, v117
	v_add_f32_e32 v120, 1.0, v120
	v_add_f32_e32 v123, 1.0, v123
	v_rcp_f32_e32 v116, v116
	v_rcp_f32_e32 v117, v117
	v_rcp_f32_e32 v118, v118
	v_rcp_f32_e32 v119, v119
	v_rcp_f32_e32 v120, v120
	v_rcp_f32_e32 v123, v123
	v_fma_f32 v116, v242, v116, v38
	v_fma_f32 v117, v241, v117, v39
	v_fma_f32 v118, v239, v118, v41
	v_fma_f32 v119, v234, v119, v35
	v_fma_f32 v120, v233, v120, v36
	v_fma_f32 v123, v229, v123, v37
	v_log_f32_e32 v116, v116
	v_log_f32_e32 v120, v120
	v_log_f32_e32 v123, v123
	v_log_f32_e32 v124, v119
	v_log_f32_e32 v125, v118
	v_log_f32_e32 v126, v117
	s_and_b64 s[18:19], s[54:55], exec
	s_cselect_b32 s19, s87, s92
	s_cselect_b32 s18, s79, s89
	v_lshlrev_b64 v[106:107], 10, v[206:207]
	v_lshl_add_u64 v[106:107], s[18:19], 0, v[106:107]
	v_lshlrev_b32_e32 v176, 1, v191
	v_cvt_pk_f16_f32 v119, v120, v123
	v_cvt_pk_f16_f32 v118, v122, v124
	v_cvt_pk_f16_f32 v117, v121, v125
	v_cvt_pk_f16_f32 v116, v116, v126
	v_lshl_add_u64 v[106:107], v[106:107], 0, v[176:177]
	global_store_dwordx4 v[106:107], v[116:119], off
	s_nop 1
	v_lshlrev_b64 v[116:117], 10, v[206:207]
	v_lshl_add_u64 v[106:107], s[8:9], 0, v[116:117]
	s_branch .LBB0_1518

.LBB0_1518:
	v_mov_b32_e32 v209, v208
	v_pk_fma_f32 v[102:103], v[102:103], v[208:209], v[30:31]
	v_pk_fma_f32 v[104:105], v[104:105], v[208:209], v[32:33]
	v_pk_fma_f32 v[98:99], v[98:99], v[208:209], v[26:27]
	v_pk_fma_f32 v[100:101], v[100:101], v[208:209], v[28:29]
	s_and_b64 vcc, exec, s[4:5]
	s_mov_b64 s[18:19], -1
	s_cbranch_vccnz .LBB0_1536
	s_and_b64 vcc, exec, s[2:3]
	s_cbranch_vccnz .LBB0_1533
	s_cmp_lt_i32 s39, 4
	s_cbranch_scc1 .LBB0_1530
	s_cmp_lg_u32 s39, 4
	s_cbranch_scc0 .LBB0_1527
	s_andn2_b64 vcc, exec, s[56:57]
	s_cbranch_vccnz .LBB0_1524
	v_mul_f32_e32 v108, 0xbfb8aa3b, v102
	v_mul_f32_e32 v109, 0xbfb8aa3b, v103
	v_exp_f32_e32 v108, v108
	v_exp_f32_e32 v109, v109
	v_mul_f32_e32 v111, 0xbfb8aa3b, v105
	v_exp_f32_e32 v111, v111
	v_add_f32_e32 v108, 1.0, v108
	v_add_f32_e32 v109, 1.0, v109
	v_rcp_f32_e32 v108, v108
	v_rcp_f32_e32 v109, v109
	v_mul_f32_e32 v112, 0xbfb8aa3b, v101
	v_mul_f32_e32 v110, 0xbfb8aa3b, v104
	v_max_f32_e32 v114, 0x219392ef, v108
	v_max_f32_e32 v115, 0x219392ef, v109
	v_add_f32_e32 v108, 1.0, v111
	v_mul_f32_e32 v109, 0xbfb8aa3b, v98
	v_mul_f32_e32 v111, 0xbfb8aa3b, v99
	v_rcp_f32_e32 v108, v108
	v_exp_f32_e32 v109, v109
	v_exp_f32_e32 v111, v111
	v_exp_f32_e32 v112, v112
	v_max_f32_e32 v118, 0x219392ef, v108
	v_add_f32_e32 v108, 1.0, v109
	v_add_f32_e32 v109, 1.0, v111
	v_mul_f32_e32 v111, 0xbfb8aa3b, v100
	v_exp_f32_e32 v110, v110
	v_exp_f32_e32 v111, v111
	v_rcp_f32_e32 v108, v108
	v_rcp_f32_e32 v109, v109
	v_add_f32_e32 v112, 1.0, v112
	v_add_f32_e32 v110, 1.0, v110
	v_add_f32_e32 v111, 1.0, v111
	v_rcp_f32_e32 v112, v112
	v_rcp_f32_e32 v110, v110
	v_rcp_f32_e32 v111, v111
	v_max_f32_e32 v119, 0x219392ef, v108
	v_max_f32_e32 v120, 0x219392ef, v109
	v_lshlrev_b64 v[108:109], 12, v[206:207]
	v_lshl_add_u64 v[108:109], s[16:17], 0, v[108:109]
	v_max_f32_e32 v121, 0x219392ef, v112
	v_lshl_add_u64 v[112:113], v[186:187], 1, v[108:109]
	v_max_f32_e32 v110, 0x219392ef, v110
	v_max_f32_e32 v111, 0x219392ef, v111
	v_add_co_u32_e32 v112, vcc, 0xfffff000, v112
	v_cvt_pk_bf16_f32 v108, v114, v115
	v_cvt_pk_bf16_f32 v109, v110, v118
	v_cvt_pk_bf16_f32 v110, v119, v120
	v_cvt_pk_bf16_f32 v111, v111, v121
	v_addc_co_u32_e32 v113, vcc, -1, v113, vcc
	s_mov_b64 s[18:19], 0
	global_store_dwordx4 v[112:113], v[108:111], off offset:-3840 nt
	s_nop 1
	s_branch .LBB0_1538
.LBB0_1524:
	s_andn2_b64 vcc, exec, s[18:19]
	s_cbranch_vccnz .LBB0_1526
	s_ashr_i32 s18, s41, 11
	s_ashr_i32 s19, s18, 31
	s_lshl_b64 s[18:19], s[18:19], 11
	v_lshl_add_u64 v[108:109], s[18:19], 0, v[154:155]
	s_movk_i32 s18, 0x7ff
	v_and_or_b32 v108, v206, s18, v108
	v_lshl_add_u64 v[112:113], v[108:109], 4, s[14:15]
	v_cvt_pk_bf16_f32 v108, v102, v103
	v_cvt_pk_bf16_f32 v109, v104, v105
	v_cvt_pk_bf16_f32 v110, v98, v99
	v_cvt_pk_bf16_f32 v111, v100, v101
	global_store_dwordx4 v[112:113], v[108:111], off nt
	s_nop 1
	s_branch .LBB0_1538

.LBB0_1527:
	s_andn2_b64 vcc, exec, s[18:19]
	s_cbranch_vccnz .LBB0_1529
	v_mul_f32_e32 v108, 0xbfb8aa3b, v102
	v_mul_f32_e32 v109, 0xbfb8aa3b, v103
	v_mul_f32_e32 v110, 0xbfb8aa3b, v104
	v_mul_f32_e32 v111, 0xbfb8aa3b, v105
	v_mul_f32_e32 v112, 0xbfb8aa3b, v98
	v_mul_f32_e32 v113, 0xbfb8aa3b, v99
	v_mul_f32_e32 v114, 0xbfb8aa3b, v100
	v_mul_f32_e32 v115, 0xbfb8aa3b, v101
	v_exp_f32_e32 v108, v108
	v_exp_f32_e32 v109, v109
	v_exp_f32_e32 v110, v110
	v_exp_f32_e32 v111, v111
	v_exp_f32_e32 v112, v112
	v_exp_f32_e32 v113, v113
	v_exp_f32_e32 v114, v114
	v_exp_f32_e32 v115, v115
	v_add_f32_e32 v108, 1.0, v108
	v_add_f32_e32 v109, 1.0, v109
	v_add_f32_e32 v110, 1.0, v110
	v_add_f32_e32 v111, 1.0, v111
	v_add_f32_e32 v112, 1.0, v112
	v_add_f32_e32 v113, 1.0, v113
	v_add_f32_e32 v114, 1.0, v114
	v_add_f32_e32 v115, 1.0, v115
	v_rcp_f32_e32 v108, v108
	v_rcp_f32_e32 v109, v109
	v_rcp_f32_e32 v110, v110
	v_rcp_f32_e32 v111, v111
	v_rcp_f32_e32 v112, v112
	v_rcp_f32_e32 v113, v113
	v_rcp_f32_e32 v114, v114
	v_rcp_f32_e32 v115, v115
	v_pk_mul_f32 v[108:109], v[102:103], v[108:109]
	v_pk_mul_f32 v[110:111], v[104:105], v[110:111]
	v_pk_mul_f32 v[112:113], v[98:99], v[112:113]
	v_pk_mul_f32 v[114:115], v[100:101], v[114:115]
	v_lshl_add_u64 v[118:119], s[12:13], 0, v[116:117]
	v_lshl_add_u64 v[118:119], v[186:187], 1, v[118:119]
	v_cvt_pk_bf16_f32 v108, v108, v109
	v_cvt_pk_bf16_f32 v109, v110, v111
	v_cvt_pk_bf16_f32 v110, v112, v113
	v_cvt_pk_bf16_f32 v111, v114, v115
	global_store_dwordx4 v[118:119], v[108:111], off offset:-3840 nt
	s_nop 1
	s_branch .LBB0_1538

.LBB0_1530:
	s_andn2_b64 vcc, exec, s[18:19]
	s_cbranch_vccnz .LBB0_1532
	v_mul_f32_e32 v108, 0xbfb8aa3b, v102
	v_mul_f32_e32 v109, 0xbfb8aa3b, v103
	v_mul_f32_e32 v110, 0xbfb8aa3b, v104
	v_mul_f32_e32 v111, 0xbfb8aa3b, v105
	v_mul_f32_e32 v112, 0xbfb8aa3b, v98
	v_mul_f32_e32 v113, 0xbfb8aa3b, v99
	v_mul_f32_e32 v114, 0xbfb8aa3b, v100
	v_mul_f32_e32 v115, 0xbfb8aa3b, v101
	v_exp_f32_e32 v108, v108
	v_exp_f32_e32 v109, v109
	v_exp_f32_e32 v110, v110
	v_exp_f32_e32 v111, v111
	v_exp_f32_e32 v112, v112
	v_exp_f32_e32 v113, v113
	v_exp_f32_e32 v114, v114
	v_exp_f32_e32 v115, v115
	v_add_f32_e32 v108, 1.0, v108
	v_add_f32_e32 v109, 1.0, v109
	v_add_f32_e32 v110, 1.0, v110
	v_add_f32_e32 v111, 1.0, v111
	v_add_f32_e32 v112, 1.0, v112
	v_add_f32_e32 v113, 1.0, v113
	v_add_f32_e32 v114, 1.0, v114
	v_add_f32_e32 v115, 1.0, v115
	v_rcp_f32_e32 v108, v108
	v_rcp_f32_e32 v109, v109
	v_rcp_f32_e32 v110, v110
	v_rcp_f32_e32 v111, v111
	v_rcp_f32_e32 v112, v112
	v_rcp_f32_e32 v113, v113
	v_rcp_f32_e32 v114, v114
	v_rcp_f32_e32 v115, v115
	v_pk_mul_f32 v[108:109], v[102:103], v[108:109]
	v_pk_mul_f32 v[110:111], v[104:105], v[110:111]
	v_pk_mul_f32 v[112:113], v[98:99], v[112:113]
	v_pk_mul_f32 v[114:115], v[100:101], v[114:115]
	v_lshl_add_u64 v[118:119], s[10:11], 0, v[116:117]
	v_lshl_add_u64 v[118:119], v[186:187], 1, v[118:119]
	v_cvt_pk_bf16_f32 v108, v108, v109
	v_cvt_pk_bf16_f32 v109, v110, v111
	v_cvt_pk_bf16_f32 v110, v112, v113
	v_cvt_pk_bf16_f32 v111, v114, v115
	global_store_dwordx4 v[118:119], v[108:111], off offset:-2816 nt
	s_nop 1
	s_branch .LBB0_1538

.LBB0_1533:
	s_and_b64 vcc, exec, s[18:19]
	s_cbranch_vccz .LBB0_1535
	v_mul_f32_e32 v110, 0xbfb8aa3b, v104
	v_exp_f32_e32 v110, v110
	v_mul_f32_e32 v111, 0xbfb8aa3b, v105
	v_mul_f32_e32 v112, 0xbfb8aa3b, v98
	v_exp_f32_e32 v111, v111
	v_add_f32_e32 v110, 1.0, v110
	v_rcp_f32_e32 v110, v110
	v_exp_f32_e32 v112, v112
	v_mul_f32_e32 v115, 0xbfb8aa3b, v101
	v_mul_f32_e32 v108, 0xbfb8aa3b, v102
	v_fma_f32 v110, v235, v110, v12
	v_log_f32_e32 v113, v110
	v_add_f32_e32 v110, 1.0, v111
	v_add_f32_e32 v111, 1.0, v112
	v_rcp_f32_e32 v111, v111
	v_mul_f32_e32 v112, 0xbfb8aa3b, v99
	v_exp_f32_e32 v112, v112
	v_mul_f32_e32 v109, 0xbfb8aa3b, v103
	v_fma_f32 v111, v223, v111, v14
	v_log_f32_e32 v114, v111
	v_add_f32_e32 v111, 1.0, v112
	v_mul_f32_e32 v112, 0xbfb8aa3b, v100
	v_exp_f32_e32 v112, v112
	v_exp_f32_e32 v115, v115
	v_exp_f32_e32 v108, v108
	v_exp_f32_e32 v109, v109
	v_add_f32_e32 v112, 1.0, v112
	v_add_f32_e32 v115, 1.0, v115
	v_add_f32_e32 v108, 1.0, v108
	v_add_f32_e32 v109, 1.0, v109
	v_rcp_f32_e32 v110, v110
	v_rcp_f32_e32 v112, v112
	v_rcp_f32_e32 v115, v115
	v_rcp_f32_e32 v108, v108
	v_rcp_f32_e32 v109, v109
	v_rcp_f32_e32 v111, v111
	v_fma_f32 v110, v222, v110, v13
	v_fma_f32 v112, v221, v112, v16
	v_fma_f32 v115, v161, v115, v17
	v_fma_f32 v108, v237, v108, v10
	v_fma_f32 v109, v236, v109, v11
	v_fma_f32 v111, v220, v111, v15
	v_log_f32_e32 v112, v112
	v_log_f32_e32 v115, v115
	v_log_f32_e32 v119, v110
	v_log_f32_e32 v108, v108
	v_log_f32_e32 v118, v111
	v_log_f32_e32 v120, v109
	s_and_b64 s[18:19], s[54:55], exec
	s_cselect_b32 s19, s87, s92
	s_cselect_b32 s18, s79, s89
	v_cvt_pk_f16_f32 v111, v112, v115
	v_cvt_pk_f16_f32 v109, v113, v119
	v_lshl_add_u64 v[112:113], s[18:19], 0, v[116:117]
	v_lshlrev_b32_e32 v176, 1, v160
	v_cvt_pk_f16_f32 v110, v114, v118
	v_cvt_pk_f16_f32 v108, v108, v120
	v_lshl_add_u64 v[112:113], v[112:113], 0, v[176:177]
	global_store_dwordx4 v[112:113], v[108:111], off
	s_nop 1
	s_branch .LBB0_1538

.LBB0_1538:
	v_add_u32_e32 v98, 0x80, v204
	v_ashrrev_i32_e32 v99, 31, v98
	v_pk_fma_f32 v[94:95], v[94:95], v[202:203], v[54:55] op_sel_hi:[1,0,1]
	v_pk_fma_f32 v[96:97], v[96:97], v[202:203], v[56:57] op_sel_hi:[1,0,1]
	v_pk_fma_f32 v[100:101], v[90:91], v[202:203], v[50:51] op_sel_hi:[1,0,1]
	v_pk_fma_f32 v[92:93], v[92:93], v[202:203], v[52:53] op_sel_hi:[1,0,1]
	s_and_b64 vcc, exec, s[4:5]
	s_mov_b64 s[18:19], -1
	s_cbranch_vccnz .LBB0_1556
	s_and_b64 vcc, exec, s[2:3]
	s_cbranch_vccnz .LBB0_1553
	s_cmp_lt_i32 s39, 4
	s_cbranch_scc1 .LBB0_1550
	s_cmp_lg_u32 s39, 4
	s_cbranch_scc0 .LBB0_1547
	s_andn2_b64 vcc, exec, s[56:57]
	s_cbranch_vccnz .LBB0_1544
	v_mul_f32_e32 v90, 0xbfb8aa3b, v94
	v_mul_f32_e32 v91, 0xbfb8aa3b, v95
	v_mul_f32_e32 v102, 0xbfb8aa3b, v96
	v_exp_f32_e32 v90, v90
	v_exp_f32_e32 v91, v91
	v_exp_f32_e32 v102, v102
	v_mul_f32_e32 v103, 0xbfb8aa3b, v97
	v_add_f32_e32 v90, 1.0, v90
	v_add_f32_e32 v91, 1.0, v91
	v_add_f32_e32 v102, 1.0, v102
	v_rcp_f32_e32 v90, v90
	v_rcp_f32_e32 v91, v91
	v_rcp_f32_e32 v102, v102
	v_exp_f32_e32 v103, v103
	v_max_f32_e32 v104, 0x219392ef, v90
	v_max_f32_e32 v105, 0x219392ef, v91
	v_max_f32_e32 v106, 0x219392ef, v102
	v_add_f32_e32 v90, 1.0, v103
	v_mul_f32_e32 v91, 0xbfb8aa3b, v100
	v_mul_f32_e32 v102, 0xbfb8aa3b, v101
	v_rcp_f32_e32 v90, v90
	v_exp_f32_e32 v91, v91
	v_exp_f32_e32 v102, v102
	v_mul_f32_e32 v107, 0xbfb8aa3b, v93
	v_max_f32_e32 v103, 0x219392ef, v90
	v_add_f32_e32 v90, 1.0, v91
	v_add_f32_e32 v91, 1.0, v102
	v_mul_f32_e32 v102, 0xbfb8aa3b, v92
	v_exp_f32_e32 v102, v102
	v_exp_f32_e32 v107, v107
	v_rcp_f32_e32 v90, v90
	v_rcp_f32_e32 v91, v91
	v_add_f32_e32 v102, 1.0, v102
	v_add_f32_e32 v107, 1.0, v107
	v_rcp_f32_e32 v102, v102
	v_rcp_f32_e32 v107, v107
	v_max_f32_e32 v108, 0x219392ef, v90
	v_max_f32_e32 v109, 0x219392ef, v91
	v_lshlrev_b64 v[90:91], 12, v[98:99]
	v_lshl_add_u64 v[90:91], s[16:17], 0, v[90:91]
	v_lshl_add_u64 v[90:91], v[186:187], 1, v[90:91]
	v_max_f32_e32 v110, 0x219392ef, v102
	v_max_f32_e32 v107, 0x219392ef, v107
	v_add_co_u32_e32 v90, vcc, 0xffffe000, v90
	v_cvt_pk_bf16_f32 v102, v104, v105
	v_cvt_pk_bf16_f32 v103, v106, v103
	v_cvt_pk_bf16_f32 v104, v108, v109
	v_cvt_pk_bf16_f32 v105, v110, v107
	v_addc_co_u32_e32 v91, vcc, -1, v91, vcc
	s_mov_b64 s[18:19], 0
	global_store_dwordx4 v[90:91], v[102:105], off nt
	s_nop 1
	v_lshlrev_b64 v[102:103], 10, v[98:99]
	v_lshl_add_u64 v[90:91], s[8:9], 0, v[102:103]
	s_branch .LBB0_1558
.LBB0_1544:
	s_andn2_b64 vcc, exec, s[18:19]
	s_cbranch_vccnz .LBB0_1546
	v_ashrrev_i32_e32 v90, 11, v98
	v_ashrrev_i32_e32 v91, 31, v90
	v_lshlrev_b64 v[90:91], 11, v[90:91]
	v_lshl_add_u64 v[90:91], v[90:91], 0, v[192:193]
	s_movk_i32 s18, 0x7cf
	v_and_or_b32 v90, v98, s18, v90
	v_lshl_add_u64 v[90:91], v[90:91], 4, s[14:15]
	v_cvt_pk_bf16_f32 v102, v94, v95
	v_cvt_pk_bf16_f32 v103, v96, v97
	v_cvt_pk_bf16_f32 v104, v100, v101
	v_cvt_pk_bf16_f32 v105, v92, v93
	global_store_dwordx4 v[90:91], v[102:105], off nt
	s_nop 1
	v_lshlrev_b64 v[102:103], 10, v[98:99]
	v_lshl_add_u64 v[90:91], s[8:9], 0, v[102:103]
	s_branch .LBB0_1558

.LBB0_1547:
	s_andn2_b64 vcc, exec, s[18:19]
	s_cbranch_vccnz .LBB0_1549
	v_mul_f32_e32 v102, 0xbfb8aa3b, v96
	v_mul_f32_e32 v103, 0xbfb8aa3b, v97
	v_mul_f32_e32 v90, 0xbfb8aa3b, v94
	v_mul_f32_e32 v91, 0xbfb8aa3b, v95
	v_exp_f32_e32 v102, v102
	v_exp_f32_e32 v103, v103
	v_mul_f32_e32 v104, 0xbfb8aa3b, v100
	v_mul_f32_e32 v105, 0xbfb8aa3b, v101
	v_mul_f32_e32 v106, 0xbfb8aa3b, v92
	v_mul_f32_e32 v107, 0xbfb8aa3b, v93
	v_exp_f32_e32 v90, v90
	v_exp_f32_e32 v91, v91
	v_exp_f32_e32 v104, v104
	v_exp_f32_e32 v105, v105
	v_exp_f32_e32 v106, v106
	v_exp_f32_e32 v107, v107
	v_add_f32_e32 v102, 1.0, v102
	v_add_f32_e32 v103, 1.0, v103
	v_add_f32_e32 v90, 1.0, v90
	v_add_f32_e32 v91, 1.0, v91
	v_rcp_f32_e32 v102, v102
	v_rcp_f32_e32 v103, v103
	v_add_f32_e32 v104, 1.0, v104
	v_add_f32_e32 v105, 1.0, v105
	v_add_f32_e32 v106, 1.0, v106
	v_add_f32_e32 v107, 1.0, v107
	v_rcp_f32_e32 v90, v90
	v_rcp_f32_e32 v91, v91
	v_rcp_f32_e32 v104, v104
	v_rcp_f32_e32 v105, v105
	v_rcp_f32_e32 v106, v106
	v_rcp_f32_e32 v107, v107
	v_pk_mul_f32 v[108:109], v[96:97], v[102:103]
	v_lshlrev_b64 v[102:103], 10, v[98:99]
	v_pk_mul_f32 v[90:91], v[94:95], v[90:91]
	v_pk_mul_f32 v[104:105], v[100:101], v[104:105]
	v_pk_mul_f32 v[106:107], v[92:93], v[106:107]
	v_lshl_add_u64 v[102:103], s[12:13], 0, v[102:103]
	v_lshl_add_u64 v[110:111], v[186:187], 1, v[102:103]
	v_cvt_pk_bf16_f32 v102, v90, v91
	v_cvt_pk_bf16_f32 v103, v108, v109
	v_cvt_pk_bf16_f32 v104, v104, v105
	v_cvt_pk_bf16_f32 v105, v106, v107
	global_store_dwordx4 v[110:111], v[102:105], off offset:-4096 nt
	s_nop 1
	v_lshlrev_b64 v[102:103], 10, v[98:99]
	v_lshl_add_u64 v[90:91], s[8:9], 0, v[102:103]
	s_branch .LBB0_1558

.LBB0_1550:
	s_andn2_b64 vcc, exec, s[18:19]
	s_cbranch_vccnz .LBB0_1552
	v_mul_f32_e32 v102, 0xbfb8aa3b, v96
	v_mul_f32_e32 v103, 0xbfb8aa3b, v97
	v_mul_f32_e32 v90, 0xbfb8aa3b, v94
	v_mul_f32_e32 v91, 0xbfb8aa3b, v95
	v_exp_f32_e32 v102, v102
	v_exp_f32_e32 v103, v103
	v_mul_f32_e32 v104, 0xbfb8aa3b, v100
	v_mul_f32_e32 v105, 0xbfb8aa3b, v101
	v_mul_f32_e32 v106, 0xbfb8aa3b, v92
	v_mul_f32_e32 v107, 0xbfb8aa3b, v93
	v_exp_f32_e32 v90, v90
	v_exp_f32_e32 v91, v91
	v_exp_f32_e32 v104, v104
	v_exp_f32_e32 v105, v105
	v_exp_f32_e32 v106, v106
	v_exp_f32_e32 v107, v107
	v_add_f32_e32 v102, 1.0, v102
	v_add_f32_e32 v103, 1.0, v103
	v_add_f32_e32 v90, 1.0, v90
	v_add_f32_e32 v91, 1.0, v91
	v_rcp_f32_e32 v102, v102
	v_rcp_f32_e32 v103, v103
	v_add_f32_e32 v104, 1.0, v104
	v_add_f32_e32 v105, 1.0, v105
	v_add_f32_e32 v106, 1.0, v106
	v_add_f32_e32 v107, 1.0, v107
	v_rcp_f32_e32 v90, v90
	v_rcp_f32_e32 v91, v91
	v_rcp_f32_e32 v104, v104
	v_rcp_f32_e32 v105, v105
	v_rcp_f32_e32 v106, v106
	v_rcp_f32_e32 v107, v107
	v_pk_mul_f32 v[108:109], v[96:97], v[102:103]
	v_lshlrev_b64 v[102:103], 10, v[98:99]
	v_pk_mul_f32 v[90:91], v[94:95], v[90:91]
	v_pk_mul_f32 v[104:105], v[100:101], v[104:105]
	v_pk_mul_f32 v[106:107], v[92:93], v[106:107]
	v_lshl_add_u64 v[102:103], s[10:11], 0, v[102:103]
	v_lshl_add_u64 v[110:111], v[186:187], 1, v[102:103]
	v_cvt_pk_bf16_f32 v102, v90, v91
	v_cvt_pk_bf16_f32 v103, v108, v109
	v_cvt_pk_bf16_f32 v104, v104, v105
	v_cvt_pk_bf16_f32 v105, v106, v107
	global_store_dwordx4 v[110:111], v[102:105], off offset:-3072 nt
	s_nop 1
	v_lshlrev_b64 v[102:103], 10, v[98:99]
	v_lshl_add_u64 v[90:91], s[8:9], 0, v[102:103]
	s_branch .LBB0_1558

.LBB0_1553:
	s_and_b64 vcc, exec, s[18:19]
	s_cbranch_vccz .LBB0_1555
	v_mul_f32_e32 v104, 0xbfb8aa3b, v96
	v_exp_f32_e32 v104, v104
	v_mul_f32_e32 v105, 0xbfb8aa3b, v97
	v_mul_f32_e32 v106, 0xbfb8aa3b, v100
	v_exp_f32_e32 v105, v105
	v_add_f32_e32 v104, 1.0, v104
	v_rcp_f32_e32 v104, v104
	v_exp_f32_e32 v106, v106
	v_mul_f32_e32 v90, 0xbfb8aa3b, v94
	v_mul_f32_e32 v103, 0xbfb8aa3b, v95
	v_fma_f32 v104, v240, v104, v40
	v_log_f32_e32 v107, v104
	v_add_f32_e32 v104, 1.0, v105
	v_add_f32_e32 v105, 1.0, v106
	v_rcp_f32_e32 v105, v105
	v_mul_f32_e32 v106, 0xbfb8aa3b, v101
	v_exp_f32_e32 v106, v106
	v_mul_f32_e32 v109, 0xbfb8aa3b, v93
	v_fma_f32 v105, v238, v105, v34
	v_log_f32_e32 v108, v105
	v_add_f32_e32 v105, 1.0, v106
	v_mul_f32_e32 v106, 0xbfb8aa3b, v92
	v_exp_f32_e32 v102, v90
	v_exp_f32_e32 v103, v103
	v_exp_f32_e32 v106, v106
	v_exp_f32_e32 v109, v109
	v_add_f32_e32 v102, 1.0, v102
	v_add_f32_e32 v103, 1.0, v103
	v_add_f32_e32 v106, 1.0, v106
	v_add_f32_e32 v109, 1.0, v109
	v_rcp_f32_e32 v102, v102
	v_rcp_f32_e32 v103, v103
	v_rcp_f32_e32 v104, v104
	v_rcp_f32_e32 v105, v105
	v_rcp_f32_e32 v106, v106
	v_rcp_f32_e32 v109, v109
	v_fma_f32 v102, v242, v102, v38
	v_fma_f32 v103, v241, v103, v39
	v_fma_f32 v104, v239, v104, v41
	v_fma_f32 v105, v234, v105, v35
	v_fma_f32 v106, v233, v106, v36
	v_fma_f32 v109, v229, v109, v37
	v_log_f32_e32 v102, v102
	v_log_f32_e32 v106, v106
	v_log_f32_e32 v109, v109
	v_log_f32_e32 v110, v105
	v_log_f32_e32 v111, v104
	v_log_f32_e32 v112, v103
	s_and_b64 s[18:19], s[54:55], exec
	s_cselect_b32 s19, s87, s92
	s_cselect_b32 s18, s79, s89
	v_lshlrev_b64 v[90:91], 10, v[98:99]
	v_lshl_add_u64 v[90:91], s[18:19], 0, v[90:91]
	v_lshlrev_b32_e32 v176, 1, v191
	v_cvt_pk_f16_f32 v105, v106, v109
	v_cvt_pk_f16_f32 v104, v108, v110
	v_cvt_pk_f16_f32 v103, v107, v111
	v_cvt_pk_f16_f32 v102, v102, v112
	v_lshl_add_u64 v[90:91], v[90:91], 0, v[176:177]
	global_store_dwordx4 v[90:91], v[102:105], off
	s_nop 1
	v_lshlrev_b64 v[102:103], 10, v[98:99]
	v_lshl_add_u64 v[90:91], s[8:9], 0, v[102:103]
	s_branch .LBB0_1558

.LBB0_1558:
	v_mov_b32_e32 v203, v202
	v_pk_fma_f32 v[86:87], v[86:87], v[202:203], v[30:31]
	v_pk_fma_f32 v[88:89], v[88:89], v[202:203], v[32:33]
	v_pk_fma_f32 v[82:83], v[82:83], v[202:203], v[26:27]
	v_pk_fma_f32 v[84:85], v[84:85], v[202:203], v[28:29]
	s_and_b64 vcc, exec, s[4:5]
	s_mov_b64 s[18:19], -1
	s_cbranch_vccnz .LBB0_1576
	s_and_b64 vcc, exec, s[2:3]
	s_cbranch_vccnz .LBB0_1573
	s_cmp_lt_i32 s39, 4
	s_cbranch_scc1 .LBB0_1570
	s_cmp_lg_u32 s39, 4
	s_cbranch_scc0 .LBB0_1567
	s_andn2_b64 vcc, exec, s[56:57]
	s_cbranch_vccnz .LBB0_1564
	v_mul_f32_e32 v92, 0xbfb8aa3b, v86
	v_mul_f32_e32 v93, 0xbfb8aa3b, v87
	v_exp_f32_e32 v92, v92
	v_exp_f32_e32 v93, v93
	v_mul_f32_e32 v95, 0xbfb8aa3b, v89
	v_exp_f32_e32 v95, v95
	v_add_f32_e32 v92, 1.0, v92
	v_add_f32_e32 v93, 1.0, v93
	v_rcp_f32_e32 v92, v92
	v_rcp_f32_e32 v93, v93
	v_mul_f32_e32 v96, 0xbfb8aa3b, v85
	v_mul_f32_e32 v94, 0xbfb8aa3b, v88
	v_max_f32_e32 v100, 0x219392ef, v92
	v_max_f32_e32 v101, 0x219392ef, v93
	v_add_f32_e32 v92, 1.0, v95
	v_mul_f32_e32 v93, 0xbfb8aa3b, v82
	v_mul_f32_e32 v95, 0xbfb8aa3b, v83
	v_rcp_f32_e32 v92, v92
	v_exp_f32_e32 v93, v93
	v_exp_f32_e32 v95, v95
	v_exp_f32_e32 v96, v96
	v_max_f32_e32 v104, 0x219392ef, v92
	v_add_f32_e32 v92, 1.0, v93
	v_add_f32_e32 v93, 1.0, v95
	v_mul_f32_e32 v95, 0xbfb8aa3b, v84
	v_exp_f32_e32 v94, v94
	v_exp_f32_e32 v95, v95
	v_rcp_f32_e32 v92, v92
	v_rcp_f32_e32 v93, v93
	v_add_f32_e32 v96, 1.0, v96
	v_add_f32_e32 v94, 1.0, v94
	v_add_f32_e32 v95, 1.0, v95
	v_rcp_f32_e32 v96, v96
	v_rcp_f32_e32 v94, v94
	v_rcp_f32_e32 v95, v95
	v_max_f32_e32 v105, 0x219392ef, v92
	v_max_f32_e32 v106, 0x219392ef, v93
	v_lshlrev_b64 v[92:93], 12, v[98:99]
	v_lshl_add_u64 v[92:93], s[16:17], 0, v[92:93]
	v_max_f32_e32 v107, 0x219392ef, v96
	v_lshl_add_u64 v[96:97], v[186:187], 1, v[92:93]
	v_max_f32_e32 v94, 0x219392ef, v94
	v_max_f32_e32 v95, 0x219392ef, v95
	v_add_co_u32_e32 v96, vcc, 0xfffff000, v96
	v_cvt_pk_bf16_f32 v92, v100, v101
	v_cvt_pk_bf16_f32 v93, v94, v104
	v_cvt_pk_bf16_f32 v94, v105, v106
	v_cvt_pk_bf16_f32 v95, v95, v107
	v_addc_co_u32_e32 v97, vcc, -1, v97, vcc
	s_mov_b64 s[18:19], 0
	global_store_dwordx4 v[96:97], v[92:95], off offset:-3840 nt
	s_nop 1
	s_branch .LBB0_1578
.LBB0_1564:
	s_andn2_b64 vcc, exec, s[18:19]
	s_cbranch_vccnz .LBB0_1566
	v_ashrrev_i32_e32 v92, 11, v98
	v_ashrrev_i32_e32 v93, 31, v92
	v_lshlrev_b64 v[92:93], 11, v[92:93]
	v_lshl_add_u64 v[92:93], v[92:93], 0, v[154:155]
	s_movk_i32 s18, 0x7cf
	v_and_or_b32 v92, v98, s18, v92
	v_lshl_add_u64 v[96:97], v[92:93], 4, s[14:15]
	v_cvt_pk_bf16_f32 v92, v86, v87
	v_cvt_pk_bf16_f32 v93, v88, v89
	v_cvt_pk_bf16_f32 v94, v82, v83
	v_cvt_pk_bf16_f32 v95, v84, v85
	global_store_dwordx4 v[96:97], v[92:95], off nt
	s_nop 1
	s_branch .LBB0_1578

.LBB0_1567:
	s_andn2_b64 vcc, exec, s[18:19]
	s_cbranch_vccnz .LBB0_1569
	v_mul_f32_e32 v99, 0xbfb8aa3b, v84
	v_mul_f32_e32 v92, 0xbfb8aa3b, v86
	v_mul_f32_e32 v93, 0xbfb8aa3b, v87
	v_mul_f32_e32 v94, 0xbfb8aa3b, v88
	v_mul_f32_e32 v95, 0xbfb8aa3b, v89
	v_mul_f32_e32 v96, 0xbfb8aa3b, v82
	v_mul_f32_e32 v97, 0xbfb8aa3b, v83
	v_exp_f32_e32 v99, v99
	v_mul_f32_e32 v100, 0xbfb8aa3b, v85
	v_exp_f32_e32 v92, v92
	v_exp_f32_e32 v93, v93
	v_exp_f32_e32 v94, v94
	v_exp_f32_e32 v95, v95
	v_exp_f32_e32 v96, v96
	v_exp_f32_e32 v97, v97
	v_exp_f32_e32 v101, v100
	v_add_f32_e32 v99, 1.0, v99
	v_add_f32_e32 v92, 1.0, v92
	v_add_f32_e32 v93, 1.0, v93
	v_add_f32_e32 v94, 1.0, v94
	v_add_f32_e32 v95, 1.0, v95
	v_add_f32_e32 v96, 1.0, v96
	v_add_f32_e32 v97, 1.0, v97
	v_rcp_f32_e32 v100, v99
	v_add_f32_e32 v99, 1.0, v101
	v_rcp_f32_e32 v92, v92
	v_rcp_f32_e32 v93, v93
	v_rcp_f32_e32 v94, v94
	v_rcp_f32_e32 v95, v95
	v_rcp_f32_e32 v96, v96
	v_rcp_f32_e32 v97, v97
	v_rcp_f32_e32 v101, v99
	v_pk_mul_f32 v[92:93], v[86:87], v[92:93]
	v_pk_mul_f32 v[94:95], v[88:89], v[94:95]
	v_pk_mul_f32 v[96:97], v[82:83], v[96:97]
	v_pk_mul_f32 v[100:101], v[84:85], v[100:101]
	v_lshl_add_u64 v[104:105], s[12:13], 0, v[102:103]
	v_lshl_add_u64 v[104:105], v[186:187], 1, v[104:105]
	v_cvt_pk_bf16_f32 v92, v92, v93
	v_cvt_pk_bf16_f32 v93, v94, v95
	v_cvt_pk_bf16_f32 v94, v96, v97
	v_cvt_pk_bf16_f32 v95, v100, v101
	global_store_dwordx4 v[104:105], v[92:95], off offset:-3840 nt
	s_nop 1
	s_branch .LBB0_1578

.LBB0_1570:
	s_andn2_b64 vcc, exec, s[18:19]
	s_cbranch_vccnz .LBB0_1572
	v_mul_f32_e32 v99, 0xbfb8aa3b, v84
	v_mul_f32_e32 v92, 0xbfb8aa3b, v86
	v_mul_f32_e32 v93, 0xbfb8aa3b, v87
	v_mul_f32_e32 v94, 0xbfb8aa3b, v88
	v_mul_f32_e32 v95, 0xbfb8aa3b, v89
	v_mul_f32_e32 v96, 0xbfb8aa3b, v82
	v_mul_f32_e32 v97, 0xbfb8aa3b, v83
	v_exp_f32_e32 v99, v99
	v_mul_f32_e32 v100, 0xbfb8aa3b, v85
	v_exp_f32_e32 v92, v92
	v_exp_f32_e32 v93, v93
	v_exp_f32_e32 v94, v94
	v_exp_f32_e32 v95, v95
	v_exp_f32_e32 v96, v96
	v_exp_f32_e32 v97, v97
	v_exp_f32_e32 v101, v100
	v_add_f32_e32 v99, 1.0, v99
	v_add_f32_e32 v92, 1.0, v92
	v_add_f32_e32 v93, 1.0, v93
	v_add_f32_e32 v94, 1.0, v94
	v_add_f32_e32 v95, 1.0, v95
	v_add_f32_e32 v96, 1.0, v96
	v_add_f32_e32 v97, 1.0, v97
	v_rcp_f32_e32 v100, v99
	v_add_f32_e32 v99, 1.0, v101
	v_rcp_f32_e32 v92, v92
	v_rcp_f32_e32 v93, v93
	v_rcp_f32_e32 v94, v94
	v_rcp_f32_e32 v95, v95
	v_rcp_f32_e32 v96, v96
	v_rcp_f32_e32 v97, v97
	v_rcp_f32_e32 v101, v99
	v_pk_mul_f32 v[92:93], v[86:87], v[92:93]
	v_pk_mul_f32 v[94:95], v[88:89], v[94:95]
	v_pk_mul_f32 v[96:97], v[82:83], v[96:97]
	v_pk_mul_f32 v[100:101], v[84:85], v[100:101]
	v_lshl_add_u64 v[104:105], s[10:11], 0, v[102:103]
	v_lshl_add_u64 v[104:105], v[186:187], 1, v[104:105]
	v_cvt_pk_bf16_f32 v92, v92, v93
	v_cvt_pk_bf16_f32 v93, v94, v95
	v_cvt_pk_bf16_f32 v94, v96, v97
	v_cvt_pk_bf16_f32 v95, v100, v101
	global_store_dwordx4 v[104:105], v[92:95], off offset:-2816 nt
	s_nop 1
	s_branch .LBB0_1578

.LBB0_1573:
	s_and_b64 vcc, exec, s[18:19]
	s_cbranch_vccz .LBB0_1575
	v_mul_f32_e32 v94, 0xbfb8aa3b, v88
	v_exp_f32_e32 v94, v94
	v_mul_f32_e32 v95, 0xbfb8aa3b, v89
	v_mul_f32_e32 v96, 0xbfb8aa3b, v82
	v_exp_f32_e32 v95, v95
	v_add_f32_e32 v94, 1.0, v94
	v_rcp_f32_e32 v94, v94
	v_exp_f32_e32 v96, v96
	v_mul_f32_e32 v100, 0xbfb8aa3b, v85
	v_mul_f32_e32 v92, 0xbfb8aa3b, v86
	v_fma_f32 v94, v235, v94, v12
	v_log_f32_e32 v97, v94
	v_add_f32_e32 v94, 1.0, v95
	v_add_f32_e32 v95, 1.0, v96
	v_rcp_f32_e32 v95, v95
	v_mul_f32_e32 v96, 0xbfb8aa3b, v83
	v_exp_f32_e32 v96, v96
	v_mul_f32_e32 v93, 0xbfb8aa3b, v87
	v_fma_f32 v95, v223, v95, v14
	v_log_f32_e32 v99, v95
	v_add_f32_e32 v95, 1.0, v96
	v_mul_f32_e32 v96, 0xbfb8aa3b, v84
	v_exp_f32_e32 v96, v96
	v_exp_f32_e32 v100, v100
	v_exp_f32_e32 v92, v92
	v_exp_f32_e32 v93, v93
	v_add_f32_e32 v96, 1.0, v96
	v_add_f32_e32 v100, 1.0, v100
	v_add_f32_e32 v92, 1.0, v92
	v_add_f32_e32 v93, 1.0, v93
	v_rcp_f32_e32 v94, v94
	v_rcp_f32_e32 v96, v96
	v_rcp_f32_e32 v100, v100
	v_rcp_f32_e32 v92, v92
	v_rcp_f32_e32 v93, v93
	v_rcp_f32_e32 v95, v95
	v_fma_f32 v94, v222, v94, v13
	v_fma_f32 v96, v221, v96, v16
	v_fma_f32 v100, v161, v100, v17
	v_fma_f32 v92, v237, v92, v10
	v_fma_f32 v93, v236, v93, v11
	v_fma_f32 v95, v220, v95, v15
	v_log_f32_e32 v96, v96
	v_log_f32_e32 v100, v100
	v_log_f32_e32 v104, v94
	v_log_f32_e32 v92, v92
	v_log_f32_e32 v101, v95
	v_log_f32_e32 v105, v93
	s_and_b64 s[18:19], s[54:55], exec
	s_cselect_b32 s19, s87, s92
	s_cselect_b32 s18, s79, s89
	v_cvt_pk_f16_f32 v95, v96, v100
	v_cvt_pk_f16_f32 v93, v97, v104
	v_lshl_add_u64 v[96:97], s[18:19], 0, v[102:103]
	v_lshlrev_b32_e32 v176, 1, v160
	v_cvt_pk_f16_f32 v94, v99, v101
	v_cvt_pk_f16_f32 v92, v92, v105
	v_lshl_add_u64 v[96:97], v[96:97], 0, v[176:177]
	global_store_dwordx4 v[96:97], v[92:95], off
	s_nop 1
	s_branch .LBB0_1578

.LBB0_1578:
	v_pk_fma_f32 v[78:79], v[78:79], v[200:201], v[54:55] op_sel_hi:[1,0,1]
	v_pk_fma_f32 v[80:81], v[80:81], v[200:201], v[56:57] op_sel_hi:[1,0,1]
	v_pk_fma_f32 v[82:83], v[74:75], v[200:201], v[50:51] op_sel_hi:[1,0,1]
	v_pk_fma_f32 v[76:77], v[76:77], v[200:201], v[52:53] op_sel_hi:[1,0,1]
	s_and_b64 vcc, exec, s[4:5]
	s_mov_b64 s[18:19], -1
	s_cbranch_vccnz .LBB0_1596
	s_and_b64 vcc, exec, s[2:3]
	s_cbranch_vccnz .LBB0_1593
	s_cmp_lt_i32 s39, 4
	s_cbranch_scc1 .LBB0_1590
	s_cmp_lg_u32 s39, 4
	s_cbranch_scc0 .LBB0_1587
	s_andn2_b64 vcc, exec, s[56:57]
	s_cbranch_vccnz .LBB0_1584
	v_mul_f32_e32 v74, 0xbfb8aa3b, v78
	v_mul_f32_e32 v75, 0xbfb8aa3b, v79
	v_mul_f32_e32 v84, 0xbfb8aa3b, v80
	v_exp_f32_e32 v74, v74
	v_exp_f32_e32 v75, v75
	v_exp_f32_e32 v84, v84
	v_mul_f32_e32 v85, 0xbfb8aa3b, v81
	v_add_f32_e32 v74, 1.0, v74
	v_add_f32_e32 v75, 1.0, v75
	v_add_f32_e32 v84, 1.0, v84
	v_rcp_f32_e32 v74, v74
	v_rcp_f32_e32 v75, v75
	v_rcp_f32_e32 v84, v84
	v_exp_f32_e32 v85, v85
	v_max_f32_e32 v86, 0x219392ef, v74
	v_max_f32_e32 v87, 0x219392ef, v75
	v_max_f32_e32 v88, 0x219392ef, v84
	v_add_f32_e32 v74, 1.0, v85
	v_mul_f32_e32 v75, 0xbfb8aa3b, v82
	v_mul_f32_e32 v84, 0xbfb8aa3b, v83
	v_rcp_f32_e32 v74, v74
	v_exp_f32_e32 v75, v75
	v_exp_f32_e32 v84, v84
	v_mul_f32_e32 v89, 0xbfb8aa3b, v77
	v_max_f32_e32 v85, 0x219392ef, v74
	v_add_f32_e32 v74, 1.0, v75
	v_add_f32_e32 v75, 1.0, v84
	v_mul_f32_e32 v84, 0xbfb8aa3b, v76
	v_exp_f32_e32 v84, v84
	v_exp_f32_e32 v89, v89
	v_rcp_f32_e32 v74, v74
	v_rcp_f32_e32 v75, v75
	v_add_f32_e32 v84, 1.0, v84
	v_add_f32_e32 v89, 1.0, v89
	v_rcp_f32_e32 v84, v84
	v_rcp_f32_e32 v89, v89
	v_max_f32_e32 v90, 0x219392ef, v74
	v_max_f32_e32 v91, 0x219392ef, v75
	v_lshlrev_b64 v[74:75], 12, v[198:199]
	v_lshl_add_u64 v[74:75], s[16:17], 0, v[74:75]
	v_lshl_add_u64 v[74:75], v[186:187], 1, v[74:75]
	v_max_f32_e32 v92, 0x219392ef, v84
	v_max_f32_e32 v89, 0x219392ef, v89
	v_add_co_u32_e32 v74, vcc, 0xffffe000, v74
	v_cvt_pk_bf16_f32 v84, v86, v87
	v_cvt_pk_bf16_f32 v85, v88, v85
	v_cvt_pk_bf16_f32 v86, v90, v91
	v_cvt_pk_bf16_f32 v87, v92, v89
	v_addc_co_u32_e32 v75, vcc, -1, v75, vcc
	s_mov_b64 s[18:19], 0
	global_store_dwordx4 v[74:75], v[84:87], off nt
	s_nop 1
	v_lshlrev_b64 v[84:85], 10, v[198:199]
	v_lshl_add_u64 v[74:75], s[8:9], 0, v[84:85]
	s_branch .LBB0_1598
.LBB0_1584:
	s_andn2_b64 vcc, exec, s[18:19]
	s_cbranch_vccnz .LBB0_1586
	v_ashrrev_i32_e32 v74, 11, v98
	v_ashrrev_i32_e32 v75, 31, v74
	v_lshlrev_b64 v[74:75], 11, v[74:75]
	v_lshl_add_u64 v[74:75], v[74:75], 0, v[192:193]
	s_movk_i32 s18, 0x7df
	v_and_or_b32 v74, v198, s18, v74
	v_lshl_add_u64 v[74:75], v[74:75], 4, s[14:15]
	v_cvt_pk_bf16_f32 v84, v78, v79
	v_cvt_pk_bf16_f32 v85, v80, v81
	v_cvt_pk_bf16_f32 v86, v82, v83
	v_cvt_pk_bf16_f32 v87, v76, v77
	global_store_dwordx4 v[74:75], v[84:87], off nt
	s_nop 1
	v_lshlrev_b64 v[84:85], 10, v[198:199]
	v_lshl_add_u64 v[74:75], s[8:9], 0, v[84:85]
	s_branch .LBB0_1598

.LBB0_1587:
	s_andn2_b64 vcc, exec, s[18:19]
	s_cbranch_vccnz .LBB0_1589
	v_mul_f32_e32 v84, 0xbfb8aa3b, v80
	v_mul_f32_e32 v85, 0xbfb8aa3b, v81
	v_mul_f32_e32 v74, 0xbfb8aa3b, v78
	v_mul_f32_e32 v75, 0xbfb8aa3b, v79
	v_exp_f32_e32 v84, v84
	v_exp_f32_e32 v85, v85
	v_mul_f32_e32 v86, 0xbfb8aa3b, v82
	v_mul_f32_e32 v87, 0xbfb8aa3b, v83
	v_mul_f32_e32 v88, 0xbfb8aa3b, v76
	v_mul_f32_e32 v89, 0xbfb8aa3b, v77
	v_exp_f32_e32 v74, v74
	v_exp_f32_e32 v75, v75
	v_exp_f32_e32 v86, v86
	v_exp_f32_e32 v87, v87
	v_exp_f32_e32 v88, v88
	v_exp_f32_e32 v89, v89
	v_add_f32_e32 v84, 1.0, v84
	v_add_f32_e32 v85, 1.0, v85
	v_add_f32_e32 v74, 1.0, v74
	v_add_f32_e32 v75, 1.0, v75
	v_rcp_f32_e32 v84, v84
	v_rcp_f32_e32 v85, v85
	v_add_f32_e32 v86, 1.0, v86
	v_add_f32_e32 v87, 1.0, v87
	v_add_f32_e32 v88, 1.0, v88
	v_add_f32_e32 v89, 1.0, v89
	v_rcp_f32_e32 v74, v74
	v_rcp_f32_e32 v75, v75
	v_rcp_f32_e32 v86, v86
	v_rcp_f32_e32 v87, v87
	v_rcp_f32_e32 v88, v88
	v_rcp_f32_e32 v89, v89
	v_pk_mul_f32 v[90:91], v[80:81], v[84:85]
	v_lshlrev_b64 v[84:85], 10, v[198:199]
	v_pk_mul_f32 v[74:75], v[78:79], v[74:75]
	v_pk_mul_f32 v[86:87], v[82:83], v[86:87]
	v_pk_mul_f32 v[88:89], v[76:77], v[88:89]
	v_lshl_add_u64 v[84:85], s[12:13], 0, v[84:85]
	v_lshl_add_u64 v[92:93], v[186:187], 1, v[84:85]
	v_cvt_pk_bf16_f32 v84, v74, v75
	v_cvt_pk_bf16_f32 v85, v90, v91
	v_cvt_pk_bf16_f32 v86, v86, v87
	v_cvt_pk_bf16_f32 v87, v88, v89
	global_store_dwordx4 v[92:93], v[84:87], off offset:-4096 nt
	s_nop 1
	v_lshlrev_b64 v[84:85], 10, v[198:199]
	v_lshl_add_u64 v[74:75], s[8:9], 0, v[84:85]
	s_branch .LBB0_1598

.LBB0_1590:
	s_andn2_b64 vcc, exec, s[18:19]
	s_cbranch_vccnz .LBB0_1592
	v_mul_f32_e32 v84, 0xbfb8aa3b, v80
	v_mul_f32_e32 v85, 0xbfb8aa3b, v81
	v_mul_f32_e32 v74, 0xbfb8aa3b, v78
	v_mul_f32_e32 v75, 0xbfb8aa3b, v79
	v_exp_f32_e32 v84, v84
	v_exp_f32_e32 v85, v85
	v_mul_f32_e32 v86, 0xbfb8aa3b, v82
	v_mul_f32_e32 v87, 0xbfb8aa3b, v83
	v_mul_f32_e32 v88, 0xbfb8aa3b, v76
	v_mul_f32_e32 v89, 0xbfb8aa3b, v77
	v_exp_f32_e32 v74, v74
	v_exp_f32_e32 v75, v75
	v_exp_f32_e32 v86, v86
	v_exp_f32_e32 v87, v87
	v_exp_f32_e32 v88, v88
	v_exp_f32_e32 v89, v89
	v_add_f32_e32 v84, 1.0, v84
	v_add_f32_e32 v85, 1.0, v85
	v_add_f32_e32 v74, 1.0, v74
	v_add_f32_e32 v75, 1.0, v75
	v_rcp_f32_e32 v84, v84
	v_rcp_f32_e32 v85, v85
	v_add_f32_e32 v86, 1.0, v86
	v_add_f32_e32 v87, 1.0, v87
	v_add_f32_e32 v88, 1.0, v88
	v_add_f32_e32 v89, 1.0, v89
	v_rcp_f32_e32 v74, v74
	v_rcp_f32_e32 v75, v75
	v_rcp_f32_e32 v86, v86
	v_rcp_f32_e32 v87, v87
	v_rcp_f32_e32 v88, v88
	v_rcp_f32_e32 v89, v89
	v_pk_mul_f32 v[90:91], v[80:81], v[84:85]
	v_lshlrev_b64 v[84:85], 10, v[198:199]
	v_pk_mul_f32 v[74:75], v[78:79], v[74:75]
	v_pk_mul_f32 v[86:87], v[82:83], v[86:87]
	v_pk_mul_f32 v[88:89], v[76:77], v[88:89]
	v_lshl_add_u64 v[84:85], s[10:11], 0, v[84:85]
	v_lshl_add_u64 v[92:93], v[186:187], 1, v[84:85]
	v_cvt_pk_bf16_f32 v84, v74, v75
	v_cvt_pk_bf16_f32 v85, v90, v91
	v_cvt_pk_bf16_f32 v86, v86, v87
	v_cvt_pk_bf16_f32 v87, v88, v89
	global_store_dwordx4 v[92:93], v[84:87], off offset:-3072 nt
	s_nop 1
	v_lshlrev_b64 v[84:85], 10, v[198:199]
	v_lshl_add_u64 v[74:75], s[8:9], 0, v[84:85]
	s_branch .LBB0_1598

.LBB0_1593:
	s_and_b64 vcc, exec, s[18:19]
	s_cbranch_vccz .LBB0_1595
	v_mul_f32_e32 v86, 0xbfb8aa3b, v80
	v_exp_f32_e32 v86, v86
	v_mul_f32_e32 v87, 0xbfb8aa3b, v81
	v_mul_f32_e32 v88, 0xbfb8aa3b, v82
	v_exp_f32_e32 v87, v87
	v_add_f32_e32 v86, 1.0, v86
	v_rcp_f32_e32 v86, v86
	v_exp_f32_e32 v88, v88
	v_mul_f32_e32 v74, 0xbfb8aa3b, v78
	v_mul_f32_e32 v85, 0xbfb8aa3b, v79
	v_fma_f32 v86, v240, v86, v40
	v_log_f32_e32 v89, v86
	v_add_f32_e32 v86, 1.0, v87
	v_add_f32_e32 v87, 1.0, v88
	v_rcp_f32_e32 v87, v87
	v_mul_f32_e32 v88, 0xbfb8aa3b, v83
	v_exp_f32_e32 v88, v88
	v_mul_f32_e32 v91, 0xbfb8aa3b, v77
	v_fma_f32 v87, v238, v87, v34
	v_log_f32_e32 v90, v87
	v_add_f32_e32 v87, 1.0, v88
	v_mul_f32_e32 v88, 0xbfb8aa3b, v76
	v_exp_f32_e32 v84, v74
	v_exp_f32_e32 v85, v85
	v_exp_f32_e32 v88, v88
	v_exp_f32_e32 v91, v91
	v_add_f32_e32 v84, 1.0, v84
	v_add_f32_e32 v85, 1.0, v85
	v_add_f32_e32 v88, 1.0, v88
	v_add_f32_e32 v91, 1.0, v91
	v_rcp_f32_e32 v84, v84
	v_rcp_f32_e32 v85, v85
	v_rcp_f32_e32 v86, v86
	v_rcp_f32_e32 v87, v87
	v_rcp_f32_e32 v88, v88
	v_rcp_f32_e32 v91, v91
	v_fma_f32 v84, v242, v84, v38
	v_fma_f32 v85, v241, v85, v39
	v_fma_f32 v86, v239, v86, v41
	v_fma_f32 v87, v234, v87, v35
	v_fma_f32 v88, v233, v88, v36
	v_fma_f32 v91, v229, v91, v37
	v_log_f32_e32 v84, v84
	v_log_f32_e32 v88, v88
	v_log_f32_e32 v91, v91
	v_log_f32_e32 v92, v87
	v_log_f32_e32 v93, v86
	v_log_f32_e32 v94, v85
	s_and_b64 s[18:19], s[54:55], exec
	s_cselect_b32 s19, s87, s92
	s_cselect_b32 s18, s79, s89
	v_lshlrev_b64 v[74:75], 10, v[198:199]
	v_lshl_add_u64 v[74:75], s[18:19], 0, v[74:75]
	v_lshlrev_b32_e32 v176, 1, v191
	v_cvt_pk_f16_f32 v87, v88, v91
	v_cvt_pk_f16_f32 v86, v90, v92
	v_cvt_pk_f16_f32 v85, v89, v93
	v_cvt_pk_f16_f32 v84, v84, v94
	v_lshl_add_u64 v[74:75], v[74:75], 0, v[176:177]
	global_store_dwordx4 v[74:75], v[84:87], off
	s_nop 1
	v_lshlrev_b64 v[84:85], 10, v[198:199]
	v_lshl_add_u64 v[74:75], s[8:9], 0, v[84:85]
	s_branch .LBB0_1598

.LBB0_1598:
	v_mov_b32_e32 v201, v200
	v_pk_fma_f32 v[70:71], v[70:71], v[200:201], v[30:31]
	v_pk_fma_f32 v[72:73], v[72:73], v[200:201], v[32:33]
	v_pk_fma_f32 v[66:67], v[66:67], v[200:201], v[26:27]
	v_pk_fma_f32 v[68:69], v[68:69], v[200:201], v[28:29]
	s_and_b64 vcc, exec, s[4:5]
	s_mov_b64 s[18:19], -1
	s_cbranch_vccnz .LBB0_1616
	s_and_b64 vcc, exec, s[2:3]
	s_cbranch_vccnz .LBB0_1613
	s_cmp_lt_i32 s39, 4
	s_cbranch_scc1 .LBB0_1610
	s_cmp_lg_u32 s39, 4
	s_cbranch_scc0 .LBB0_1607
	s_andn2_b64 vcc, exec, s[56:57]
	s_cbranch_vccnz .LBB0_1604
	v_mul_f32_e32 v76, 0xbfb8aa3b, v70
	v_mul_f32_e32 v77, 0xbfb8aa3b, v71
	v_exp_f32_e32 v76, v76
	v_exp_f32_e32 v77, v77
	v_mul_f32_e32 v79, 0xbfb8aa3b, v73
	v_exp_f32_e32 v79, v79
	v_add_f32_e32 v76, 1.0, v76
	v_add_f32_e32 v77, 1.0, v77
	v_rcp_f32_e32 v76, v76
	v_rcp_f32_e32 v77, v77
	v_mul_f32_e32 v80, 0xbfb8aa3b, v69
	v_mul_f32_e32 v78, 0xbfb8aa3b, v72
	v_max_f32_e32 v82, 0x219392ef, v76
	v_max_f32_e32 v83, 0x219392ef, v77
	v_add_f32_e32 v76, 1.0, v79
	v_mul_f32_e32 v77, 0xbfb8aa3b, v66
	v_mul_f32_e32 v79, 0xbfb8aa3b, v67
	v_rcp_f32_e32 v76, v76
	v_exp_f32_e32 v77, v77
	v_exp_f32_e32 v79, v79
	v_exp_f32_e32 v80, v80
	v_max_f32_e32 v86, 0x219392ef, v76
	v_add_f32_e32 v76, 1.0, v77
	v_add_f32_e32 v77, 1.0, v79
	v_mul_f32_e32 v79, 0xbfb8aa3b, v68
	v_exp_f32_e32 v78, v78
	v_exp_f32_e32 v79, v79
	v_rcp_f32_e32 v76, v76
	v_rcp_f32_e32 v77, v77
	v_add_f32_e32 v80, 1.0, v80
	v_add_f32_e32 v78, 1.0, v78
	v_add_f32_e32 v79, 1.0, v79
	v_rcp_f32_e32 v80, v80
	v_rcp_f32_e32 v78, v78
	v_rcp_f32_e32 v79, v79
	v_max_f32_e32 v87, 0x219392ef, v76
	v_max_f32_e32 v88, 0x219392ef, v77
	v_lshlrev_b64 v[76:77], 12, v[198:199]
	v_lshl_add_u64 v[76:77], s[16:17], 0, v[76:77]
	v_max_f32_e32 v89, 0x219392ef, v80
	v_lshl_add_u64 v[80:81], v[186:187], 1, v[76:77]
	v_max_f32_e32 v78, 0x219392ef, v78
	v_max_f32_e32 v79, 0x219392ef, v79
	v_add_co_u32_e32 v80, vcc, 0xfffff000, v80
	v_cvt_pk_bf16_f32 v76, v82, v83
	v_cvt_pk_bf16_f32 v77, v78, v86
	v_cvt_pk_bf16_f32 v78, v87, v88
	v_cvt_pk_bf16_f32 v79, v79, v89
	v_addc_co_u32_e32 v81, vcc, -1, v81, vcc
	s_mov_b64 s[18:19], 0
	global_store_dwordx4 v[80:81], v[76:79], off offset:-3840 nt
	s_nop 1
	s_branch .LBB0_1618
.LBB0_1604:
	s_andn2_b64 vcc, exec, s[18:19]
	s_cbranch_vccnz .LBB0_1606
	v_ashrrev_i32_e32 v76, 11, v98
	v_ashrrev_i32_e32 v77, 31, v76
	v_lshlrev_b64 v[76:77], 11, v[76:77]
	v_lshl_add_u64 v[76:77], v[76:77], 0, v[154:155]
	s_movk_i32 s18, 0x7df
	v_and_or_b32 v76, v198, s18, v76
	v_lshl_add_u64 v[80:81], v[76:77], 4, s[14:15]
	v_cvt_pk_bf16_f32 v76, v70, v71
	v_cvt_pk_bf16_f32 v77, v72, v73
	v_cvt_pk_bf16_f32 v78, v66, v67
	v_cvt_pk_bf16_f32 v79, v68, v69
	global_store_dwordx4 v[80:81], v[76:79], off nt
	s_nop 1
	s_branch .LBB0_1618

.LBB0_1607:
	s_andn2_b64 vcc, exec, s[18:19]
	s_cbranch_vccnz .LBB0_1609
	v_mul_f32_e32 v76, 0xbfb8aa3b, v70
	v_mul_f32_e32 v77, 0xbfb8aa3b, v71
	v_mul_f32_e32 v78, 0xbfb8aa3b, v72
	v_mul_f32_e32 v79, 0xbfb8aa3b, v73
	v_mul_f32_e32 v80, 0xbfb8aa3b, v66
	v_mul_f32_e32 v81, 0xbfb8aa3b, v67
	v_mul_f32_e32 v82, 0xbfb8aa3b, v68
	v_mul_f32_e32 v83, 0xbfb8aa3b, v69
	v_exp_f32_e32 v76, v76
	v_exp_f32_e32 v77, v77
	v_exp_f32_e32 v78, v78
	v_exp_f32_e32 v79, v79
	v_exp_f32_e32 v80, v80
	v_exp_f32_e32 v81, v81
	v_exp_f32_e32 v82, v82
	v_exp_f32_e32 v83, v83
	v_add_f32_e32 v76, 1.0, v76
	v_add_f32_e32 v77, 1.0, v77
	v_add_f32_e32 v78, 1.0, v78
	v_add_f32_e32 v79, 1.0, v79
	v_add_f32_e32 v80, 1.0, v80
	v_add_f32_e32 v81, 1.0, v81
	v_add_f32_e32 v82, 1.0, v82
	v_add_f32_e32 v83, 1.0, v83
	v_rcp_f32_e32 v76, v76
	v_rcp_f32_e32 v77, v77
	v_rcp_f32_e32 v78, v78
	v_rcp_f32_e32 v79, v79
	v_rcp_f32_e32 v80, v80
	v_rcp_f32_e32 v81, v81
	v_rcp_f32_e32 v82, v82
	v_rcp_f32_e32 v83, v83
	v_pk_mul_f32 v[76:77], v[70:71], v[76:77]
	v_pk_mul_f32 v[78:79], v[72:73], v[78:79]
	v_pk_mul_f32 v[80:81], v[66:67], v[80:81]
	v_pk_mul_f32 v[82:83], v[68:69], v[82:83]
	v_lshl_add_u64 v[86:87], s[12:13], 0, v[84:85]
	v_lshl_add_u64 v[86:87], v[186:187], 1, v[86:87]
	v_cvt_pk_bf16_f32 v76, v76, v77
	v_cvt_pk_bf16_f32 v77, v78, v79
	v_cvt_pk_bf16_f32 v78, v80, v81
	v_cvt_pk_bf16_f32 v79, v82, v83
	global_store_dwordx4 v[86:87], v[76:79], off offset:-3840 nt
	s_nop 1
	s_branch .LBB0_1618

.LBB0_1610:
	s_andn2_b64 vcc, exec, s[18:19]
	s_cbranch_vccnz .LBB0_1612
	v_mul_f32_e32 v76, 0xbfb8aa3b, v70
	v_mul_f32_e32 v77, 0xbfb8aa3b, v71
	v_mul_f32_e32 v78, 0xbfb8aa3b, v72
	v_mul_f32_e32 v79, 0xbfb8aa3b, v73
	v_mul_f32_e32 v80, 0xbfb8aa3b, v66
	v_mul_f32_e32 v81, 0xbfb8aa3b, v67
	v_mul_f32_e32 v82, 0xbfb8aa3b, v68
	v_mul_f32_e32 v83, 0xbfb8aa3b, v69
	v_exp_f32_e32 v76, v76
	v_exp_f32_e32 v77, v77
	v_exp_f32_e32 v78, v78
	v_exp_f32_e32 v79, v79
	v_exp_f32_e32 v80, v80
	v_exp_f32_e32 v81, v81
	v_exp_f32_e32 v82, v82
	v_exp_f32_e32 v83, v83
	v_add_f32_e32 v76, 1.0, v76
	v_add_f32_e32 v77, 1.0, v77
	v_add_f32_e32 v78, 1.0, v78
	v_add_f32_e32 v79, 1.0, v79
	v_add_f32_e32 v80, 1.0, v80
	v_add_f32_e32 v81, 1.0, v81
	v_add_f32_e32 v82, 1.0, v82
	v_add_f32_e32 v83, 1.0, v83
	v_rcp_f32_e32 v76, v76
	v_rcp_f32_e32 v77, v77
	v_rcp_f32_e32 v78, v78
	v_rcp_f32_e32 v79, v79
	v_rcp_f32_e32 v80, v80
	v_rcp_f32_e32 v81, v81
	v_rcp_f32_e32 v82, v82
	v_rcp_f32_e32 v83, v83
	v_pk_mul_f32 v[76:77], v[70:71], v[76:77]
	v_pk_mul_f32 v[78:79], v[72:73], v[78:79]
	v_pk_mul_f32 v[80:81], v[66:67], v[80:81]
	v_pk_mul_f32 v[82:83], v[68:69], v[82:83]
	v_lshl_add_u64 v[86:87], s[10:11], 0, v[84:85]
	v_lshl_add_u64 v[86:87], v[186:187], 1, v[86:87]
	v_cvt_pk_bf16_f32 v76, v76, v77
	v_cvt_pk_bf16_f32 v77, v78, v79
	v_cvt_pk_bf16_f32 v78, v80, v81
	v_cvt_pk_bf16_f32 v79, v82, v83
	global_store_dwordx4 v[86:87], v[76:79], off offset:-2816 nt
	s_nop 1
	s_branch .LBB0_1618

.LBB0_1613:
	s_and_b64 vcc, exec, s[18:19]
	s_cbranch_vccz .LBB0_1615
	v_mul_f32_e32 v78, 0xbfb8aa3b, v72
	v_exp_f32_e32 v78, v78
	v_mul_f32_e32 v79, 0xbfb8aa3b, v73
	v_mul_f32_e32 v80, 0xbfb8aa3b, v66
	v_exp_f32_e32 v79, v79
	v_add_f32_e32 v78, 1.0, v78
	v_rcp_f32_e32 v78, v78
	v_exp_f32_e32 v80, v80
	v_mul_f32_e32 v83, 0xbfb8aa3b, v69
	v_mul_f32_e32 v76, 0xbfb8aa3b, v70
	v_fma_f32 v78, v235, v78, v12
	v_log_f32_e32 v81, v78
	v_add_f32_e32 v78, 1.0, v79
	v_add_f32_e32 v79, 1.0, v80
	v_rcp_f32_e32 v79, v79
	v_mul_f32_e32 v80, 0xbfb8aa3b, v67
	v_exp_f32_e32 v80, v80
	v_mul_f32_e32 v77, 0xbfb8aa3b, v71
	v_fma_f32 v79, v223, v79, v14
	v_log_f32_e32 v82, v79
	v_add_f32_e32 v79, 1.0, v80
	v_mul_f32_e32 v80, 0xbfb8aa3b, v68
	v_exp_f32_e32 v80, v80
	v_exp_f32_e32 v83, v83
	v_exp_f32_e32 v76, v76
	v_exp_f32_e32 v77, v77
	v_add_f32_e32 v80, 1.0, v80
	v_add_f32_e32 v83, 1.0, v83
	v_add_f32_e32 v76, 1.0, v76
	v_add_f32_e32 v77, 1.0, v77
	v_rcp_f32_e32 v78, v78
	v_rcp_f32_e32 v80, v80
	v_rcp_f32_e32 v83, v83
	v_rcp_f32_e32 v76, v76
	v_rcp_f32_e32 v77, v77
	v_rcp_f32_e32 v79, v79
	v_fma_f32 v78, v222, v78, v13
	v_fma_f32 v80, v221, v80, v16
	v_fma_f32 v83, v161, v83, v17
	v_fma_f32 v76, v237, v76, v10
	v_fma_f32 v77, v236, v77, v11
	v_fma_f32 v79, v220, v79, v15
	v_log_f32_e32 v80, v80
	v_log_f32_e32 v83, v83
	v_log_f32_e32 v87, v78
	v_log_f32_e32 v76, v76
	v_log_f32_e32 v86, v79
	v_log_f32_e32 v88, v77
	s_and_b64 s[18:19], s[54:55], exec
	s_cselect_b32 s19, s87, s92
	s_cselect_b32 s18, s79, s89
	v_cvt_pk_f16_f32 v79, v80, v83
	v_cvt_pk_f16_f32 v77, v81, v87
	v_lshl_add_u64 v[80:81], s[18:19], 0, v[84:85]
	v_lshlrev_b32_e32 v176, 1, v160
	v_cvt_pk_f16_f32 v78, v82, v86
	v_cvt_pk_f16_f32 v76, v76, v88
	v_lshl_add_u64 v[80:81], v[80:81], 0, v[176:177]
	global_store_dwordx4 v[80:81], v[76:79], off
	s_nop 1
	s_branch .LBB0_1618

.LBB0_1618:
	v_pk_fma_f32 v[62:63], v[62:63], v[196:197], v[54:55] op_sel_hi:[1,0,1]
	v_pk_fma_f32 v[64:65], v[64:65], v[196:197], v[56:57] op_sel_hi:[1,0,1]
	v_pk_fma_f32 v[66:67], v[58:59], v[196:197], v[50:51] op_sel_hi:[1,0,1]
	v_pk_fma_f32 v[60:61], v[60:61], v[196:197], v[52:53] op_sel_hi:[1,0,1]
	s_and_b64 vcc, exec, s[4:5]
	s_mov_b64 s[18:19], -1
	s_cbranch_vccnz .LBB0_1636
	s_and_b64 vcc, exec, s[2:3]
	s_cbranch_vccnz .LBB0_1633
	s_cmp_lt_i32 s39, 4
	s_cbranch_scc1 .LBB0_1630
	s_cmp_lg_u32 s39, 4
	s_cbranch_scc0 .LBB0_1627
	s_andn2_b64 vcc, exec, s[56:57]
	s_cbranch_vccnz .LBB0_1624
	v_mul_f32_e32 v58, 0xbfb8aa3b, v62
	v_mul_f32_e32 v59, 0xbfb8aa3b, v63
	v_mul_f32_e32 v68, 0xbfb8aa3b, v64
	v_exp_f32_e32 v58, v58
	v_exp_f32_e32 v59, v59
	v_exp_f32_e32 v68, v68
	v_mul_f32_e32 v69, 0xbfb8aa3b, v65
	v_add_f32_e32 v58, 1.0, v58
	v_add_f32_e32 v59, 1.0, v59
	v_add_f32_e32 v68, 1.0, v68
	v_rcp_f32_e32 v58, v58
	v_rcp_f32_e32 v59, v59
	v_rcp_f32_e32 v68, v68
	v_exp_f32_e32 v69, v69
	v_max_f32_e32 v70, 0x219392ef, v58
	v_max_f32_e32 v71, 0x219392ef, v59
	v_max_f32_e32 v72, 0x219392ef, v68
	v_add_f32_e32 v58, 1.0, v69
	v_mul_f32_e32 v59, 0xbfb8aa3b, v66
	v_mul_f32_e32 v68, 0xbfb8aa3b, v67
	v_rcp_f32_e32 v58, v58
	v_exp_f32_e32 v59, v59
	v_exp_f32_e32 v68, v68
	v_mul_f32_e32 v73, 0xbfb8aa3b, v61
	v_max_f32_e32 v69, 0x219392ef, v58
	v_add_f32_e32 v58, 1.0, v59
	v_add_f32_e32 v59, 1.0, v68
	v_mul_f32_e32 v68, 0xbfb8aa3b, v60
	v_exp_f32_e32 v68, v68
	v_exp_f32_e32 v73, v73
	v_rcp_f32_e32 v58, v58
	v_rcp_f32_e32 v59, v59
	v_add_f32_e32 v68, 1.0, v68
	v_add_f32_e32 v73, 1.0, v73
	v_rcp_f32_e32 v68, v68
	v_rcp_f32_e32 v73, v73
	v_max_f32_e32 v74, 0x219392ef, v58
	v_max_f32_e32 v75, 0x219392ef, v59
	v_lshlrev_b64 v[58:59], 12, v[194:195]
	v_lshl_add_u64 v[58:59], s[16:17], 0, v[58:59]
	v_lshl_add_u64 v[58:59], v[186:187], 1, v[58:59]
	v_max_f32_e32 v76, 0x219392ef, v68
	v_max_f32_e32 v73, 0x219392ef, v73
	v_add_co_u32_e32 v58, vcc, 0xffffe000, v58
	v_cvt_pk_bf16_f32 v68, v70, v71
	v_cvt_pk_bf16_f32 v69, v72, v69
	v_cvt_pk_bf16_f32 v70, v74, v75
	v_cvt_pk_bf16_f32 v71, v76, v73
	v_addc_co_u32_e32 v59, vcc, -1, v59, vcc
	s_mov_b64 s[18:19], 0
	global_store_dwordx4 v[58:59], v[68:71], off nt
	s_nop 1
	v_lshlrev_b64 v[68:69], 10, v[194:195]
	v_lshl_add_u64 v[58:59], s[8:9], 0, v[68:69]
	s_branch .LBB0_1638
.LBB0_1624:
	s_andn2_b64 vcc, exec, s[18:19]
	s_cbranch_vccnz .LBB0_1626
	v_ashrrev_i32_e32 v58, 11, v98
	v_ashrrev_i32_e32 v59, 31, v58
	v_lshlrev_b64 v[58:59], 11, v[58:59]
	v_lshl_add_u64 v[58:59], v[58:59], 0, v[192:193]
	s_movk_i32 s18, 0x7ef
	v_and_or_b32 v58, v194, s18, v58
	v_lshl_add_u64 v[58:59], v[58:59], 4, s[14:15]
	v_cvt_pk_bf16_f32 v68, v62, v63
	v_cvt_pk_bf16_f32 v69, v64, v65
	v_cvt_pk_bf16_f32 v70, v66, v67
	v_cvt_pk_bf16_f32 v71, v60, v61
	global_store_dwordx4 v[58:59], v[68:71], off nt
	s_nop 1
	v_lshlrev_b64 v[68:69], 10, v[194:195]
	v_lshl_add_u64 v[58:59], s[8:9], 0, v[68:69]
	s_branch .LBB0_1638

.LBB0_1627:
	s_andn2_b64 vcc, exec, s[18:19]
	s_cbranch_vccnz .LBB0_1629
	v_mul_f32_e32 v68, 0xbfb8aa3b, v64
	v_mul_f32_e32 v69, 0xbfb8aa3b, v65
	v_mul_f32_e32 v58, 0xbfb8aa3b, v62
	v_mul_f32_e32 v59, 0xbfb8aa3b, v63
	v_exp_f32_e32 v68, v68
	v_exp_f32_e32 v69, v69
	v_mul_f32_e32 v70, 0xbfb8aa3b, v66
	v_mul_f32_e32 v71, 0xbfb8aa3b, v67
	v_mul_f32_e32 v72, 0xbfb8aa3b, v60
	v_mul_f32_e32 v73, 0xbfb8aa3b, v61
	v_exp_f32_e32 v58, v58
	v_exp_f32_e32 v59, v59
	v_exp_f32_e32 v70, v70
	v_exp_f32_e32 v71, v71
	v_exp_f32_e32 v72, v72
	v_exp_f32_e32 v73, v73
	v_add_f32_e32 v68, 1.0, v68
	v_add_f32_e32 v69, 1.0, v69
	v_add_f32_e32 v58, 1.0, v58
	v_add_f32_e32 v59, 1.0, v59
	v_rcp_f32_e32 v68, v68
	v_rcp_f32_e32 v69, v69
	v_add_f32_e32 v70, 1.0, v70
	v_add_f32_e32 v71, 1.0, v71
	v_add_f32_e32 v72, 1.0, v72
	v_add_f32_e32 v73, 1.0, v73
	v_rcp_f32_e32 v58, v58
	v_rcp_f32_e32 v59, v59
	v_rcp_f32_e32 v70, v70
	v_rcp_f32_e32 v71, v71
	v_rcp_f32_e32 v72, v72
	v_rcp_f32_e32 v73, v73
	v_pk_mul_f32 v[74:75], v[64:65], v[68:69]
	v_lshlrev_b64 v[68:69], 10, v[194:195]
	v_pk_mul_f32 v[58:59], v[62:63], v[58:59]
	v_pk_mul_f32 v[70:71], v[66:67], v[70:71]
	v_pk_mul_f32 v[72:73], v[60:61], v[72:73]
	v_lshl_add_u64 v[68:69], s[12:13], 0, v[68:69]
	v_lshl_add_u64 v[76:77], v[186:187], 1, v[68:69]
	v_cvt_pk_bf16_f32 v68, v58, v59
	v_cvt_pk_bf16_f32 v69, v74, v75
	v_cvt_pk_bf16_f32 v70, v70, v71
	v_cvt_pk_bf16_f32 v71, v72, v73
	global_store_dwordx4 v[76:77], v[68:71], off offset:-4096 nt
	s_nop 1
	v_lshlrev_b64 v[68:69], 10, v[194:195]
	v_lshl_add_u64 v[58:59], s[8:9], 0, v[68:69]
	s_branch .LBB0_1638

.LBB0_1630:
	s_andn2_b64 vcc, exec, s[18:19]
	s_cbranch_vccnz .LBB0_1632
	v_mul_f32_e32 v68, 0xbfb8aa3b, v64
	v_mul_f32_e32 v69, 0xbfb8aa3b, v65
	v_mul_f32_e32 v58, 0xbfb8aa3b, v62
	v_mul_f32_e32 v59, 0xbfb8aa3b, v63
	v_exp_f32_e32 v68, v68
	v_exp_f32_e32 v69, v69
	v_mul_f32_e32 v70, 0xbfb8aa3b, v66
	v_mul_f32_e32 v71, 0xbfb8aa3b, v67
	v_mul_f32_e32 v72, 0xbfb8aa3b, v60
	v_mul_f32_e32 v73, 0xbfb8aa3b, v61
	v_exp_f32_e32 v58, v58
	v_exp_f32_e32 v59, v59
	v_exp_f32_e32 v70, v70
	v_exp_f32_e32 v71, v71
	v_exp_f32_e32 v72, v72
	v_exp_f32_e32 v73, v73
	v_add_f32_e32 v68, 1.0, v68
	v_add_f32_e32 v69, 1.0, v69
	v_add_f32_e32 v58, 1.0, v58
	v_add_f32_e32 v59, 1.0, v59
	v_rcp_f32_e32 v68, v68
	v_rcp_f32_e32 v69, v69
	v_add_f32_e32 v70, 1.0, v70
	v_add_f32_e32 v71, 1.0, v71
	v_add_f32_e32 v72, 1.0, v72
	v_add_f32_e32 v73, 1.0, v73
	v_rcp_f32_e32 v58, v58
	v_rcp_f32_e32 v59, v59
	v_rcp_f32_e32 v70, v70
	v_rcp_f32_e32 v71, v71
	v_rcp_f32_e32 v72, v72
	v_rcp_f32_e32 v73, v73
	v_pk_mul_f32 v[74:75], v[64:65], v[68:69]
	v_lshlrev_b64 v[68:69], 10, v[194:195]
	v_pk_mul_f32 v[58:59], v[62:63], v[58:59]
	v_pk_mul_f32 v[70:71], v[66:67], v[70:71]
	v_pk_mul_f32 v[72:73], v[60:61], v[72:73]
	v_lshl_add_u64 v[68:69], s[10:11], 0, v[68:69]
	v_lshl_add_u64 v[76:77], v[186:187], 1, v[68:69]
	v_cvt_pk_bf16_f32 v68, v58, v59
	v_cvt_pk_bf16_f32 v69, v74, v75
	v_cvt_pk_bf16_f32 v70, v70, v71
	v_cvt_pk_bf16_f32 v71, v72, v73
	global_store_dwordx4 v[76:77], v[68:71], off offset:-3072 nt
	s_nop 1
	v_lshlrev_b64 v[68:69], 10, v[194:195]
	v_lshl_add_u64 v[58:59], s[8:9], 0, v[68:69]
	s_branch .LBB0_1638

.LBB0_1633:
	s_and_b64 vcc, exec, s[18:19]
	s_cbranch_vccz .LBB0_1635
	v_mul_f32_e32 v70, 0xbfb8aa3b, v64
	v_exp_f32_e32 v70, v70
	v_mul_f32_e32 v71, 0xbfb8aa3b, v65
	v_mul_f32_e32 v72, 0xbfb8aa3b, v66
	v_exp_f32_e32 v71, v71
	v_add_f32_e32 v70, 1.0, v70
	v_rcp_f32_e32 v70, v70
	v_exp_f32_e32 v72, v72
	v_mul_f32_e32 v58, 0xbfb8aa3b, v62
	v_mul_f32_e32 v69, 0xbfb8aa3b, v63
	v_fma_f32 v70, v240, v70, v40
	v_log_f32_e32 v73, v70
	v_add_f32_e32 v70, 1.0, v71
	v_add_f32_e32 v71, 1.0, v72
	v_rcp_f32_e32 v71, v71
	v_mul_f32_e32 v72, 0xbfb8aa3b, v67
	v_exp_f32_e32 v72, v72
	v_mul_f32_e32 v75, 0xbfb8aa3b, v61
	v_fma_f32 v71, v238, v71, v34
	v_log_f32_e32 v74, v71
	v_add_f32_e32 v71, 1.0, v72
	v_mul_f32_e32 v72, 0xbfb8aa3b, v60
	v_exp_f32_e32 v68, v58
	v_exp_f32_e32 v69, v69
	v_exp_f32_e32 v72, v72
	v_exp_f32_e32 v75, v75
	v_add_f32_e32 v68, 1.0, v68
	v_add_f32_e32 v69, 1.0, v69
	v_add_f32_e32 v72, 1.0, v72
	v_add_f32_e32 v75, 1.0, v75
	v_rcp_f32_e32 v68, v68
	v_rcp_f32_e32 v69, v69
	v_rcp_f32_e32 v70, v70
	v_rcp_f32_e32 v71, v71
	v_rcp_f32_e32 v72, v72
	v_rcp_f32_e32 v75, v75
	v_fma_f32 v68, v242, v68, v38
	v_fma_f32 v69, v241, v69, v39
	v_fma_f32 v70, v239, v70, v41
	v_fma_f32 v71, v234, v71, v35
	v_fma_f32 v72, v233, v72, v36
	v_fma_f32 v75, v229, v75, v37
	v_log_f32_e32 v68, v68
	v_log_f32_e32 v72, v72
	v_log_f32_e32 v75, v75
	v_log_f32_e32 v76, v71
	v_log_f32_e32 v77, v70
	v_log_f32_e32 v78, v69
	s_and_b64 s[18:19], s[54:55], exec
	s_cselect_b32 s19, s87, s92
	s_cselect_b32 s18, s79, s89
	v_lshlrev_b64 v[58:59], 10, v[194:195]
	v_lshl_add_u64 v[58:59], s[18:19], 0, v[58:59]
	v_lshlrev_b32_e32 v176, 1, v191
	v_cvt_pk_f16_f32 v71, v72, v75
	v_cvt_pk_f16_f32 v70, v74, v76
	v_cvt_pk_f16_f32 v69, v73, v77
	v_cvt_pk_f16_f32 v68, v68, v78
	v_lshl_add_u64 v[58:59], v[58:59], 0, v[176:177]
	global_store_dwordx4 v[58:59], v[68:71], off
	s_nop 1
	v_lshlrev_b64 v[68:69], 10, v[194:195]
	v_lshl_add_u64 v[58:59], s[8:9], 0, v[68:69]
	s_branch .LBB0_1638

.LBB0_1638:
	v_mov_b32_e32 v197, v196
	v_pk_fma_f32 v[46:47], v[46:47], v[196:197], v[30:31]
	v_pk_fma_f32 v[48:49], v[48:49], v[196:197], v[32:33]
	v_pk_fma_f32 v[42:43], v[42:43], v[196:197], v[26:27]
	v_pk_fma_f32 v[44:45], v[44:45], v[196:197], v[28:29]
	s_and_b64 vcc, exec, s[4:5]
	s_mov_b64 s[18:19], -1
	s_cbranch_vccnz .LBB0_1656
	s_and_b64 vcc, exec, s[2:3]
	s_cbranch_vccnz .LBB0_1653
	s_cmp_lt_i32 s39, 4
	s_cbranch_scc1 .LBB0_1650
	s_cmp_lg_u32 s39, 4
	s_cbranch_scc0 .LBB0_1647
	s_andn2_b64 vcc, exec, s[56:57]
	s_cbranch_vccnz .LBB0_1644
	v_mul_f32_e32 v60, 0xbfb8aa3b, v46
	v_mul_f32_e32 v61, 0xbfb8aa3b, v47
	v_exp_f32_e32 v60, v60
	v_exp_f32_e32 v61, v61
	v_mul_f32_e32 v63, 0xbfb8aa3b, v49
	v_exp_f32_e32 v63, v63
	v_add_f32_e32 v60, 1.0, v60
	v_add_f32_e32 v61, 1.0, v61
	v_rcp_f32_e32 v60, v60
	v_rcp_f32_e32 v61, v61
	v_mul_f32_e32 v64, 0xbfb8aa3b, v45
	v_mul_f32_e32 v62, 0xbfb8aa3b, v48
	v_max_f32_e32 v66, 0x219392ef, v60
	v_max_f32_e32 v67, 0x219392ef, v61
	v_add_f32_e32 v60, 1.0, v63
	v_mul_f32_e32 v61, 0xbfb8aa3b, v42
	v_mul_f32_e32 v63, 0xbfb8aa3b, v43
	v_rcp_f32_e32 v60, v60
	v_exp_f32_e32 v61, v61
	v_exp_f32_e32 v63, v63
	v_exp_f32_e32 v64, v64
	v_max_f32_e32 v70, 0x219392ef, v60
	v_add_f32_e32 v60, 1.0, v61
	v_add_f32_e32 v61, 1.0, v63
	v_mul_f32_e32 v63, 0xbfb8aa3b, v44
	v_exp_f32_e32 v62, v62
	v_exp_f32_e32 v63, v63
	v_rcp_f32_e32 v60, v60
	v_rcp_f32_e32 v61, v61
	v_add_f32_e32 v64, 1.0, v64
	v_add_f32_e32 v62, 1.0, v62
	v_add_f32_e32 v63, 1.0, v63
	v_rcp_f32_e32 v64, v64
	v_rcp_f32_e32 v62, v62
	v_rcp_f32_e32 v63, v63
	v_max_f32_e32 v71, 0x219392ef, v60
	v_max_f32_e32 v72, 0x219392ef, v61
	v_lshlrev_b64 v[60:61], 12, v[194:195]
	v_lshl_add_u64 v[60:61], s[16:17], 0, v[60:61]
	v_max_f32_e32 v73, 0x219392ef, v64
	v_lshl_add_u64 v[64:65], v[186:187], 1, v[60:61]
	v_max_f32_e32 v62, 0x219392ef, v62
	v_max_f32_e32 v63, 0x219392ef, v63
	v_add_co_u32_e32 v64, vcc, 0xfffff000, v64
	v_cvt_pk_bf16_f32 v60, v66, v67
	v_cvt_pk_bf16_f32 v61, v62, v70
	v_cvt_pk_bf16_f32 v62, v71, v72
	v_cvt_pk_bf16_f32 v63, v63, v73
	v_addc_co_u32_e32 v65, vcc, -1, v65, vcc
	s_mov_b64 s[18:19], 0
	global_store_dwordx4 v[64:65], v[60:63], off offset:-3840 nt
	s_nop 1
	s_branch .LBB0_1658
.LBB0_1644:
	s_andn2_b64 vcc, exec, s[18:19]
	s_cbranch_vccnz .LBB0_1646
	v_ashrrev_i32_e32 v60, 11, v98
	v_ashrrev_i32_e32 v61, 31, v60
	v_lshlrev_b64 v[60:61], 11, v[60:61]
	v_lshl_add_u64 v[60:61], v[60:61], 0, v[154:155]
	s_movk_i32 s18, 0x7ef
	v_and_or_b32 v60, v194, s18, v60
	v_lshl_add_u64 v[64:65], v[60:61], 4, s[14:15]
	v_cvt_pk_bf16_f32 v60, v46, v47
	v_cvt_pk_bf16_f32 v61, v48, v49
	v_cvt_pk_bf16_f32 v62, v42, v43
	v_cvt_pk_bf16_f32 v63, v44, v45
	global_store_dwordx4 v[64:65], v[60:63], off nt
	s_nop 1
	s_branch .LBB0_1658

.LBB0_1647:
	s_andn2_b64 vcc, exec, s[18:19]
	s_cbranch_vccnz .LBB0_1649
	v_mul_f32_e32 v60, 0xbfb8aa3b, v46
	v_mul_f32_e32 v61, 0xbfb8aa3b, v47
	v_mul_f32_e32 v62, 0xbfb8aa3b, v48
	v_mul_f32_e32 v63, 0xbfb8aa3b, v49
	v_mul_f32_e32 v64, 0xbfb8aa3b, v42
	v_mul_f32_e32 v65, 0xbfb8aa3b, v43
	v_mul_f32_e32 v66, 0xbfb8aa3b, v44
	v_mul_f32_e32 v67, 0xbfb8aa3b, v45
	v_exp_f32_e32 v60, v60
	v_exp_f32_e32 v61, v61
	v_exp_f32_e32 v62, v62
	v_exp_f32_e32 v63, v63
	v_exp_f32_e32 v64, v64
	v_exp_f32_e32 v65, v65
	v_exp_f32_e32 v66, v66
	v_exp_f32_e32 v67, v67
	v_add_f32_e32 v60, 1.0, v60
	v_add_f32_e32 v61, 1.0, v61
	v_add_f32_e32 v62, 1.0, v62
	v_add_f32_e32 v63, 1.0, v63
	v_add_f32_e32 v64, 1.0, v64
	v_add_f32_e32 v65, 1.0, v65
	v_add_f32_e32 v66, 1.0, v66
	v_add_f32_e32 v67, 1.0, v67
	v_rcp_f32_e32 v60, v60
	v_rcp_f32_e32 v61, v61
	v_rcp_f32_e32 v62, v62
	v_rcp_f32_e32 v63, v63
	v_rcp_f32_e32 v64, v64
	v_rcp_f32_e32 v65, v65
	v_rcp_f32_e32 v66, v66
	v_rcp_f32_e32 v67, v67
	v_pk_mul_f32 v[60:61], v[46:47], v[60:61]
	v_pk_mul_f32 v[62:63], v[48:49], v[62:63]
	v_pk_mul_f32 v[64:65], v[42:43], v[64:65]
	v_pk_mul_f32 v[66:67], v[44:45], v[66:67]
	v_lshl_add_u64 v[70:71], s[12:13], 0, v[68:69]
	v_lshl_add_u64 v[70:71], v[186:187], 1, v[70:71]
	v_cvt_pk_bf16_f32 v60, v60, v61
	v_cvt_pk_bf16_f32 v61, v62, v63
	v_cvt_pk_bf16_f32 v62, v64, v65
	v_cvt_pk_bf16_f32 v63, v66, v67
	global_store_dwordx4 v[70:71], v[60:63], off offset:-3840 nt
	s_nop 1
	s_branch .LBB0_1658

.LBB0_1650:
	s_andn2_b64 vcc, exec, s[18:19]
	s_cbranch_vccnz .LBB0_1652
	v_mul_f32_e32 v60, 0xbfb8aa3b, v46
	v_mul_f32_e32 v61, 0xbfb8aa3b, v47
	v_mul_f32_e32 v62, 0xbfb8aa3b, v48
	v_mul_f32_e32 v63, 0xbfb8aa3b, v49
	v_mul_f32_e32 v64, 0xbfb8aa3b, v42
	v_mul_f32_e32 v65, 0xbfb8aa3b, v43
	v_mul_f32_e32 v66, 0xbfb8aa3b, v44
	v_mul_f32_e32 v67, 0xbfb8aa3b, v45
	v_exp_f32_e32 v60, v60
	v_exp_f32_e32 v61, v61
	v_exp_f32_e32 v62, v62
	v_exp_f32_e32 v63, v63
	v_exp_f32_e32 v64, v64
	v_exp_f32_e32 v65, v65
	v_exp_f32_e32 v66, v66
	v_exp_f32_e32 v67, v67
	v_add_f32_e32 v60, 1.0, v60
	v_add_f32_e32 v61, 1.0, v61
	v_add_f32_e32 v62, 1.0, v62
	v_add_f32_e32 v63, 1.0, v63
	v_add_f32_e32 v64, 1.0, v64
	v_add_f32_e32 v65, 1.0, v65
	v_add_f32_e32 v66, 1.0, v66
	v_add_f32_e32 v67, 1.0, v67
	v_rcp_f32_e32 v60, v60
	v_rcp_f32_e32 v61, v61
	v_rcp_f32_e32 v62, v62
	v_rcp_f32_e32 v63, v63
	v_rcp_f32_e32 v64, v64
	v_rcp_f32_e32 v65, v65
	v_rcp_f32_e32 v66, v66
	v_rcp_f32_e32 v67, v67
	v_pk_mul_f32 v[60:61], v[46:47], v[60:61]
	v_pk_mul_f32 v[62:63], v[48:49], v[62:63]
	v_pk_mul_f32 v[64:65], v[42:43], v[64:65]
	v_pk_mul_f32 v[66:67], v[44:45], v[66:67]
	v_lshl_add_u64 v[70:71], s[10:11], 0, v[68:69]
	v_lshl_add_u64 v[70:71], v[186:187], 1, v[70:71]
	v_cvt_pk_bf16_f32 v60, v60, v61
	v_cvt_pk_bf16_f32 v61, v62, v63
	v_cvt_pk_bf16_f32 v62, v64, v65
	v_cvt_pk_bf16_f32 v63, v66, v67
	global_store_dwordx4 v[70:71], v[60:63], off offset:-2816 nt
	s_nop 1
	s_branch .LBB0_1658

.LBB0_1653:
	s_and_b64 vcc, exec, s[18:19]
	s_cbranch_vccz .LBB0_1655
	v_mul_f32_e32 v62, 0xbfb8aa3b, v48
	v_exp_f32_e32 v62, v62
	v_mul_f32_e32 v63, 0xbfb8aa3b, v49
	v_mul_f32_e32 v64, 0xbfb8aa3b, v42
	v_exp_f32_e32 v63, v63
	v_add_f32_e32 v62, 1.0, v62
	v_rcp_f32_e32 v62, v62
	v_exp_f32_e32 v64, v64
	v_mul_f32_e32 v67, 0xbfb8aa3b, v45
	v_mul_f32_e32 v60, 0xbfb8aa3b, v46
	v_fma_f32 v62, v235, v62, v12
	v_log_f32_e32 v65, v62
	v_add_f32_e32 v62, 1.0, v63
	v_add_f32_e32 v63, 1.0, v64
	v_rcp_f32_e32 v63, v63
	v_mul_f32_e32 v64, 0xbfb8aa3b, v43
	v_exp_f32_e32 v64, v64
	v_mul_f32_e32 v61, 0xbfb8aa3b, v47
	v_fma_f32 v63, v223, v63, v14
	v_log_f32_e32 v66, v63
	v_add_f32_e32 v63, 1.0, v64
	v_mul_f32_e32 v64, 0xbfb8aa3b, v44
	v_exp_f32_e32 v64, v64
	v_exp_f32_e32 v67, v67
	v_exp_f32_e32 v60, v60
	v_exp_f32_e32 v61, v61
	v_add_f32_e32 v64, 1.0, v64
	v_add_f32_e32 v67, 1.0, v67
	v_add_f32_e32 v60, 1.0, v60
	v_add_f32_e32 v61, 1.0, v61
	v_rcp_f32_e32 v62, v62
	v_rcp_f32_e32 v64, v64
	v_rcp_f32_e32 v67, v67
	v_rcp_f32_e32 v60, v60
	v_rcp_f32_e32 v61, v61
	v_rcp_f32_e32 v63, v63
	v_fma_f32 v62, v222, v62, v13
	v_fma_f32 v64, v221, v64, v16
	v_fma_f32 v67, v161, v67, v17
	v_fma_f32 v60, v237, v60, v10
	v_fma_f32 v61, v236, v61, v11
	v_fma_f32 v63, v220, v63, v15
	v_log_f32_e32 v64, v64
	v_log_f32_e32 v67, v67
	v_log_f32_e32 v71, v62
	v_log_f32_e32 v60, v60
	v_log_f32_e32 v70, v63
	v_log_f32_e32 v72, v61
	s_and_b64 s[18:19], s[54:55], exec
	s_cselect_b32 s19, s87, s92
	s_cselect_b32 s18, s79, s89
	v_cvt_pk_f16_f32 v63, v64, v67
	v_cvt_pk_f16_f32 v61, v65, v71
	v_lshl_add_u64 v[64:65], s[18:19], 0, v[68:69]
	v_lshlrev_b32_e32 v176, 1, v160
	v_cvt_pk_f16_f32 v62, v66, v70
	v_cvt_pk_f16_f32 v60, v60, v72
	v_lshl_add_u64 v[64:65], v[64:65], 0, v[176:177]
	global_store_dwordx4 v[64:65], v[60:63], off
	s_nop 1
	s_branch .LBB0_1658

.LBB0_1658:
	v_pk_fma_f32 v[22:23], v[22:23], v[190:191], v[54:55] op_sel_hi:[1,0,1]
	v_pk_fma_f32 v[24:25], v[24:25], v[190:191], v[56:57] op_sel_hi:[1,0,1]
	v_pk_fma_f32 v[18:19], v[18:19], v[190:191], v[50:51] op_sel_hi:[1,0,1]
	v_pk_fma_f32 v[20:21], v[20:21], v[190:191], v[52:53] op_sel_hi:[1,0,1]
	s_and_b64 vcc, exec, s[4:5]
	s_mov_b64 s[18:19], -1
	s_cbranch_vccnz .LBB0_1676
	s_and_b64 vcc, exec, s[2:3]
	s_cbranch_vccnz .LBB0_1673
	s_cmp_lt_i32 s39, 4
	s_cbranch_scc1 .LBB0_1670
	s_cmp_lg_u32 s39, 4
	s_cbranch_scc0 .LBB0_1667
	s_andn2_b64 vcc, exec, s[56:57]
	s_cbranch_vccnz .LBB0_1664
	v_mul_f32_e32 v42, 0xbfb8aa3b, v22
	v_mul_f32_e32 v43, 0xbfb8aa3b, v23
	v_exp_f32_e32 v42, v42
	v_exp_f32_e32 v43, v43
	v_mul_f32_e32 v45, 0xbfb8aa3b, v25
	v_exp_f32_e32 v45, v45
	v_add_f32_e32 v42, 1.0, v42
	v_add_f32_e32 v43, 1.0, v43
	v_rcp_f32_e32 v42, v42
	v_rcp_f32_e32 v43, v43
	v_mul_f32_e32 v46, 0xbfb8aa3b, v21
	v_mul_f32_e32 v44, 0xbfb8aa3b, v24
	v_max_f32_e32 v48, 0x219392ef, v42
	v_max_f32_e32 v49, 0x219392ef, v43
	v_add_f32_e32 v42, 1.0, v45
	v_mul_f32_e32 v43, 0xbfb8aa3b, v18
	v_mul_f32_e32 v45, 0xbfb8aa3b, v19
	v_rcp_f32_e32 v42, v42
	v_exp_f32_e32 v43, v43
	v_exp_f32_e32 v45, v45
	v_exp_f32_e32 v46, v46
	v_max_f32_e32 v50, 0x219392ef, v42
	v_add_f32_e32 v42, 1.0, v43
	v_add_f32_e32 v43, 1.0, v45
	v_mul_f32_e32 v45, 0xbfb8aa3b, v20
	v_exp_f32_e32 v44, v44
	v_exp_f32_e32 v45, v45
	v_rcp_f32_e32 v42, v42
	v_rcp_f32_e32 v43, v43
	v_add_f32_e32 v46, 1.0, v46
	v_add_f32_e32 v44, 1.0, v44
	v_add_f32_e32 v45, 1.0, v45
	v_rcp_f32_e32 v46, v46
	v_rcp_f32_e32 v44, v44
	v_rcp_f32_e32 v45, v45
	v_max_f32_e32 v51, 0x219392ef, v42
	v_max_f32_e32 v52, 0x219392ef, v43
	v_lshlrev_b64 v[42:43], 12, v[188:189]
	v_lshl_add_u64 v[42:43], s[16:17], 0, v[42:43]
	v_max_f32_e32 v53, 0x219392ef, v46
	v_lshl_add_u64 v[46:47], v[186:187], 1, v[42:43]
	v_max_f32_e32 v44, 0x219392ef, v44
	v_max_f32_e32 v45, 0x219392ef, v45
	v_add_co_u32_e32 v46, vcc, 0xffffe000, v46
	v_cvt_pk_bf16_f32 v42, v48, v49
	v_cvt_pk_bf16_f32 v43, v44, v50
	v_cvt_pk_bf16_f32 v44, v51, v52
	v_cvt_pk_bf16_f32 v45, v45, v53
	v_addc_co_u32_e32 v47, vcc, -1, v47, vcc
	s_mov_b64 s[18:19], 0
	global_store_dwordx4 v[46:47], v[42:45], off nt
	s_nop 1
	v_lshlrev_b64 v[36:37], 10, v[188:189]
	v_lshl_add_u64 v[34:35], s[8:9], 0, v[36:37]
	s_branch .LBB0_1678
.LBB0_1664:
	s_andn2_b64 vcc, exec, s[18:19]
	s_cbranch_vccnz .LBB0_1666
	v_ashrrev_i32_e32 v42, 11, v98
	v_ashrrev_i32_e32 v43, 31, v42
	v_lshlrev_b64 v[42:43], 11, v[42:43]
	v_lshl_add_u64 v[42:43], v[42:43], 0, v[192:193]
	s_movk_i32 s18, 0x7ff
	v_and_or_b32 v42, v188, s18, v42
	v_lshl_add_u64 v[46:47], v[42:43], 4, s[14:15]
	v_cvt_pk_bf16_f32 v42, v22, v23
	v_cvt_pk_bf16_f32 v43, v24, v25
	v_cvt_pk_bf16_f32 v44, v18, v19
	v_cvt_pk_bf16_f32 v45, v20, v21
	global_store_dwordx4 v[46:47], v[42:45], off nt
	s_nop 1
	v_lshlrev_b64 v[36:37], 10, v[188:189]
	v_lshl_add_u64 v[34:35], s[8:9], 0, v[36:37]
	s_branch .LBB0_1678

.LBB0_1667:
	s_andn2_b64 vcc, exec, s[18:19]
	s_cbranch_vccnz .LBB0_1669
	v_mul_f32_e32 v42, 0xbfb8aa3b, v22
	v_mul_f32_e32 v43, 0xbfb8aa3b, v23
	v_mul_f32_e32 v44, 0xbfb8aa3b, v24
	v_mul_f32_e32 v45, 0xbfb8aa3b, v25
	v_mul_f32_e32 v46, 0xbfb8aa3b, v18
	v_mul_f32_e32 v47, 0xbfb8aa3b, v19
	v_mul_f32_e32 v48, 0xbfb8aa3b, v20
	v_mul_f32_e32 v49, 0xbfb8aa3b, v21
	v_exp_f32_e32 v42, v42
	v_exp_f32_e32 v43, v43
	v_exp_f32_e32 v44, v44
	v_exp_f32_e32 v45, v45
	v_exp_f32_e32 v46, v46
	v_exp_f32_e32 v47, v47
	v_exp_f32_e32 v48, v48
	v_exp_f32_e32 v49, v49
	v_add_f32_e32 v42, 1.0, v42
	v_add_f32_e32 v43, 1.0, v43
	v_add_f32_e32 v44, 1.0, v44
	v_add_f32_e32 v45, 1.0, v45
	v_add_f32_e32 v46, 1.0, v46
	v_add_f32_e32 v47, 1.0, v47
	v_add_f32_e32 v48, 1.0, v48
	v_add_f32_e32 v49, 1.0, v49
	v_rcp_f32_e32 v42, v42
	v_rcp_f32_e32 v43, v43
	v_rcp_f32_e32 v44, v44
	v_rcp_f32_e32 v45, v45
	v_rcp_f32_e32 v46, v46
	v_rcp_f32_e32 v47, v47
	v_rcp_f32_e32 v48, v48
	v_rcp_f32_e32 v49, v49
	v_lshlrev_b64 v[50:51], 10, v[188:189]
	v_pk_mul_f32 v[42:43], v[22:23], v[42:43]
	v_pk_mul_f32 v[44:45], v[24:25], v[44:45]
	v_pk_mul_f32 v[46:47], v[18:19], v[46:47]
	v_pk_mul_f32 v[48:49], v[20:21], v[48:49]
	v_lshl_add_u64 v[50:51], s[12:13], 0, v[50:51]
	v_lshl_add_u64 v[50:51], v[186:187], 1, v[50:51]
	v_cvt_pk_bf16_f32 v42, v42, v43
	v_cvt_pk_bf16_f32 v43, v44, v45
	v_cvt_pk_bf16_f32 v44, v46, v47
	v_cvt_pk_bf16_f32 v45, v48, v49
	global_store_dwordx4 v[50:51], v[42:45], off offset:-4096 nt
	s_nop 1
	v_lshlrev_b64 v[36:37], 10, v[188:189]
	v_lshl_add_u64 v[34:35], s[8:9], 0, v[36:37]
	s_branch .LBB0_1678

.LBB0_1670:
	s_andn2_b64 vcc, exec, s[18:19]
	s_cbranch_vccnz .LBB0_1672
	v_mul_f32_e32 v42, 0xbfb8aa3b, v22
	v_mul_f32_e32 v43, 0xbfb8aa3b, v23
	v_mul_f32_e32 v44, 0xbfb8aa3b, v24
	v_mul_f32_e32 v45, 0xbfb8aa3b, v25
	v_mul_f32_e32 v46, 0xbfb8aa3b, v18
	v_mul_f32_e32 v47, 0xbfb8aa3b, v19
	v_mul_f32_e32 v48, 0xbfb8aa3b, v20
	v_mul_f32_e32 v49, 0xbfb8aa3b, v21
	v_exp_f32_e32 v42, v42
	v_exp_f32_e32 v43, v43
	v_exp_f32_e32 v44, v44
	v_exp_f32_e32 v45, v45
	v_exp_f32_e32 v46, v46
	v_exp_f32_e32 v47, v47
	v_exp_f32_e32 v48, v48
	v_exp_f32_e32 v49, v49
	v_add_f32_e32 v42, 1.0, v42
	v_add_f32_e32 v43, 1.0, v43
	v_add_f32_e32 v44, 1.0, v44
	v_add_f32_e32 v45, 1.0, v45
	v_add_f32_e32 v46, 1.0, v46
	v_add_f32_e32 v47, 1.0, v47
	v_add_f32_e32 v48, 1.0, v48
	v_add_f32_e32 v49, 1.0, v49
	v_rcp_f32_e32 v42, v42
	v_rcp_f32_e32 v43, v43
	v_rcp_f32_e32 v44, v44
	v_rcp_f32_e32 v45, v45
	v_rcp_f32_e32 v46, v46
	v_rcp_f32_e32 v47, v47
	v_rcp_f32_e32 v48, v48
	v_rcp_f32_e32 v49, v49
	v_lshlrev_b64 v[50:51], 10, v[188:189]
	v_pk_mul_f32 v[42:43], v[22:23], v[42:43]
	v_pk_mul_f32 v[44:45], v[24:25], v[44:45]
	v_pk_mul_f32 v[46:47], v[18:19], v[46:47]
	v_pk_mul_f32 v[48:49], v[20:21], v[48:49]
	v_lshl_add_u64 v[50:51], s[10:11], 0, v[50:51]
	v_lshl_add_u64 v[50:51], v[186:187], 1, v[50:51]
	v_cvt_pk_bf16_f32 v42, v42, v43
	v_cvt_pk_bf16_f32 v43, v44, v45
	v_cvt_pk_bf16_f32 v44, v46, v47
	v_cvt_pk_bf16_f32 v45, v48, v49
	global_store_dwordx4 v[50:51], v[42:45], off offset:-3072 nt
	s_nop 1
	v_lshlrev_b64 v[36:37], 10, v[188:189]
	v_lshl_add_u64 v[34:35], s[8:9], 0, v[36:37]
	s_branch .LBB0_1678

.LBB0_1673:
	s_and_b64 vcc, exec, s[18:19]
	s_cbranch_vccz .LBB0_1675
	v_mul_f32_e32 v44, 0xbfb8aa3b, v22
	v_exp_f32_e32 v44, v44
	s_and_b64 s[18:19], s[54:55], exec
	s_cselect_b32 s35, s87, s92
	s_cselect_b32 s34, s79, s89
	v_add_f32_e32 v44, 1.0, v44
	v_rcp_f32_e32 v44, v44
	v_lshlrev_b64 v[42:43], 10, v[188:189]
	v_lshlrev_b32_e32 v176, 1, v191
	v_fmac_f32_e32 v38, v242, v44
	v_mul_f32_e32 v44, 0xbfb8aa3b, v23
	v_exp_f32_e32 v44, v44
	v_log_f32_e32 v38, v38
	v_add_f32_e32 v44, 1.0, v44
	v_rcp_f32_e32 v44, v44
	s_nop 0
	v_fmac_f32_e32 v39, v241, v44
	v_mul_f32_e32 v44, 0xbfb8aa3b, v24
	v_exp_f32_e32 v44, v44
	v_log_f32_e32 v39, v39
	v_add_f32_e32 v44, 1.0, v44
	v_rcp_f32_e32 v44, v44
	s_nop 0
	v_fmac_f32_e32 v40, v240, v44
	v_mul_f32_e32 v44, 0xbfb8aa3b, v25
	v_exp_f32_e32 v44, v44
	v_log_f32_e32 v40, v40
	v_add_f32_e32 v44, 1.0, v44
	v_rcp_f32_e32 v44, v44
	s_nop 0
	v_fmac_f32_e32 v41, v239, v44
	v_mul_f32_e32 v44, 0xbfb8aa3b, v18
	v_exp_f32_e32 v44, v44
	v_log_f32_e32 v41, v41
	v_add_f32_e32 v44, 1.0, v44
	v_rcp_f32_e32 v44, v44
	s_nop 0
	v_fmac_f32_e32 v34, v238, v44
	v_mul_f32_e32 v44, 0xbfb8aa3b, v19
	v_exp_f32_e32 v44, v44
	v_log_f32_e32 v34, v34
	v_add_f32_e32 v44, 1.0, v44
	v_rcp_f32_e32 v44, v44
	s_nop 0
	v_fmac_f32_e32 v35, v234, v44
	v_mul_f32_e32 v44, 0xbfb8aa3b, v20
	v_exp_f32_e32 v44, v44
	v_log_f32_e32 v35, v35
	v_add_f32_e32 v44, 1.0, v44
	v_rcp_f32_e32 v44, v44
	s_nop 0
	v_fmac_f32_e32 v36, v233, v44
	v_mul_f32_e32 v44, 0xbfb8aa3b, v21
	v_exp_f32_e32 v44, v44
	v_log_f32_e32 v36, v36
	v_add_f32_e32 v44, 1.0, v44
	v_rcp_f32_e32 v44, v44
	s_nop 0
	v_fmac_f32_e32 v37, v229, v44
	v_log_f32_e32 v37, v37
	s_nop 0
	v_cvt_pk_f16_f32 v37, v36, v37
	v_cvt_pk_f16_f32 v36, v34, v35
	v_cvt_pk_f16_f32 v34, v38, v39
	v_lshl_add_u64 v[38:39], s[34:35], 0, v[42:43]
	v_cvt_pk_f16_f32 v35, v40, v41
	v_lshl_add_u64 v[38:39], v[38:39], 0, v[176:177]
	global_store_dwordx4 v[38:39], v[34:37], off
	s_nop 1
	v_lshlrev_b64 v[36:37], 10, v[188:189]
	v_lshl_add_u64 v[34:35], s[8:9], 0, v[36:37]
	s_branch .LBB0_1678

.LBB0_1678:
	v_mov_b32_e32 v191, v190
	v_pk_fma_f32 v[6:7], v[6:7], v[190:191], v[30:31]
	v_pk_fma_f32 v[8:9], v[8:9], v[190:191], v[32:33]
	v_pk_fma_f32 v[2:3], v[2:3], v[190:191], v[26:27]
	v_pk_fma_f32 v[4:5], v[4:5], v[190:191], v[28:29]
	s_and_b64 vcc, exec, s[4:5]
	s_mov_b64 s[4:5], -1
	s_cbranch_vccnz .LBB0_1696
	s_and_b64 vcc, exec, s[2:3]
	s_mov_b64 s[2:3], -1
	s_cbranch_vccnz .LBB0_1693
	s_cmp_lt_i32 s39, 4
	s_cbranch_scc1 .LBB0_1690
	s_cmp_lg_u32 s39, 4
	s_cbranch_scc0 .LBB0_1687
	s_andn2_b64 vcc, exec, s[56:57]
	s_cbranch_vccnz .LBB0_1684
	v_mul_f32_e32 v18, 0xbfb8aa3b, v6
	v_mul_f32_e32 v19, 0xbfb8aa3b, v7
	v_exp_f32_e32 v18, v18
	v_exp_f32_e32 v19, v19
	v_mul_f32_e32 v21, 0xbfb8aa3b, v9
	v_exp_f32_e32 v21, v21
	v_add_f32_e32 v18, 1.0, v18
	v_add_f32_e32 v19, 1.0, v19
	v_rcp_f32_e32 v18, v18
	v_rcp_f32_e32 v19, v19
	v_mul_f32_e32 v22, 0xbfb8aa3b, v5
	v_mul_f32_e32 v20, 0xbfb8aa3b, v8
	v_max_f32_e32 v24, 0x219392ef, v18
	v_max_f32_e32 v25, 0x219392ef, v19
	v_add_f32_e32 v18, 1.0, v21
	v_mul_f32_e32 v19, 0xbfb8aa3b, v2
	v_mul_f32_e32 v21, 0xbfb8aa3b, v3
	v_rcp_f32_e32 v18, v18
	v_exp_f32_e32 v19, v19
	v_exp_f32_e32 v21, v21
	v_exp_f32_e32 v22, v22
	v_max_f32_e32 v26, 0x219392ef, v18
	v_add_f32_e32 v18, 1.0, v19
	v_add_f32_e32 v19, 1.0, v21
	v_mul_f32_e32 v21, 0xbfb8aa3b, v4
	v_exp_f32_e32 v20, v20
	v_exp_f32_e32 v21, v21
	v_rcp_f32_e32 v18, v18
	v_rcp_f32_e32 v19, v19
	v_add_f32_e32 v22, 1.0, v22
	v_add_f32_e32 v20, 1.0, v20
	v_add_f32_e32 v21, 1.0, v21
	v_rcp_f32_e32 v22, v22
	v_rcp_f32_e32 v20, v20
	v_rcp_f32_e32 v21, v21
	v_max_f32_e32 v27, 0x219392ef, v18
	v_max_f32_e32 v28, 0x219392ef, v19
	v_lshlrev_b64 v[18:19], 12, v[188:189]
	v_lshl_add_u64 v[18:19], s[16:17], 0, v[18:19]
	v_max_f32_e32 v29, 0x219392ef, v22
	v_lshl_add_u64 v[22:23], v[186:187], 1, v[18:19]
	v_max_f32_e32 v20, 0x219392ef, v20
	v_max_f32_e32 v21, 0x219392ef, v21
	v_add_co_u32_e32 v22, vcc, 0xfffff000, v22
	v_cvt_pk_bf16_f32 v18, v24, v25
	v_cvt_pk_bf16_f32 v19, v20, v26
	v_cvt_pk_bf16_f32 v20, v27, v28
	v_cvt_pk_bf16_f32 v21, v21, v29
	v_addc_co_u32_e32 v23, vcc, -1, v23, vcc
	s_mov_b64 s[2:3], 0
	global_store_dwordx4 v[22:23], v[18:21], off offset:-3840 nt
	s_nop 1
	s_branch .LBB0_1368
.LBB0_1684:
	s_andn2_b64 vcc, exec, s[2:3]
	s_cbranch_vccnz .LBB0_1686
	v_ashrrev_i32_e32 v18, 11, v98
	v_ashrrev_i32_e32 v19, 31, v18
	v_lshlrev_b64 v[18:19], 11, v[18:19]
	v_lshl_add_u64 v[18:19], v[18:19], 0, v[154:155]
	s_movk_i32 s2, 0x7ff
	v_and_or_b32 v18, v188, s2, v18
	v_lshl_add_u64 v[22:23], v[18:19], 4, s[14:15]
	v_cvt_pk_bf16_f32 v18, v6, v7
	v_cvt_pk_bf16_f32 v19, v8, v9
	v_cvt_pk_bf16_f32 v20, v2, v3
	v_cvt_pk_bf16_f32 v21, v4, v5
	global_store_dwordx4 v[22:23], v[18:21], off nt
	s_nop 1
	s_branch .LBB0_1368

.LBB0_1687:
	s_andn2_b64 vcc, exec, s[2:3]
	s_cbranch_vccnz .LBB0_1689
	v_mul_f32_e32 v18, 0xbfb8aa3b, v6
	v_mul_f32_e32 v19, 0xbfb8aa3b, v7
	v_mul_f32_e32 v20, 0xbfb8aa3b, v8
	v_mul_f32_e32 v21, 0xbfb8aa3b, v9
	v_mul_f32_e32 v22, 0xbfb8aa3b, v2
	v_mul_f32_e32 v23, 0xbfb8aa3b, v3
	v_mul_f32_e32 v24, 0xbfb8aa3b, v4
	v_mul_f32_e32 v25, 0xbfb8aa3b, v5
	v_exp_f32_e32 v18, v18
	v_exp_f32_e32 v19, v19
	v_exp_f32_e32 v20, v20
	v_exp_f32_e32 v21, v21
	v_exp_f32_e32 v22, v22
	v_exp_f32_e32 v23, v23
	v_exp_f32_e32 v24, v24
	v_exp_f32_e32 v25, v25
	v_add_f32_e32 v18, 1.0, v18
	v_add_f32_e32 v19, 1.0, v19
	v_add_f32_e32 v20, 1.0, v20
	v_add_f32_e32 v21, 1.0, v21
	v_add_f32_e32 v22, 1.0, v22
	v_add_f32_e32 v23, 1.0, v23
	v_add_f32_e32 v24, 1.0, v24
	v_add_f32_e32 v25, 1.0, v25
	v_rcp_f32_e32 v18, v18
	v_rcp_f32_e32 v19, v19
	v_rcp_f32_e32 v20, v20
	v_rcp_f32_e32 v21, v21
	v_rcp_f32_e32 v22, v22
	v_rcp_f32_e32 v23, v23
	v_rcp_f32_e32 v24, v24
	v_rcp_f32_e32 v25, v25
	v_pk_mul_f32 v[18:19], v[6:7], v[18:19]
	v_pk_mul_f32 v[20:21], v[8:9], v[20:21]
	v_pk_mul_f32 v[22:23], v[2:3], v[22:23]
	v_pk_mul_f32 v[24:25], v[4:5], v[24:25]
	v_lshl_add_u64 v[26:27], s[12:13], 0, v[36:37]
	v_lshl_add_u64 v[26:27], v[186:187], 1, v[26:27]
	v_cvt_pk_bf16_f32 v18, v18, v19
	v_cvt_pk_bf16_f32 v19, v20, v21
	v_cvt_pk_bf16_f32 v20, v22, v23
	v_cvt_pk_bf16_f32 v21, v24, v25
	global_store_dwordx4 v[26:27], v[18:21], off offset:-3840 nt
	s_nop 1
	s_branch .LBB0_1368

.LBB0_1690:
	s_andn2_b64 vcc, exec, s[2:3]
	s_cbranch_vccnz .LBB0_1692
	v_mul_f32_e32 v18, 0xbfb8aa3b, v6
	v_mul_f32_e32 v19, 0xbfb8aa3b, v7
	v_mul_f32_e32 v20, 0xbfb8aa3b, v8
	v_mul_f32_e32 v21, 0xbfb8aa3b, v9
	v_mul_f32_e32 v22, 0xbfb8aa3b, v2
	v_mul_f32_e32 v23, 0xbfb8aa3b, v3
	v_mul_f32_e32 v24, 0xbfb8aa3b, v4
	v_mul_f32_e32 v25, 0xbfb8aa3b, v5
	v_exp_f32_e32 v18, v18
	v_exp_f32_e32 v19, v19
	v_exp_f32_e32 v20, v20
	v_exp_f32_e32 v21, v21
	v_exp_f32_e32 v22, v22
	v_exp_f32_e32 v23, v23
	v_exp_f32_e32 v24, v24
	v_exp_f32_e32 v25, v25
	v_add_f32_e32 v18, 1.0, v18
	v_add_f32_e32 v19, 1.0, v19
	v_add_f32_e32 v20, 1.0, v20
	v_add_f32_e32 v21, 1.0, v21
	v_add_f32_e32 v22, 1.0, v22
	v_add_f32_e32 v23, 1.0, v23
	v_add_f32_e32 v24, 1.0, v24
	v_add_f32_e32 v25, 1.0, v25
	v_rcp_f32_e32 v18, v18
	v_rcp_f32_e32 v19, v19
	v_rcp_f32_e32 v20, v20
	v_rcp_f32_e32 v21, v21
	v_rcp_f32_e32 v22, v22
	v_rcp_f32_e32 v23, v23
	v_rcp_f32_e32 v24, v24
	v_rcp_f32_e32 v25, v25
	v_pk_mul_f32 v[18:19], v[6:7], v[18:19]
	v_pk_mul_f32 v[20:21], v[8:9], v[20:21]
	v_pk_mul_f32 v[22:23], v[2:3], v[22:23]
	v_pk_mul_f32 v[24:25], v[4:5], v[24:25]
	v_lshl_add_u64 v[26:27], s[10:11], 0, v[36:37]
	v_lshl_add_u64 v[26:27], v[186:187], 1, v[26:27]
	v_cvt_pk_bf16_f32 v18, v18, v19
	v_cvt_pk_bf16_f32 v19, v20, v21
	v_cvt_pk_bf16_f32 v20, v22, v23
	v_cvt_pk_bf16_f32 v21, v24, v25
	global_store_dwordx4 v[26:27], v[18:21], off offset:-2816 nt
	s_nop 1
	s_branch .LBB0_1368

.LBB0_1693:
	s_and_b64 vcc, exec, s[2:3]
	s_cbranch_vccz .LBB0_1695
	v_mul_f32_e32 v18, 0xbfb8aa3b, v6
	v_mul_f32_e32 v19, 0xbfb8aa3b, v7
	v_exp_f32_e32 v18, v18
	v_exp_f32_e32 v19, v19
	v_mul_f32_e32 v20, 0xbfb8aa3b, v8
	v_exp_f32_e32 v20, v20
	v_add_f32_e32 v18, 1.0, v18
	v_add_f32_e32 v19, 1.0, v19
	v_rcp_f32_e32 v18, v18
	v_rcp_f32_e32 v19, v19
	v_add_f32_e32 v20, 1.0, v20
	v_rcp_f32_e32 v20, v20
	v_fmac_f32_e32 v10, v237, v18
	v_fmac_f32_e32 v11, v236, v19
	v_mul_f32_e32 v18, 0xbfb8aa3b, v9
	v_mul_f32_e32 v19, 0xbfb8aa3b, v2
	v_exp_f32_e32 v18, v18
	v_exp_f32_e32 v19, v19
	v_fmac_f32_e32 v12, v235, v20
	v_log_f32_e32 v20, v12
	v_add_f32_e32 v12, 1.0, v18
	v_add_f32_e32 v18, 1.0, v19
	v_rcp_f32_e32 v18, v18
	v_mul_f32_e32 v19, 0xbfb8aa3b, v3
	v_rcp_f32_e32 v12, v12
	v_exp_f32_e32 v19, v19
	v_fmac_f32_e32 v14, v223, v18
	v_mul_f32_e32 v18, 0xbfb8aa3b, v4
	v_fmac_f32_e32 v13, v222, v12
	v_log_f32_e32 v12, v14
	v_add_f32_e32 v14, 1.0, v19
	v_mul_f32_e32 v19, 0xbfb8aa3b, v5
	v_exp_f32_e32 v18, v18
	v_exp_f32_e32 v19, v19
	v_rcp_f32_e32 v14, v14
	v_log_f32_e32 v10, v10
	v_add_f32_e32 v18, 1.0, v18
	v_add_f32_e32 v19, 1.0, v19
	v_rcp_f32_e32 v18, v18
	v_rcp_f32_e32 v19, v19
	v_fmac_f32_e32 v15, v220, v14
	v_log_f32_e32 v15, v15
	v_fmac_f32_e32 v16, v221, v18
	v_fmac_f32_e32 v17, v161, v19
	v_log_f32_e32 v14, v16
	v_log_f32_e32 v16, v17
	v_log_f32_e32 v17, v13
	v_log_f32_e32 v18, v11
	s_and_b64 s[2:3], s[54:55], exec
	s_cselect_b32 s3, s87, s92
	s_cselect_b32 s2, s79, s89
	v_cvt_pk_f16_f32 v13, v14, v16
	v_cvt_pk_f16_f32 v12, v12, v15
	v_lshl_add_u64 v[14:15], s[2:3], 0, v[36:37]
	v_lshlrev_b32_e32 v176, 1, v160
	v_cvt_pk_f16_f32 v11, v20, v17
	v_cvt_pk_f16_f32 v10, v10, v18
	v_lshl_add_u64 v[14:15], v[14:15], 0, v[176:177]
	global_store_dwordx4 v[14:15], v[10:13], off
	s_nop 1
	s_branch .LBB0_1368
